# PEER apply: V sweep walks id ranges per 4-token group with register accumulators; U/V rows fetched by buffer loads with SGPR row offset; shorter per-row scalar stream
# speedup vs baseline: 1.1812x; 1.0100x over previous
; #define TIDX tid_fn()
; __device__ __forceinline__ void ph_peer_apply(const Params& P, int layer, float* xlat, float* xctx_in, float* xctx_out, int nrows, bool write_next, char* smem, float* xlat_out = nullptr) {
;     ...
;   const int tid = TIDX, wave = tid >> 6, lane = tid & 63;
;   const bool lact = lane < P6_NB;
;   const int lb = lact ? lane : 0;
;   for (int row = blockIdx.x * (NTHR / 64) + wave; row < nrows; row += gridDim.x * (NTHR / 64)) {
;     float xv[32];
; #pragma unroll
;     for (int j8 = 0; j8 < 4; ++j8) {
;       const h16x8 t = *(const h16x8*)(xq + (size_t)row * D + lb * 32 + j8 * 8);
; #pragma unroll
;       for (int j = 0; j < 8; ++j) xv[j8 * 8 + j] = lact ? (float)t[j] : 0.f;
;     }
;     const int id0 = seli[(size_t)row * NSEL + lane], id1 = seli[(size_t)row * NSEL + 64 + lane];
;     const float g0 = selg[(size_t)row * NSEL + lane], g1 = selg[(size_t)row * NSEL + 64 + lane];
;     float a0 = 0.f, a1 = 0.f;
;     P6Blk bufA[PB_G], bufB[PB_G];
.LBB0_1953:
	s_or_b64 exec, exec, s[6:7]
	s_mov_b64 s[4:5], s[96:97]
	s_waitcnt lgkmcnt(0)
	v_mov_b32_e32 v1, v0
	s_barrier
	s_load_dwordx4 s[4:7], s[96:97], 0x170
	s_load_dwordx4 s[8:11], s[96:97], 0x30
	v_readfirstlane_b32 s12, v0
	s_lshr_b32 s12, s12, 6
	v_and_b32_e32 v1, 63, v0
	v_mul_u32_u24_e32 v2, 24, v1
	v_add_u32_e32 v3, 0x600, v1
	v_lshlrev_b32_e32 v224, 6, v1
	v_lshlrev_b32_e32 v225, 7, v1
	v_lshlrev_b32_e32 v226, 2, v1
	v_lshrrev_b32_e32 v192, 2, v1
	v_and_b32_e32 v193, 1, v1
	v_lshl_add_u32 v192, v192, 1, v193
	v_lshlrev_b32_e32 v227, 2, v192
	s_mul_i32 s15, s12, 0x2800
	v_add_u32_e32 v228, s15, v226
	v_add_u32_e32 v227, s15, v227
	s_mov_b32 s46, 0x3333
	s_mov_b32 s47, 0
	s_mov_b32 s34, 0x22222222
	s_mov_b32 s35, 0x22222222
	s_waitcnt lgkmcnt(0)
	s_mov_b64 s[40:41], s[4:5]
	s_mov_b64 s[4:5], s[6:7]
	s_mov_b64 s[6:7], s[40:41]
	s_add_u32 s16, s4, 0x3c7c000
	s_addc_u32 s17, s5, 0
	s_add_u32 s18, s4, 0x7c7c000
	s_addc_u32 s19, s5, 0
	s_add_u32 s13, s60, s12
	s_lshl_b32 s44, s84, 3
	s_add_u32 s16, s4, 0x3c7c000
	s_addc_u32 s17, s5, 0
	s_and_b32 s17, s17, 0xffff
	s_mov_b32 s18, 0x1900000
	s_mov_b32 s19, 0x20000
	s_mov_b32 s50, 0
	s_mov_b32 s1, s13
.Lau0_ntl:
	s_add_u32 s50, s50, 1
	s_add_u32 s1, s1, s44
	s_cmp_lt_u32 s1, 0x8200
	s_cbranch_scc1 .Lau0_ntl
	s_mov_b32 s58, 0
	s_mov_b32 s59, 0
	s_mov_b32 s62, 0
	s_mov_b32 s48, 0
	s_mov_b32 s49, 0
	s_mov_b32 s45, s13
	s_lshl_b32 s15, s45, 12
	s_lshr_b32 s31, s45, 20
	s_add_u32 s20, s4, 0xbe4c000
	s_addc_u32 s21, s5, 0
	s_add_u32 s20, s20, s15
	s_addc_u32 s21, s21, s31
	s_lshl_b32 s15, s45, 9
	s_add_u32 s22, s4, 0x1404c000
	s_addc_u32 s23, s5, 0
	s_add_u32 s22, s22, s15
	s_addc_u32 s23, s23, 0
	global_load_dwordx4 v[230:233], v224, s[20:21]
	global_load_dwordx4 v[234:237], v224, s[20:21] offset:16
	global_load_dwordx4 v[238:241], v224, s[20:21] offset:32
	global_load_dwordx4 v[242:245], v224, s[20:21] offset:48
	global_load_dword v36, v226, s[22:23]
	global_load_dword v37, v226, s[22:23] offset:256
	s_waitcnt vmcnt(0)
	v_cvt_f32_f16_e32 v4, v230
	v_cvt_f32_f16_sdwa v5, v230 dst_sel:DWORD dst_unused:UNUSED_PAD src0_sel:WORD_1
	v_cvt_f32_f16_e32 v6, v231
	v_cvt_f32_f16_sdwa v7, v231 dst_sel:DWORD dst_unused:UNUSED_PAD src0_sel:WORD_1
	v_cvt_f32_f16_e32 v8, v232
	v_cvt_f32_f16_sdwa v9, v232 dst_sel:DWORD dst_unused:UNUSED_PAD src0_sel:WORD_1
	v_cvt_f32_f16_e32 v10, v233
	v_cvt_f32_f16_sdwa v11, v233 dst_sel:DWORD dst_unused:UNUSED_PAD src0_sel:WORD_1
	v_cvt_f32_f16_e32 v12, v234
	v_cvt_f32_f16_sdwa v13, v234 dst_sel:DWORD dst_unused:UNUSED_PAD src0_sel:WORD_1
	v_cvt_f32_f16_e32 v14, v235
	v_cvt_f32_f16_sdwa v15, v235 dst_sel:DWORD dst_unused:UNUSED_PAD src0_sel:WORD_1
	v_cvt_f32_f16_e32 v16, v236
	v_cvt_f32_f16_sdwa v17, v236 dst_sel:DWORD dst_unused:UNUSED_PAD src0_sel:WORD_1
	v_cvt_f32_f16_e32 v18, v237
	v_cvt_f32_f16_sdwa v19, v237 dst_sel:DWORD dst_unused:UNUSED_PAD src0_sel:WORD_1
	v_cvt_f32_f16_e32 v20, v238
	v_cvt_f32_f16_sdwa v21, v238 dst_sel:DWORD dst_unused:UNUSED_PAD src0_sel:WORD_1
	v_cvt_f32_f16_e32 v22, v239
	v_cvt_f32_f16_sdwa v23, v239 dst_sel:DWORD dst_unused:UNUSED_PAD src0_sel:WORD_1
	v_cvt_f32_f16_e32 v24, v240
	v_cvt_f32_f16_sdwa v25, v240 dst_sel:DWORD dst_unused:UNUSED_PAD src0_sel:WORD_1
	v_cvt_f32_f16_e32 v26, v241
	v_cvt_f32_f16_sdwa v27, v241 dst_sel:DWORD dst_unused:UNUSED_PAD src0_sel:WORD_1
	v_cvt_f32_f16_e32 v28, v242
	v_cvt_f32_f16_sdwa v29, v242 dst_sel:DWORD dst_unused:UNUSED_PAD src0_sel:WORD_1
	v_cvt_f32_f16_e32 v30, v243
	v_cvt_f32_f16_sdwa v31, v243 dst_sel:DWORD dst_unused:UNUSED_PAD src0_sel:WORD_1
	v_cvt_f32_f16_e32 v32, v244
	v_cvt_f32_f16_sdwa v33, v244 dst_sel:DWORD dst_unused:UNUSED_PAD src0_sel:WORD_1
	v_cvt_f32_f16_e32 v34, v245
	v_cvt_f32_f16_sdwa v35, v245 dst_sel:DWORD dst_unused:UNUSED_PAD src0_sel:WORD_1
	v_lshrrev_b32_e32 v249, 11, v36
	v_lshrrev_b32_e32 v250, 11, v37
	v_cmp_eq_u32_e64 s[52:53], s58, v249
	v_cmp_eq_u32_e64 s[54:55], s58, v250
	v_mul_u32_u24_e32 v44, 0x640, v36
	s_mov_b32 s61, 0
	s_lshl_b32 s63, s59, 9
	s_mul_i32 s1, s12, 0x2800
	s_add_u32 s63, s63, s1
	v_add_u32_e32 v46, s63, v226
	s_bcnt1_i32_b64 s1, s[52:53]
	s_bcnt1_i32_b64 s15, s[54:55]
	s_add_u32 s1, s1, s15
	s_sub_u32 s57, 8, s1
	s_cselect_b32 s57, 0, s57
	s_add_u32 s1, s59, 1
	s_cmp_lt_u32 s1, s50
	s_cbranch_scc1 .Lau0_pfki
	s_mov_b32 s1, 0
	s_cmp_lt_u32 s58, 7
	s_cbranch_scc0 .Lau0_pfdi
.Lau0_pfki:
	s_mul_i32 s1, s1, s44
	s_add_u32 s1, s1, s13
	s_lshl_b32 s15, s1, 12
	s_lshr_b32 s31, s1, 20
	s_add_u32 s20, s4, 0xbe4c000
	s_addc_u32 s21, s5, 0
	s_add_u32 s20, s20, s15
	s_addc_u32 s21, s21, s31
	s_lshl_b32 s15, s1, 9
	s_add_u32 s22, s4, 0x1404c000
	s_addc_u32 s23, s5, 0
	s_add_u32 s22, s22, s15
	s_addc_u32 s23, s23, 0
	global_load_dword v38, v226, s[22:23]
	global_load_dword v39, v226, s[22:23] offset:256
	global_load_dwordx4 v[230:233], v224, s[20:21]
	global_load_dwordx4 v[234:237], v224, s[20:21] offset:16
	global_load_dwordx4 v[238:241], v224, s[20:21] offset:32
	global_load_dwordx4 v[242:245], v224, s[20:21] offset:48
.Lau0_pfdi:
	v_mov_b32_e32 v47, 0
	v_mov_b32_e32 v45, 0
.Lau0_issp0:
	s_cmp_lg_u64 s[52:53], 0
	s_cbranch_scc0 .Lau0_slowp0
	s_ff1_i32_b64 s56, s[52:53]
	s_bitset0_b64 s[52:53], s56
	v_readlane_b32 s26, v44, s56
	v_readlane_b32 s1, v46, s56
.Lau0_sdp0:
	v_writelane_b32 v47, s1, 0
	s_mov_b32 s33, s62
	s_nop 3
	buffer_load_dwordx4 v[48:51], v2, s[16:19], s26 offen
	buffer_load_dwordx2 v[52:53], v2, s[16:19], s26 offen offset:16
	buffer_load_ubyte v54, v3, s[16:19], s26 offen

.Lau0_sdp1:
	v_writelane_b32 v47, s1, 1
	s_mov_b32 s38, s62
	s_nop 3
	buffer_load_dwordx4 v[56:59], v2, s[16:19], s26 offen
	buffer_load_dwordx2 v[60:61], v2, s[16:19], s26 offen offset:16
	buffer_load_ubyte v62, v3, s[16:19], s26 offen

.Lau0_sdp2:
	v_writelane_b32 v47, s1, 4
	s_mov_b32 s39, s62
	s_nop 3
	buffer_load_dwordx4 v[64:67], v2, s[16:19], s26 offen
	buffer_load_dwordx2 v[68:69], v2, s[16:19], s26 offen offset:16
	buffer_load_ubyte v70, v3, s[16:19], s26 offen

.Lau0_sdp3:
	v_writelane_b32 v47, s1, 5
	s_mov_b32 s51, s62
	s_nop 3
	buffer_load_dwordx4 v[72:75], v2, s[16:19], s26 offen
	buffer_load_dwordx2 v[76:77], v2, s[16:19], s26 offen offset:16
	buffer_load_ubyte v78, v3, s[16:19], s26 offen

.Lau0_sdp4:
	v_writelane_b32 v47, s1, 8
	s_mov_b32 s28, s62
	s_nop 3
	buffer_load_dwordx4 v[80:83], v2, s[16:19], s26 offen
	buffer_load_dwordx2 v[84:85], v2, s[16:19], s26 offen offset:16
	buffer_load_ubyte v86, v3, s[16:19], s26 offen

.Lau0_sdp5:
	v_writelane_b32 v47, s1, 9
	s_mov_b32 s30, s62
	s_nop 3
	buffer_load_dwordx4 v[88:91], v2, s[16:19], s26 offen
	buffer_load_dwordx2 v[92:93], v2, s[16:19], s26 offen offset:16
	buffer_load_ubyte v94, v3, s[16:19], s26 offen

.Lau0_sdp6:
	v_writelane_b32 v47, s1, 12
	s_mov_b32 s36, s62
	s_nop 3
	buffer_load_dwordx4 v[96:99], v2, s[16:19], s26 offen
	buffer_load_dwordx2 v[100:101], v2, s[16:19], s26 offen offset:16
	buffer_load_ubyte v102, v3, s[16:19], s26 offen

.Lau0_sdp7:
	v_writelane_b32 v47, s1, 13
	s_mov_b32 s37, s62
	s_nop 3
	buffer_load_dwordx4 v[104:107], v2, s[16:19], s26 offen
	buffer_load_dwordx2 v[108:109], v2, s[16:19], s26 offen offset:16
	buffer_load_ubyte v110, v3, s[16:19], s26 offen
	v_mov_b32_e32 v45, v47
	s_branch .Lau0_pro2

; __device__ __forceinline__ void ph_peer_apply(const Params& P, int layer, float* xlat, float* xctx_in, float* xctx_out, int nrows, bool write_next, char* smem, float* xlat_out = nullptr) {
;     ...
;   for (int row = blockIdx.x * (NTHR / 64) + wave; row < nrows; row += gridDim.x * (NTHR / 64)) {
;     float xv[32];
; #pragma unroll
;     for (int j8 = 0; j8 < 4; ++j8) {
;       const h16x8 t = *(const h16x8*)(xq + (size_t)row * D + lb * 32 + j8 * 8);
; #pragma unroll
;       for (int j = 0; j < 8; ++j) xv[j8 * 8 + j] = lact ? (float)t[j] : 0.f;
;     }
;     const int id0 = seli[(size_t)row * NSEL + lane], id1 = seli[(size_t)row * NSEL + 64 + lane];
;     const float g0 = selg[(size_t)row * NSEL + lane], g1 = selg[(size_t)row * NSEL + 64 + lane];
;     float a0 = 0.f, a1 = 0.f;
;     P6Blk bufA[PB_G], bufB[PB_G];
.Lau0_slowcp:
	s_cmp_lg_u32 s61, 0
	s_cbranch_scc1 .Lau0_h1p
	s_mov_b32 s61, 1
	s_mov_b64 s[52:53], s[54:55]
	v_mul_u32_u24_e32 v44, 0x640, v37
	v_add_u32_e32 v46, 0x100, v46
	s_branch .Lau0_redop
.Lau0_h1p:
	s_cmp_lg_u32 s57, 0
	s_cbranch_scc1 .Lau0_padp
	s_cmp_lg_u32 s48, 0
	s_cbranch_scc1 .Lau0_dummyp
	s_add_u32 s59, s59, 1
	s_cmp_lt_u32 s59, s50
	s_cbranch_scc1 .Lau0_advp
	s_mov_b32 s59, 0
	s_add_u32 s58, s58, 1
	s_cmp_lt_u32 s58, 8
	s_cbranch_scc1 .Lau0_advp
	s_mov_b32 s48, 1
	s_branch .Lau0_dummyp
.Lau0_advp:
	s_waitcnt vmcnt(24)
	v_mov_b32_e32 v36, v38
	v_mov_b32_e32 v37, v39
	s_xor_b32 s62, s62, 1
	s_cmp_lg_u32 s62, 0
	s_cbranch_scc1 .Lau0_cv1p
	v_cvt_f32_f16_e32 v4, v230
	v_cvt_f32_f16_sdwa v5, v230 dst_sel:DWORD dst_unused:UNUSED_PAD src0_sel:WORD_1
	v_cvt_f32_f16_e32 v6, v231
	v_cvt_f32_f16_sdwa v7, v231 dst_sel:DWORD dst_unused:UNUSED_PAD src0_sel:WORD_1
	v_cvt_f32_f16_e32 v8, v232
	v_cvt_f32_f16_sdwa v9, v232 dst_sel:DWORD dst_unused:UNUSED_PAD src0_sel:WORD_1
	v_cvt_f32_f16_e32 v10, v233
	v_cvt_f32_f16_sdwa v11, v233 dst_sel:DWORD dst_unused:UNUSED_PAD src0_sel:WORD_1
	v_cvt_f32_f16_e32 v12, v234
	v_cvt_f32_f16_sdwa v13, v234 dst_sel:DWORD dst_unused:UNUSED_PAD src0_sel:WORD_1
	v_cvt_f32_f16_e32 v14, v235
	v_cvt_f32_f16_sdwa v15, v235 dst_sel:DWORD dst_unused:UNUSED_PAD src0_sel:WORD_1
	v_cvt_f32_f16_e32 v16, v236
	v_cvt_f32_f16_sdwa v17, v236 dst_sel:DWORD dst_unused:UNUSED_PAD src0_sel:WORD_1
	v_cvt_f32_f16_e32 v18, v237
	v_cvt_f32_f16_sdwa v19, v237 dst_sel:DWORD dst_unused:UNUSED_PAD src0_sel:WORD_1
	v_cvt_f32_f16_e32 v20, v238
	v_cvt_f32_f16_sdwa v21, v238 dst_sel:DWORD dst_unused:UNUSED_PAD src0_sel:WORD_1
	v_cvt_f32_f16_e32 v22, v239
	v_cvt_f32_f16_sdwa v23, v239 dst_sel:DWORD dst_unused:UNUSED_PAD src0_sel:WORD_1
	v_cvt_f32_f16_e32 v24, v240
	v_cvt_f32_f16_sdwa v25, v240 dst_sel:DWORD dst_unused:UNUSED_PAD src0_sel:WORD_1
	v_cvt_f32_f16_e32 v26, v241
	v_cvt_f32_f16_sdwa v27, v241 dst_sel:DWORD dst_unused:UNUSED_PAD src0_sel:WORD_1
	v_cvt_f32_f16_e32 v28, v242
	v_cvt_f32_f16_sdwa v29, v242 dst_sel:DWORD dst_unused:UNUSED_PAD src0_sel:WORD_1
	v_cvt_f32_f16_e32 v30, v243
	v_cvt_f32_f16_sdwa v31, v243 dst_sel:DWORD dst_unused:UNUSED_PAD src0_sel:WORD_1
	v_cvt_f32_f16_e32 v32, v244
	v_cvt_f32_f16_sdwa v33, v244 dst_sel:DWORD dst_unused:UNUSED_PAD src0_sel:WORD_1
	v_cvt_f32_f16_e32 v34, v245
	v_cvt_f32_f16_sdwa v35, v245 dst_sel:DWORD dst_unused:UNUSED_PAD src0_sel:WORD_1
	s_branch .Lau0_cvdp
.Lau0_cv1p:
	v_cvt_f32_f16_e32 v160, v230
	v_cvt_f32_f16_sdwa v161, v230 dst_sel:DWORD dst_unused:UNUSED_PAD src0_sel:WORD_1
	v_cvt_f32_f16_e32 v162, v231
	v_cvt_f32_f16_sdwa v163, v231 dst_sel:DWORD dst_unused:UNUSED_PAD src0_sel:WORD_1
	v_cvt_f32_f16_e32 v164, v232
	v_cvt_f32_f16_sdwa v165, v232 dst_sel:DWORD dst_unused:UNUSED_PAD src0_sel:WORD_1
	v_cvt_f32_f16_e32 v166, v233
	v_cvt_f32_f16_sdwa v167, v233 dst_sel:DWORD dst_unused:UNUSED_PAD src0_sel:WORD_1
	v_cvt_f32_f16_e32 v168, v234
	v_cvt_f32_f16_sdwa v169, v234 dst_sel:DWORD dst_unused:UNUSED_PAD src0_sel:WORD_1
	v_cvt_f32_f16_e32 v170, v235
	v_cvt_f32_f16_sdwa v171, v235 dst_sel:DWORD dst_unused:UNUSED_PAD src0_sel:WORD_1
	v_cvt_f32_f16_e32 v172, v236
	v_cvt_f32_f16_sdwa v173, v236 dst_sel:DWORD dst_unused:UNUSED_PAD src0_sel:WORD_1
	v_cvt_f32_f16_e32 v174, v237
	v_cvt_f32_f16_sdwa v175, v237 dst_sel:DWORD dst_unused:UNUSED_PAD src0_sel:WORD_1
	v_cvt_f32_f16_e32 v176, v238
	v_cvt_f32_f16_sdwa v177, v238 dst_sel:DWORD dst_unused:UNUSED_PAD src0_sel:WORD_1
	v_cvt_f32_f16_e32 v178, v239
	v_cvt_f32_f16_sdwa v179, v239 dst_sel:DWORD dst_unused:UNUSED_PAD src0_sel:WORD_1
	v_cvt_f32_f16_e32 v180, v240
	v_cvt_f32_f16_sdwa v181, v240 dst_sel:DWORD dst_unused:UNUSED_PAD src0_sel:WORD_1
	v_cvt_f32_f16_e32 v182, v241
	v_cvt_f32_f16_sdwa v183, v241 dst_sel:DWORD dst_unused:UNUSED_PAD src0_sel:WORD_1
	v_cvt_f32_f16_e32 v184, v242
	v_cvt_f32_f16_sdwa v185, v242 dst_sel:DWORD dst_unused:UNUSED_PAD src0_sel:WORD_1
	v_cvt_f32_f16_e32 v186, v243
	v_cvt_f32_f16_sdwa v187, v243 dst_sel:DWORD dst_unused:UNUSED_PAD src0_sel:WORD_1
	v_cvt_f32_f16_e32 v188, v244
	v_cvt_f32_f16_sdwa v189, v244 dst_sel:DWORD dst_unused:UNUSED_PAD src0_sel:WORD_1
	v_cvt_f32_f16_e32 v190, v245
	v_cvt_f32_f16_sdwa v191, v245 dst_sel:DWORD dst_unused:UNUSED_PAD src0_sel:WORD_1
.Lau0_cvdp:
	v_lshrrev_b32_e32 v249, 11, v36
	v_lshrrev_b32_e32 v250, 11, v37
	v_cmp_eq_u32_e64 s[52:53], s58, v249
	v_cmp_eq_u32_e64 s[54:55], s58, v250
	v_mul_u32_u24_e32 v44, 0x640, v36
	s_mov_b32 s61, 0
	s_lshl_b32 s63, s59, 9
	s_mul_i32 s1, s12, 0x2800
	s_add_u32 s63, s63, s1
	v_add_u32_e32 v46, s63, v226
	s_bcnt1_i32_b64 s1, s[52:53]
	s_bcnt1_i32_b64 s15, s[54:55]
	s_add_u32 s1, s1, s15
	s_sub_u32 s57, 8, s1
	s_cselect_b32 s57, 0, s57
	s_add_u32 s1, s59, 1
	s_cmp_lt_u32 s1, s50
	s_cbranch_scc1 .Lau0_pfkp
	s_mov_b32 s1, 0
	s_cmp_lt_u32 s58, 7
	s_cbranch_scc0 .Lau0_pfdp

; #define PB_FENCE asm volatile("" ::: "memory")
; __device__ __forceinline__ void ph_peer_apply(const Params& P, int layer, float* xlat, float* xctx_in, float* xctx_out, int nrows, bool write_next, char* smem, float* xlat_out = nullptr) {
;     ...
;     PB_LOAD(bufA, tu, 0);
;     for (int gq = 0; gq < NG; gq += 2) {
;       PB_LOAD(bufB, tu, gq + 1); PB_FENCE;
;       PB_DOT(bufA, gq);
;       if (gq + 2 < NG) PB_LOAD(bufA, tu, gq + 2);
;       PB_FENCE;
;       PB_DOT(bufB, gq + 1);
;     }
.Lau0_pfdp:
.Lau0_redop:
	s_bitcmp1_b32 s0, 2
	s_cbranch_scc1 .Lau0_rc1p_4
	s_bitcmp1_b32 s0, 1
	s_cbranch_scc1 .Lau0_rc1p_2
	s_bitcmp1_b32 s0, 0
	s_cbranch_scc1 .Lau0_rc1p_1
	s_branch .Lau0_issp0

; #define PB_FENCE asm volatile("" ::: "memory")
; __device__ __forceinline__ void ph_peer_apply(const Params& P, int layer, float* xlat, float* xctx_in, float* xctx_out, int nrows, bool write_next, char* smem, float* xlat_out = nullptr) {
;     ...
;     PB_LOAD(bufA, tu, 0);
;     for (int gq = 0; gq < NG; gq += 2) {
;       PB_LOAD(bufB, tu, gq + 1); PB_FENCE;
;       PB_DOT(bufA, gq);
;       if (gq + 2 < NG) PB_LOAD(bufA, tu, gq + 2);
;       PB_FENCE;
;       PB_DOT(bufB, gq + 1);
;     }
.Lau0_rc1p_2:
	s_bitcmp1_b32 s0, 0
	s_cbranch_scc1 .Lau0_rc1p_3
	s_branch .Lau0_issp2

; #define PB_FENCE asm volatile("" ::: "memory")
; __device__ __forceinline__ void ph_peer_apply(const Params& P, int layer, float* xlat, float* xctx_in, float* xctx_out, int nrows, bool write_next, char* smem, float* xlat_out = nullptr) {
;     ...
;     PB_LOAD(bufA, tu, 0);
;     for (int gq = 0; gq < NG; gq += 2) {
;       PB_LOAD(bufB, tu, gq + 1); PB_FENCE;
;       PB_DOT(bufA, gq);
;       if (gq + 2 < NG) PB_LOAD(bufA, tu, gq + 2);
;       PB_FENCE;
;       PB_DOT(bufB, gq + 1);
;     }
.Lau0_rc1p_4:
	s_bitcmp1_b32 s0, 1
	s_cbranch_scc1 .Lau0_rc1p_6
	s_bitcmp1_b32 s0, 0
	s_cbranch_scc1 .Lau0_rc1p_5
	s_branch .Lau0_issp4

.Lau0_padp:
	s_sub_u32 s57, s57, 1
.Lau0_dummyp:
	s_mov_b32 s26, 0
	s_mul_i32 s1, s12, 0x2800
	s_add_u32 s1, s1, 9216
	s_bitcmp1_b32 s0, 2
	s_cbranch_scc1 .Lau0_rc2p_4
	s_bitcmp1_b32 s0, 1
	s_cbranch_scc1 .Lau0_rc2p_2
	s_bitcmp1_b32 s0, 0
	s_cbranch_scc1 .Lau0_rc2p_1
	s_branch .Lau0_sdp0

; #define PB_FENCE asm volatile("" ::: "memory")
; __device__ __forceinline__ void ph_peer_apply(const Params& P, int layer, float* xlat, float* xctx_in, float* xctx_out, int nrows, bool write_next, char* smem, float* xlat_out = nullptr) {
;     ...
;     constexpr int NG = NSEL / PB_G;
;     PB_LOAD(bufA, tu, 0);
;     for (int gq = 0; gq < NG; gq += 2) {
;       PB_LOAD(bufB, tu, gq + 1); PB_FENCE;
;       PB_DOT(bufA, gq);
;       if (gq + 2 < NG) PB_LOAD(bufA, tu, gq + 2);
;       PB_FENCE;
;       PB_DOT(bufB, gq + 1);
;     }
.Lau0_pro2:
.Lau0_pass:
.Lau0_issl0:
	s_cmp_lg_u64 s[52:53], 0
	s_cbranch_scc0 .Lau0_slowl0
	s_ff1_i32_b64 s56, s[52:53]
	s_bitset0_b64 s[52:53], s56
	v_readlane_b32 s26, v44, s56
	v_readlane_b32 s1, v46, s56
.Lau0_sdl0:
	v_writelane_b32 v47, s1, 0
	s_waitcnt vmcnt(21)
	v_lshlrev_b32_e32 v246, 23, v54
	v_cvt_scalef32_pk32_f32_fp6 v[112:143], v[48:53], v246
	s_cmp_lg_u32 s33, 0
	s_mov_b32 s33, s62
	buffer_load_dwordx4 v[48:51], v2, s[16:19], s26 offen
	buffer_load_dwordx2 v[52:53], v2, s[16:19], s26 offen offset:16
	buffer_load_ubyte v54, v3, s[16:19], s26 offen
	s_cbranch_scc1 .Lau0_cB0
	v_pk_mul_f32 v[144:145], v[112:113], v[4:5]
	v_pk_fma_f32 v[144:145], v[114:115], v[6:7], v[144:145]
	v_pk_fma_f32 v[144:145], v[116:117], v[8:9], v[144:145]
	v_pk_fma_f32 v[144:145], v[118:119], v[10:11], v[144:145]
	v_pk_fma_f32 v[144:145], v[120:121], v[12:13], v[144:145]
	v_pk_fma_f32 v[144:145], v[122:123], v[14:15], v[144:145]
	v_pk_fma_f32 v[144:145], v[124:125], v[16:17], v[144:145]
	v_pk_fma_f32 v[144:145], v[126:127], v[18:19], v[144:145]
	v_pk_fma_f32 v[144:145], v[128:129], v[20:21], v[144:145]
	v_pk_fma_f32 v[144:145], v[130:131], v[22:23], v[144:145]
	v_pk_fma_f32 v[144:145], v[132:133], v[24:25], v[144:145]
	v_pk_fma_f32 v[144:145], v[134:135], v[26:27], v[144:145]
	v_pk_fma_f32 v[144:145], v[136:137], v[28:29], v[144:145]
	v_pk_fma_f32 v[144:145], v[138:139], v[30:31], v[144:145]
	v_pk_fma_f32 v[144:145], v[140:141], v[32:33], v[144:145]
	v_pk_fma_f32 v[144:145], v[142:143], v[34:35], v[144:145]
	v_add_f32_e32 v146, v144, v145
	s_branch .Lau0_cD0

; #define PB_FENCE asm volatile("" ::: "memory")
; __device__ __forceinline__ void ph_peer_apply(const Params& P, int layer, float* xlat, float* xctx_in, float* xctx_out, int nrows, bool write_next, char* smem, float* xlat_out = nullptr) {
;     ...
;     constexpr int NG = NSEL / PB_G;
;     PB_LOAD(bufA, tu, 0);
;     for (int gq = 0; gq < NG; gq += 2) {
;       PB_LOAD(bufB, tu, gq + 1); PB_FENCE;
;       PB_DOT(bufA, gq);
;       if (gq + 2 < NG) PB_LOAD(bufA, tu, gq + 2);
;       PB_FENCE;
;       PB_DOT(bufB, gq + 1);
;     }
.Lau0_cD0:
.Lau0_issl1:
	s_cmp_lg_u64 s[52:53], 0
	s_cbranch_scc0 .Lau0_slowl1
	s_ff1_i32_b64 s56, s[52:53]
	s_bitset0_b64 s[52:53], s56
	v_readlane_b32 s26, v44, s56
	v_readlane_b32 s1, v46, s56
.Lau0_sdl1:
	v_writelane_b32 v47, s1, 1
	s_waitcnt vmcnt(21)
	v_lshlrev_b32_e32 v246, 23, v62
	v_cvt_scalef32_pk32_f32_fp6 v[112:143], v[56:61], v246
	s_cmp_lg_u32 s38, 0
	s_mov_b32 s38, s62
	buffer_load_dwordx4 v[56:59], v2, s[16:19], s26 offen
	buffer_load_dwordx2 v[60:61], v2, s[16:19], s26 offen offset:16
	buffer_load_ubyte v62, v3, s[16:19], s26 offen
	s_cbranch_scc1 .Lau0_cB1
	v_pk_mul_f32 v[144:145], v[112:113], v[4:5]
	v_pk_fma_f32 v[144:145], v[114:115], v[6:7], v[144:145]
	v_pk_fma_f32 v[144:145], v[116:117], v[8:9], v[144:145]
	v_pk_fma_f32 v[144:145], v[118:119], v[10:11], v[144:145]
	v_pk_fma_f32 v[144:145], v[120:121], v[12:13], v[144:145]
	v_pk_fma_f32 v[144:145], v[122:123], v[14:15], v[144:145]
	v_pk_fma_f32 v[144:145], v[124:125], v[16:17], v[144:145]
	v_pk_fma_f32 v[144:145], v[126:127], v[18:19], v[144:145]
	v_pk_fma_f32 v[144:145], v[128:129], v[20:21], v[144:145]
	v_pk_fma_f32 v[144:145], v[130:131], v[22:23], v[144:145]
	v_pk_fma_f32 v[144:145], v[132:133], v[24:25], v[144:145]
	v_pk_fma_f32 v[144:145], v[134:135], v[26:27], v[144:145]
	v_pk_fma_f32 v[144:145], v[136:137], v[28:29], v[144:145]
	v_pk_fma_f32 v[144:145], v[138:139], v[30:31], v[144:145]
	v_pk_fma_f32 v[144:145], v[140:141], v[32:33], v[144:145]
	v_pk_fma_f32 v[144:145], v[142:143], v[34:35], v[144:145]
	v_add_f32_e32 v147, v144, v145
	s_branch .Lau0_cD1

; #define PB_FENCE asm volatile("" ::: "memory")
; __device__ __forceinline__ void ph_peer_apply(const Params& P, int layer, float* xlat, float* xctx_in, float* xctx_out, int nrows, bool write_next, char* smem, float* xlat_out = nullptr) {
;     ...
;     constexpr int NG = NSEL / PB_G;
;     PB_LOAD(bufA, tu, 0);
;     for (int gq = 0; gq < NG; gq += 2) {
;       PB_LOAD(bufB, tu, gq + 1); PB_FENCE;
;       PB_DOT(bufA, gq);
;       if (gq + 2 < NG) PB_LOAD(bufA, tu, gq + 2);
;       PB_FENCE;
;       PB_DOT(bufB, gq + 1);
;     }
.Lau0_sdl2:
	v_writelane_b32 v47, s1, 4
	s_waitcnt vmcnt(21)
	v_lshlrev_b32_e32 v246, 23, v70
	v_cvt_scalef32_pk32_f32_fp6 v[112:143], v[64:69], v246
	s_cmp_lg_u32 s39, 0
	s_mov_b32 s39, s62
	buffer_load_dwordx4 v[64:67], v2, s[16:19], s26 offen
	buffer_load_dwordx2 v[68:69], v2, s[16:19], s26 offen offset:16
	buffer_load_ubyte v70, v3, s[16:19], s26 offen
	s_cbranch_scc1 .Lau0_cB2
	v_pk_mul_f32 v[144:145], v[112:113], v[4:5]
	v_pk_fma_f32 v[144:145], v[114:115], v[6:7], v[144:145]
	v_pk_fma_f32 v[144:145], v[116:117], v[8:9], v[144:145]
	v_pk_fma_f32 v[144:145], v[118:119], v[10:11], v[144:145]
	v_pk_fma_f32 v[144:145], v[120:121], v[12:13], v[144:145]
	v_pk_fma_f32 v[144:145], v[122:123], v[14:15], v[144:145]
	v_pk_fma_f32 v[144:145], v[124:125], v[16:17], v[144:145]
	v_pk_fma_f32 v[144:145], v[126:127], v[18:19], v[144:145]
	v_pk_fma_f32 v[144:145], v[128:129], v[20:21], v[144:145]
	v_pk_fma_f32 v[144:145], v[130:131], v[22:23], v[144:145]
	v_pk_fma_f32 v[144:145], v[132:133], v[24:25], v[144:145]
	v_pk_fma_f32 v[144:145], v[134:135], v[26:27], v[144:145]
	v_pk_fma_f32 v[144:145], v[136:137], v[28:29], v[144:145]
	v_pk_fma_f32 v[144:145], v[138:139], v[30:31], v[144:145]
	v_pk_fma_f32 v[144:145], v[140:141], v[32:33], v[144:145]
	v_pk_fma_f32 v[144:145], v[142:143], v[34:35], v[144:145]
	v_add_f32_e32 v148, v144, v145
	s_branch .Lau0_cD2

; #define PB_FENCE asm volatile("" ::: "memory")
; __device__ __forceinline__ void ph_peer_apply(const Params& P, int layer, float* xlat, float* xctx_in, float* xctx_out, int nrows, bool write_next, char* smem, float* xlat_out = nullptr) {
;     ...
;     constexpr int NG = NSEL / PB_G;
;     PB_LOAD(bufA, tu, 0);
;     for (int gq = 0; gq < NG; gq += 2) {
;       PB_LOAD(bufB, tu, gq + 1); PB_FENCE;
;       PB_DOT(bufA, gq);
;       if (gq + 2 < NG) PB_LOAD(bufA, tu, gq + 2);
;       PB_FENCE;
;       PB_DOT(bufB, gq + 1);
;     }
.Lau0_sdl3:
	v_writelane_b32 v47, s1, 5
	s_waitcnt vmcnt(21)
	v_lshlrev_b32_e32 v246, 23, v78
	v_cvt_scalef32_pk32_f32_fp6 v[112:143], v[72:77], v246
	s_cmp_lg_u32 s51, 0
	s_mov_b32 s51, s62
	buffer_load_dwordx4 v[72:75], v2, s[16:19], s26 offen
	buffer_load_dwordx2 v[76:77], v2, s[16:19], s26 offen offset:16
	buffer_load_ubyte v78, v3, s[16:19], s26 offen
	s_cbranch_scc1 .Lau0_cB3
	v_pk_mul_f32 v[144:145], v[112:113], v[4:5]
	v_pk_fma_f32 v[144:145], v[114:115], v[6:7], v[144:145]
	v_pk_fma_f32 v[144:145], v[116:117], v[8:9], v[144:145]
	v_pk_fma_f32 v[144:145], v[118:119], v[10:11], v[144:145]
	v_pk_fma_f32 v[144:145], v[120:121], v[12:13], v[144:145]
	v_pk_fma_f32 v[144:145], v[122:123], v[14:15], v[144:145]
	v_pk_fma_f32 v[144:145], v[124:125], v[16:17], v[144:145]
	v_pk_fma_f32 v[144:145], v[126:127], v[18:19], v[144:145]
	v_pk_fma_f32 v[144:145], v[128:129], v[20:21], v[144:145]
	v_pk_fma_f32 v[144:145], v[130:131], v[22:23], v[144:145]
	v_pk_fma_f32 v[144:145], v[132:133], v[24:25], v[144:145]
	v_pk_fma_f32 v[144:145], v[134:135], v[26:27], v[144:145]
	v_pk_fma_f32 v[144:145], v[136:137], v[28:29], v[144:145]
	v_pk_fma_f32 v[144:145], v[138:139], v[30:31], v[144:145]
	v_pk_fma_f32 v[144:145], v[140:141], v[32:33], v[144:145]
	v_pk_fma_f32 v[144:145], v[142:143], v[34:35], v[144:145]
	v_add_f32_e32 v149, v144, v145
	s_branch .Lau0_cD3

; #define PB_FENCE asm volatile("" ::: "memory")
; __device__ __forceinline__ void ph_peer_apply(const Params& P, int layer, float* xlat, float* xctx_in, float* xctx_out, int nrows, bool write_next, char* smem, float* xlat_out = nullptr) {
;     ...
;     constexpr int NG = NSEL / PB_G;
;     PB_LOAD(bufA, tu, 0);
;     for (int gq = 0; gq < NG; gq += 2) {
;       PB_LOAD(bufB, tu, gq + 1); PB_FENCE;
;       PB_DOT(bufA, gq);
;       if (gq + 2 < NG) PB_LOAD(bufA, tu, gq + 2);
;       PB_FENCE;
;       PB_DOT(bufB, gq + 1);
;     }
.Lau0_sdl4:
	v_writelane_b32 v47, s1, 8
	s_waitcnt vmcnt(21)
	v_lshlrev_b32_e32 v246, 23, v86
	v_cvt_scalef32_pk32_f32_fp6 v[112:143], v[80:85], v246
	s_cmp_lg_u32 s28, 0
	s_mov_b32 s28, s62
	buffer_load_dwordx4 v[80:83], v2, s[16:19], s26 offen
	buffer_load_dwordx2 v[84:85], v2, s[16:19], s26 offen offset:16
	buffer_load_ubyte v86, v3, s[16:19], s26 offen
	s_cbranch_scc1 .Lau0_cB4
	v_pk_mul_f32 v[144:145], v[112:113], v[4:5]
	v_pk_fma_f32 v[144:145], v[114:115], v[6:7], v[144:145]
	v_pk_fma_f32 v[144:145], v[116:117], v[8:9], v[144:145]
	v_pk_fma_f32 v[144:145], v[118:119], v[10:11], v[144:145]
	v_pk_fma_f32 v[144:145], v[120:121], v[12:13], v[144:145]
	v_pk_fma_f32 v[144:145], v[122:123], v[14:15], v[144:145]
	v_pk_fma_f32 v[144:145], v[124:125], v[16:17], v[144:145]
	v_pk_fma_f32 v[144:145], v[126:127], v[18:19], v[144:145]
	v_pk_fma_f32 v[144:145], v[128:129], v[20:21], v[144:145]
	v_pk_fma_f32 v[144:145], v[130:131], v[22:23], v[144:145]
	v_pk_fma_f32 v[144:145], v[132:133], v[24:25], v[144:145]
	v_pk_fma_f32 v[144:145], v[134:135], v[26:27], v[144:145]
	v_pk_fma_f32 v[144:145], v[136:137], v[28:29], v[144:145]
	v_pk_fma_f32 v[144:145], v[138:139], v[30:31], v[144:145]
	v_pk_fma_f32 v[144:145], v[140:141], v[32:33], v[144:145]
	v_pk_fma_f32 v[144:145], v[142:143], v[34:35], v[144:145]
	v_add_f32_e32 v150, v144, v145
	s_branch .Lau0_cD4

; #define PB_FENCE asm volatile("" ::: "memory")
; __device__ __forceinline__ void ph_peer_apply(const Params& P, int layer, float* xlat, float* xctx_in, float* xctx_out, int nrows, bool write_next, char* smem, float* xlat_out = nullptr) {
;     ...
;     constexpr int NG = NSEL / PB_G;
;     PB_LOAD(bufA, tu, 0);
;     for (int gq = 0; gq < NG; gq += 2) {
;       PB_LOAD(bufB, tu, gq + 1); PB_FENCE;
;       PB_DOT(bufA, gq);
;       if (gq + 2 < NG) PB_LOAD(bufA, tu, gq + 2);
;       PB_FENCE;
;       PB_DOT(bufB, gq + 1);
;     }
.Lau0_sdl5:
	v_writelane_b32 v47, s1, 9
	s_waitcnt vmcnt(21)
	v_lshlrev_b32_e32 v246, 23, v94
	v_cvt_scalef32_pk32_f32_fp6 v[112:143], v[88:93], v246
	s_cmp_lg_u32 s30, 0
	s_mov_b32 s30, s62
	buffer_load_dwordx4 v[88:91], v2, s[16:19], s26 offen
	buffer_load_dwordx2 v[92:93], v2, s[16:19], s26 offen offset:16
	buffer_load_ubyte v94, v3, s[16:19], s26 offen
	s_cbranch_scc1 .Lau0_cB5
	v_pk_mul_f32 v[144:145], v[112:113], v[4:5]
	v_pk_fma_f32 v[144:145], v[114:115], v[6:7], v[144:145]
	v_pk_fma_f32 v[144:145], v[116:117], v[8:9], v[144:145]
	v_pk_fma_f32 v[144:145], v[118:119], v[10:11], v[144:145]
	v_pk_fma_f32 v[144:145], v[120:121], v[12:13], v[144:145]
	v_pk_fma_f32 v[144:145], v[122:123], v[14:15], v[144:145]
	v_pk_fma_f32 v[144:145], v[124:125], v[16:17], v[144:145]
	v_pk_fma_f32 v[144:145], v[126:127], v[18:19], v[144:145]
	v_pk_fma_f32 v[144:145], v[128:129], v[20:21], v[144:145]
	v_pk_fma_f32 v[144:145], v[130:131], v[22:23], v[144:145]
	v_pk_fma_f32 v[144:145], v[132:133], v[24:25], v[144:145]
	v_pk_fma_f32 v[144:145], v[134:135], v[26:27], v[144:145]
	v_pk_fma_f32 v[144:145], v[136:137], v[28:29], v[144:145]
	v_pk_fma_f32 v[144:145], v[138:139], v[30:31], v[144:145]
	v_pk_fma_f32 v[144:145], v[140:141], v[32:33], v[144:145]
	v_pk_fma_f32 v[144:145], v[142:143], v[34:35], v[144:145]
	v_add_f32_e32 v151, v144, v145
	s_branch .Lau0_cD5

; #define PB_FENCE asm volatile("" ::: "memory")
; __device__ __forceinline__ void ph_peer_apply(const Params& P, int layer, float* xlat, float* xctx_in, float* xctx_out, int nrows, bool write_next, char* smem, float* xlat_out = nullptr) {
;     ...
;     constexpr int NG = NSEL / PB_G;
;     PB_LOAD(bufA, tu, 0);
;     for (int gq = 0; gq < NG; gq += 2) {
;       PB_LOAD(bufB, tu, gq + 1); PB_FENCE;
;       PB_DOT(bufA, gq);
;       if (gq + 2 < NG) PB_LOAD(bufA, tu, gq + 2);
;       PB_FENCE;
;       PB_DOT(bufB, gq + 1);
;     }
.Lau0_sdl6:
	v_writelane_b32 v47, s1, 12
	s_waitcnt vmcnt(21)
	v_lshlrev_b32_e32 v246, 23, v102
	v_cvt_scalef32_pk32_f32_fp6 v[112:143], v[96:101], v246
	s_cmp_lg_u32 s36, 0
	s_mov_b32 s36, s62
	buffer_load_dwordx4 v[96:99], v2, s[16:19], s26 offen
	buffer_load_dwordx2 v[100:101], v2, s[16:19], s26 offen offset:16
	buffer_load_ubyte v102, v3, s[16:19], s26 offen
	s_cbranch_scc1 .Lau0_cB6
	v_pk_mul_f32 v[144:145], v[112:113], v[4:5]
	v_pk_fma_f32 v[144:145], v[114:115], v[6:7], v[144:145]
	v_pk_fma_f32 v[144:145], v[116:117], v[8:9], v[144:145]
	v_pk_fma_f32 v[144:145], v[118:119], v[10:11], v[144:145]
	v_pk_fma_f32 v[144:145], v[120:121], v[12:13], v[144:145]
	v_pk_fma_f32 v[144:145], v[122:123], v[14:15], v[144:145]
	v_pk_fma_f32 v[144:145], v[124:125], v[16:17], v[144:145]
	v_pk_fma_f32 v[144:145], v[126:127], v[18:19], v[144:145]
	v_pk_fma_f32 v[144:145], v[128:129], v[20:21], v[144:145]
	v_pk_fma_f32 v[144:145], v[130:131], v[22:23], v[144:145]
	v_pk_fma_f32 v[144:145], v[132:133], v[24:25], v[144:145]
	v_pk_fma_f32 v[144:145], v[134:135], v[26:27], v[144:145]
	v_pk_fma_f32 v[144:145], v[136:137], v[28:29], v[144:145]
	v_pk_fma_f32 v[144:145], v[138:139], v[30:31], v[144:145]
	v_pk_fma_f32 v[144:145], v[140:141], v[32:33], v[144:145]
	v_pk_fma_f32 v[144:145], v[142:143], v[34:35], v[144:145]
	v_add_f32_e32 v152, v144, v145
	s_branch .Lau0_cD6

; #define PB_FENCE asm volatile("" ::: "memory")
; __device__ __forceinline__ void ph_peer_apply(const Params& P, int layer, float* xlat, float* xctx_in, float* xctx_out, int nrows, bool write_next, char* smem, float* xlat_out = nullptr) {
;     ...
;     constexpr int NG = NSEL / PB_G;
;     PB_LOAD(bufA, tu, 0);
;     for (int gq = 0; gq < NG; gq += 2) {
;       PB_LOAD(bufB, tu, gq + 1); PB_FENCE;
;       PB_DOT(bufA, gq);
;       if (gq + 2 < NG) PB_LOAD(bufA, tu, gq + 2);
;       PB_FENCE;
;       PB_DOT(bufB, gq + 1);
;     }
.Lau0_sdl7:
	v_writelane_b32 v47, s1, 13
	s_waitcnt vmcnt(21)
	v_lshlrev_b32_e32 v246, 23, v110
	v_cvt_scalef32_pk32_f32_fp6 v[112:143], v[104:109], v246
	s_cmp_lg_u32 s37, 0
	s_mov_b32 s37, s62
	buffer_load_dwordx4 v[104:107], v2, s[16:19], s26 offen
	buffer_load_dwordx2 v[108:109], v2, s[16:19], s26 offen offset:16
	buffer_load_ubyte v110, v3, s[16:19], s26 offen
	s_cbranch_scc1 .Lau0_cB7
	v_pk_mul_f32 v[144:145], v[112:113], v[4:5]
	v_pk_fma_f32 v[144:145], v[114:115], v[6:7], v[144:145]
	v_pk_fma_f32 v[144:145], v[116:117], v[8:9], v[144:145]
	v_pk_fma_f32 v[144:145], v[118:119], v[10:11], v[144:145]
	v_pk_fma_f32 v[144:145], v[120:121], v[12:13], v[144:145]
	v_pk_fma_f32 v[144:145], v[122:123], v[14:15], v[144:145]
	v_pk_fma_f32 v[144:145], v[124:125], v[16:17], v[144:145]
	v_pk_fma_f32 v[144:145], v[126:127], v[18:19], v[144:145]
	v_pk_fma_f32 v[144:145], v[128:129], v[20:21], v[144:145]
	v_pk_fma_f32 v[144:145], v[130:131], v[22:23], v[144:145]
	v_pk_fma_f32 v[144:145], v[132:133], v[24:25], v[144:145]
	v_pk_fma_f32 v[144:145], v[134:135], v[26:27], v[144:145]
	v_pk_fma_f32 v[144:145], v[136:137], v[28:29], v[144:145]
	v_pk_fma_f32 v[144:145], v[138:139], v[30:31], v[144:145]
	v_pk_fma_f32 v[144:145], v[140:141], v[32:33], v[144:145]
	v_pk_fma_f32 v[144:145], v[142:143], v[34:35], v[144:145]
	v_add_f32_e32 v153, v144, v145
	s_branch .Lau0_cD7

; __device__ __forceinline__ float row_sum16(float v) { v += __shfl_xor(v, 1); v += __shfl_xor(v, 2); v += __shfl_xor(v, 4); v += __shfl_xor(v, 8); return v; }
; __device__ __forceinline__ float wave_sum(float v) { v = row_sum16(v); v += __shfl_xor(v, 16); v += __shfl_xor(v, 32); return v; }
; __device__ __forceinline__ float row_sum16(float v) { v += dppf<0xB1>(v); v += dppf<0x4E>(v); v += dppf<0x124>(v); v += dppf<0x128>(v); return v; }
; __device__ __forceinline__ float wave_sum(float v) {
;   v = row_sum16(v);
;   const float r0 = __builtin_bit_cast(float, __builtin_amdgcn_readlane(__builtin_bit_cast(int, v), 0));
;   const float r1 = __builtin_bit_cast(float, __builtin_amdgcn_readlane(__builtin_bit_cast(int, v), 16));
;   const float r2 = __builtin_bit_cast(float, __builtin_amdgcn_readlane(__builtin_bit_cast(int, v), 32));
;   const float r3 = __builtin_bit_cast(float, __builtin_amdgcn_readlane(__builtin_bit_cast(int, v), 48));
;   return (r0 + r1) + (r2 + r3);
; }
.Lau0_cD7:
	v_mov_b32_e32 v229, v45
	v_add_f32_dpp v146, v146, v146 row_ror:8 row_mask:0xf bank_mask:0xf bound_ctrl:1
	v_add_f32_dpp v147, v147, v147 row_ror:8 row_mask:0xf bank_mask:0xf bound_ctrl:1
	v_add_f32_dpp v148, v148, v148 row_ror:8 row_mask:0xf bank_mask:0xf bound_ctrl:1
	v_add_f32_dpp v149, v149, v149 row_ror:8 row_mask:0xf bank_mask:0xf bound_ctrl:1
	v_add_f32_dpp v146, v150, v150 row_ror:8 row_mask:0xf bank_mask:0xc bound_ctrl:1
	v_add_f32_dpp v147, v151, v151 row_ror:8 row_mask:0xf bank_mask:0xc bound_ctrl:1
	v_add_f32_dpp v148, v152, v152 row_ror:8 row_mask:0xf bank_mask:0xc bound_ctrl:1
	v_add_f32_dpp v149, v153, v153 row_ror:8 row_mask:0xf bank_mask:0xc bound_ctrl:1
	v_add_f32_dpp v146, v146, v146 row_half_mirror row_mask:0xf bank_mask:0xf bound_ctrl:1
	v_add_f32_dpp v147, v147, v147 row_half_mirror row_mask:0xf bank_mask:0xf bound_ctrl:1
	v_add_f32_dpp v146, v148, v148 row_half_mirror row_mask:0xf bank_mask:0xa bound_ctrl:1
	v_add_f32_dpp v147, v149, v149 row_half_mirror row_mask:0xf bank_mask:0xa bound_ctrl:1
	s_nop 1
	v_add_f32_dpp v146, v146, v146 quad_perm:[1,0,3,2] row_mask:0xf bank_mask:0xf bound_ctrl:1
	v_add_f32_dpp v147, v147, v147 quad_perm:[1,0,3,2] row_mask:0xf bank_mask:0xf bound_ctrl:1
	s_nop 0
	v_add_f32_dpp v146, v146, v146 quad_perm:[2,3,0,1] row_mask:0xf bank_mask:0xf bound_ctrl:1
	v_add_f32_dpp v147, v147, v147 quad_perm:[2,3,0,1] row_mask:0xf bank_mask:0xf bound_ctrl:1
	v_mov_b32_e32 v247, v146
	v_mov_b32_e32 v248, v147
	s_nop 1
	v_permlane32_swap_b32_e32 v247, v146
	v_permlane32_swap_b32_e32 v248, v147
	v_add_f32_e32 v146, v146, v247
	v_add_f32_e32 v147, v147, v248
	v_mov_b32_e32 v247, v146
	v_mov_b32_e32 v248, v147
	s_nop 1
	v_permlane16_swap_b32_e32 v247, v146
	v_permlane16_swap_b32_e32 v248, v147
	v_add_f32_e32 v146, v146, v247
	v_add_f32_e32 v147, v147, v248
	v_cndmask_b32_e64 v146, v146, v147, s[34:35]
	s_mov_b64 exec, s[46:47]
	ds_write_b32 v229, v146
	s_mov_b64 exec, -1
	v_mov_b32_e32 v45, v47
	s_cmp_lg_u32 s48, 0
	s_cbranch_scc0 .Lau0_pass
	s_add_u32 s49, s49, 1
	s_cmp_lt_u32 s49, 2
	s_cbranch_scc1 .Lau0_pass
	s_branch .Lau0_s1end

; __device__ __forceinline__ float geluf_(float x) { return 0.5f * x * (1.0f + tanhf(0.7978845608028654f * (x + 0.044715f * x * x * x))); }
; #define PB_FENCE asm volatile("" ::: "memory")
; __device__ __forceinline__ void ph_peer_apply(const Params& P, int layer, float* xlat, float* xctx_in, float* xctx_out, int nrows, bool write_next, char* smem, float* xlat_out = nullptr) {
;     ...
;     PB_LOAD(bufA, tu, 0);
;     for (int gq = 0; gq < NG; gq += 2) {
;       PB_LOAD(bufB, tu, gq + 1); PB_FENCE;
;       PB_DOT(bufA, gq);
;       if (gq + 2 < NG) PB_LOAD(bufA, tu, gq + 2);
;       PB_FENCE;
;       PB_DOT(bufB, gq + 1);
;     }
;     a0 = geluf_(a0) * g0; a1 = geluf_(a1) * g1;
.Lau0_rc2l_7:
	s_branch .Lau0_sdl7
.Lau0_s1end:
	s_waitcnt vmcnt(0) lgkmcnt(0)
	s_mov_b32 s14, 0
	s_mov_b32 s45, s13

; __device__ __forceinline__ float geluf_(float x) { return 0.5f * x * (1.0f + tanhf(0.7978845608028654f * (x + 0.044715f * x * x * x))); }
; __device__ __forceinline__ void ph_peer_apply(const Params& P, int layer, float* xlat, float* xctx_in, float* xctx_out, int nrows, bool write_next, char* smem, float* xlat_out = nullptr) {
;     ...
;     const int id0 = seli[(size_t)row * NSEL + lane], id1 = seli[(size_t)row * NSEL + 64 + lane];
;     const float g0 = selg[(size_t)row * NSEL + lane], g1 = selg[(size_t)row * NSEL + 64 + lane];
;     ...
;     a0 = geluf_(a0) * g0; a1 = geluf_(a1) * g1;
;     float o[32];
; #pragma unroll
;     for (int j = 0; j < 32; ++j) o[j] = 0.f;
;     ...
;     PB_LOAD(bufA, tv, 0);
.Lap0_gl_done:
	s_waitcnt lgkmcnt(0)
	s_add_u32 s16, s4, 0x7c7c000
	s_addc_u32 s17, s5, 0
	s_and_b32 s17, s17, 0xffff
	s_mov_b32 s18, 0x1900000
	s_mov_b32 s19, 0x20000
	s_mov_b32 s62, 0
	s_mov_b32 s1, s13
.Lav0_ntl:
	s_add_u32 s62, s62, 1
	s_add_u32 s1, s1, s44
	s_cmp_lt_u32 s1, 0x8200
	s_cbranch_scc1 .Lav0_ntl
	s_mov_b32 s51, 0
.Lav0_group:
	s_sub_u32 s57, s62, s51
	s_min_u32 s57, s57, 4
	s_add_u32 s1, s51, 0
	s_lshl_b32 s31, s1, 9
	s_mul_i32 s1, s1, s44
	s_add_u32 s1, s1, s13
	s_lshl_b32 s15, s1, 9
	s_add_u32 s22, s4, 0x1404c000
	s_addc_u32 s23, s5, 0
	s_add_u32 s22, s22, s15
	s_addc_u32 s23, s23, 0
	global_load_dword v36, v226, s[22:23]
	global_load_dword v37, v226, s[22:23] offset:256
	v_add_u32_e32 v229, s31, v228
	ds_read_b32 v112, v229
	ds_read_b32 v113, v229 offset:256
	s_cmp_le_u32 s57, 1
	s_cbranch_scc1 .Lav0_ldd
	s_add_u32 s1, s51, 1
	s_lshl_b32 s31, s1, 9
	s_mul_i32 s1, s1, s44
	s_add_u32 s1, s1, s13
	s_lshl_b32 s15, s1, 9
	s_add_u32 s22, s4, 0x1404c000
	s_addc_u32 s23, s5, 0
	s_add_u32 s22, s22, s15
	s_addc_u32 s23, s23, 0
	global_load_dword v38, v226, s[22:23]
	global_load_dword v39, v226, s[22:23] offset:256
	v_add_u32_e32 v229, s31, v228
	ds_read_b32 v146, v229
	ds_read_b32 v147, v229 offset:256
	s_cmp_le_u32 s57, 2
	s_cbranch_scc1 .Lav0_ldd
	s_add_u32 s1, s51, 2
	s_lshl_b32 s31, s1, 9
	s_mul_i32 s1, s1, s44
	s_add_u32 s1, s1, s13
	s_lshl_b32 s15, s1, 9
	s_add_u32 s22, s4, 0x1404c000
	s_addc_u32 s23, s5, 0
	s_add_u32 s22, s22, s15
	s_addc_u32 s23, s23, 0
	global_load_dword v40, v226, s[22:23]
	global_load_dword v41, v226, s[22:23] offset:256
	v_add_u32_e32 v229, s31, v228
	ds_read_b32 v230, v229
	ds_read_b32 v231, v229 offset:256
	s_cmp_le_u32 s57, 3
	s_cbranch_scc1 .Lav0_ldd
	s_add_u32 s1, s51, 3
	s_lshl_b32 s31, s1, 9
	s_mul_i32 s1, s1, s44
	s_add_u32 s1, s1, s13
	s_lshl_b32 s15, s1, 9
	s_add_u32 s22, s4, 0x1404c000
	s_addc_u32 s23, s5, 0
	s_add_u32 s22, s22, s15
	s_addc_u32 s23, s23, 0
	global_load_dword v42, v226, s[22:23]
	global_load_dword v43, v226, s[22:23] offset:256
	v_add_u32_e32 v229, s31, v228
	ds_read_b32 v252, v229
	ds_read_b32 v253, v229 offset:256
.Lav0_ldd:
	v_mov_b32_e32 v160, 0
	v_mov_b32_e32 v161, 0
	v_mov_b32_e32 v162, 0
	v_mov_b32_e32 v163, 0
	v_mov_b32_e32 v164, 0
	v_mov_b32_e32 v165, 0
	v_mov_b32_e32 v166, 0
	v_mov_b32_e32 v167, 0
	v_mov_b32_e32 v168, 0
	v_mov_b32_e32 v169, 0
	v_mov_b32_e32 v170, 0
	v_mov_b32_e32 v171, 0
	v_mov_b32_e32 v172, 0
	v_mov_b32_e32 v173, 0
	v_mov_b32_e32 v174, 0
	v_mov_b32_e32 v175, 0
	v_mov_b32_e32 v176, 0
	v_mov_b32_e32 v177, 0
	v_mov_b32_e32 v178, 0
	v_mov_b32_e32 v179, 0
	v_mov_b32_e32 v180, 0
	v_mov_b32_e32 v181, 0
	v_mov_b32_e32 v182, 0
	v_mov_b32_e32 v183, 0
	v_mov_b32_e32 v184, 0
	v_mov_b32_e32 v185, 0
	v_mov_b32_e32 v186, 0
	v_mov_b32_e32 v187, 0
	v_mov_b32_e32 v188, 0
	v_mov_b32_e32 v189, 0
	v_mov_b32_e32 v190, 0
	v_mov_b32_e32 v191, 0
	v_mov_b32_e32 v4, 0
	v_mov_b32_e32 v5, 0
	v_mov_b32_e32 v6, 0
	v_mov_b32_e32 v7, 0
	v_mov_b32_e32 v8, 0
	v_mov_b32_e32 v9, 0
	v_mov_b32_e32 v10, 0
	v_mov_b32_e32 v11, 0
	v_mov_b32_e32 v12, 0
	v_mov_b32_e32 v13, 0
	v_mov_b32_e32 v14, 0
	v_mov_b32_e32 v15, 0
	v_mov_b32_e32 v16, 0
	v_mov_b32_e32 v17, 0
	v_mov_b32_e32 v18, 0
	v_mov_b32_e32 v19, 0
	v_mov_b32_e32 v20, 0
	v_mov_b32_e32 v21, 0
	v_mov_b32_e32 v22, 0
	v_mov_b32_e32 v23, 0
	v_mov_b32_e32 v24, 0
	v_mov_b32_e32 v25, 0
	v_mov_b32_e32 v26, 0
	v_mov_b32_e32 v27, 0
	v_mov_b32_e32 v28, 0
	v_mov_b32_e32 v29, 0
	v_mov_b32_e32 v30, 0
	v_mov_b32_e32 v31, 0
	v_mov_b32_e32 v32, 0
	v_mov_b32_e32 v33, 0
	v_mov_b32_e32 v34, 0
	v_mov_b32_e32 v35, 0
	v_mov_b32_e32 v192, 0
	v_mov_b32_e32 v193, 0
	v_mov_b32_e32 v194, 0
	v_mov_b32_e32 v195, 0
	v_mov_b32_e32 v196, 0
	v_mov_b32_e32 v197, 0
	v_mov_b32_e32 v198, 0
	v_mov_b32_e32 v199, 0
	v_mov_b32_e32 v200, 0
	v_mov_b32_e32 v201, 0
	v_mov_b32_e32 v202, 0
	v_mov_b32_e32 v203, 0
	v_mov_b32_e32 v204, 0
	v_mov_b32_e32 v205, 0
	v_mov_b32_e32 v206, 0
	v_mov_b32_e32 v207, 0
	v_mov_b32_e32 v208, 0
	v_mov_b32_e32 v209, 0
	v_mov_b32_e32 v210, 0
	v_mov_b32_e32 v211, 0
	v_mov_b32_e32 v212, 0
	v_mov_b32_e32 v213, 0
	v_mov_b32_e32 v214, 0
	v_mov_b32_e32 v215, 0
	v_mov_b32_e32 v216, 0
	v_mov_b32_e32 v217, 0
	v_mov_b32_e32 v218, 0
	v_mov_b32_e32 v219, 0
	v_mov_b32_e32 v220, 0
	v_mov_b32_e32 v221, 0
	v_mov_b32_e32 v222, 0
	v_mov_b32_e32 v223, 0
	v_mov_b32_e32 v148, 0
	v_mov_b32_e32 v149, 0
	v_mov_b32_e32 v150, 0
	v_mov_b32_e32 v151, 0
	v_mov_b32_e32 v152, 0
	v_mov_b32_e32 v153, 0
	v_mov_b32_e32 v154, 0
	v_mov_b32_e32 v155, 0
	v_mov_b32_e32 v156, 0
	v_mov_b32_e32 v157, 0
	v_mov_b32_e32 v158, 0
	v_mov_b32_e32 v159, 0
	v_mov_b32_e32 v232, 0
	v_mov_b32_e32 v233, 0
	v_mov_b32_e32 v234, 0
	v_mov_b32_e32 v235, 0
	v_mov_b32_e32 v236, 0
	v_mov_b32_e32 v237, 0
	v_mov_b32_e32 v238, 0
	v_mov_b32_e32 v239, 0
	v_mov_b32_e32 v240, 0
	v_mov_b32_e32 v241, 0
	v_mov_b32_e32 v242, 0
	v_mov_b32_e32 v243, 0
	v_mov_b32_e32 v244, 0
	v_mov_b32_e32 v245, 0
	v_mov_b32_e32 v246, 0
	v_mov_b32_e32 v247, 0
	v_mov_b32_e32 v248, 0
	v_mov_b32_e32 v249, 0
	v_mov_b32_e32 v250, 0
	v_mov_b32_e32 v251, 0
	s_mov_b64 s[52:53], 0
	s_mov_b64 s[54:55], 0
	s_mov_b32 s61, 1
	s_mov_b32 s59, -1
	s_mov_b32 s58, 0
	s_mov_b32 s48, 0
	s_mov_b32 s49, 0
	s_waitcnt vmcnt(0) lgkmcnt(0)

.Lav0_sdp0:
	s_nop 2
	s_mov_b32 s20, s1
	s_mov_b32 s21, s59
	buffer_load_dwordx4 v[48:51], v2, s[16:19], s26 offen
	buffer_load_dwordx2 v[52:53], v2, s[16:19], s26 offen offset:16
	buffer_load_ubyte v54, v3, s[16:19], s26 offen

.Lav0_sdp1:
	s_nop 2
	s_mov_b32 s22, s1
	s_mov_b32 s23, s59
	buffer_load_dwordx4 v[56:59], v2, s[16:19], s26 offen
	buffer_load_dwordx2 v[60:61], v2, s[16:19], s26 offen offset:16
	buffer_load_ubyte v62, v3, s[16:19], s26 offen

.Lav0_sdp2:
	s_nop 2
	s_mov_b32 s24, s1
	s_mov_b32 s25, s59
	buffer_load_dwordx4 v[64:67], v2, s[16:19], s26 offen
	buffer_load_dwordx2 v[68:69], v2, s[16:19], s26 offen offset:16
	buffer_load_ubyte v70, v3, s[16:19], s26 offen

.Lav0_sdp3:
	s_nop 2
	s_mov_b32 s30, s1
	s_mov_b32 s31, s59
	buffer_load_dwordx4 v[72:75], v2, s[16:19], s26 offen
	buffer_load_dwordx2 v[76:77], v2, s[16:19], s26 offen offset:16
	buffer_load_ubyte v78, v3, s[16:19], s26 offen

.Lav0_sdp4:
	s_nop 2
	s_mov_b32 s36, s1
	s_mov_b32 s37, s59
	buffer_load_dwordx4 v[80:83], v2, s[16:19], s26 offen
	buffer_load_dwordx2 v[84:85], v2, s[16:19], s26 offen offset:16
	buffer_load_ubyte v86, v3, s[16:19], s26 offen

.Lav0_sdp5:
	s_nop 2
	s_mov_b32 s38, s1
	s_mov_b32 s39, s59
	buffer_load_dwordx4 v[88:91], v2, s[16:19], s26 offen
	buffer_load_dwordx2 v[92:93], v2, s[16:19], s26 offen offset:16
	buffer_load_ubyte v94, v3, s[16:19], s26 offen

.Lav0_sdp6:
	s_nop 2
	s_mov_b32 s40, s1
	s_mov_b32 s41, s59
	buffer_load_dwordx4 v[96:99], v2, s[16:19], s26 offen
	buffer_load_dwordx2 v[100:101], v2, s[16:19], s26 offen offset:16
	buffer_load_ubyte v102, v3, s[16:19], s26 offen

.Lav0_sdp7:
	s_nop 2
	s_mov_b32 s42, s1
	s_mov_b32 s43, s59
	buffer_load_dwordx4 v[104:107], v2, s[16:19], s26 offen
	buffer_load_dwordx2 v[108:109], v2, s[16:19], s26 offen offset:16
	buffer_load_ubyte v110, v3, s[16:19], s26 offen
	s_branch .Lav0_pass

; #define PB_FENCE asm volatile("" ::: "memory")
; __device__ __forceinline__ void ph_peer_apply(const Params& P, int layer, float* xlat, float* xctx_in, float* xctx_out, int nrows, bool write_next, char* smem, float* xlat_out = nullptr) {
;     ...
;     PB_LOAD(bufA, tv, 0);
;     for (int gq = 0; gq < NG; gq += 2) {
;       PB_LOAD(bufB, tv, gq + 1); PB_FENCE;
;       PB_ACC(bufA, gq);
;       if (gq + 2 < NG) PB_LOAD(bufA, tv, gq + 2);
;       PB_FENCE;
;       PB_ACC(bufB, gq + 1);
;     }
.Lav0_slowcp:
	s_cmp_lg_u32 s61, 0
	s_cbranch_scc1 .Lav0_h1p
	s_mov_b32 s61, 1
	s_mov_b64 s[52:53], s[54:55]
	v_mov_b32_e32 v44, v45
	v_mov_b32_e32 v46, v47
	s_branch .Lav0_redop
.Lav0_h1p:
	s_cmp_lg_u32 s48, 0
	s_cbranch_scc1 .Lav0_dummyp
	s_add_u32 s59, s59, 1
	s_cmp_lt_u32 s59, s57
	s_cbranch_scc1 .Lav0_nvp
	s_mov_b32 s59, 0
	s_add_u32 s58, s58, 1
	s_cmp_lt_u32 s58, 8
	s_cbranch_scc1 .Lav0_nvp
	s_mov_b32 s48, 1
	s_branch .Lav0_dummyp
.Lav0_nvp:
	s_cmp_eq_u32 s59, 1
	s_cbranch_scc1 .Lav0_nvp_1
	s_cmp_eq_u32 s59, 2
	s_cbranch_scc1 .Lav0_nvp_2
	s_cmp_eq_u32 s59, 3
	s_cbranch_scc1 .Lav0_nvp_3
	v_lshrrev_b32_e32 v114, 11, v36
	v_lshrrev_b32_e32 v115, 11, v37
	v_mul_u32_u24_e32 v44, 0x640, v36
	v_mul_u32_u24_e32 v45, 0x640, v37
	v_mov_b32_e32 v46, v112
	v_mov_b32_e32 v47, v113
	s_branch .Lav0_nvdp
.Lav0_nvp_1:
	v_lshrrev_b32_e32 v114, 11, v38
	v_lshrrev_b32_e32 v115, 11, v39
	v_mul_u32_u24_e32 v44, 0x640, v38
	v_mul_u32_u24_e32 v45, 0x640, v39
	v_mov_b32_e32 v46, v146
	v_mov_b32_e32 v47, v147
	s_branch .Lav0_nvdp
.Lav0_nvp_2:
	v_lshrrev_b32_e32 v114, 11, v40
	v_lshrrev_b32_e32 v115, 11, v41
	v_mul_u32_u24_e32 v44, 0x640, v40
	v_mul_u32_u24_e32 v45, 0x640, v41
	v_mov_b32_e32 v46, v230
	v_mov_b32_e32 v47, v231
	s_branch .Lav0_nvdp
.Lav0_nvp_3:
	v_lshrrev_b32_e32 v114, 11, v42
	v_lshrrev_b32_e32 v115, 11, v43
	v_mul_u32_u24_e32 v44, 0x640, v42
	v_mul_u32_u24_e32 v45, 0x640, v43
	v_mov_b32_e32 v46, v252
	v_mov_b32_e32 v47, v253
.Lav0_nvdp:
	v_cmp_eq_u32_e64 s[52:53], s58, v114
	v_cmp_eq_u32_e64 s[54:55], s58, v115
	s_mov_b32 s61, 0
.Lav0_redop:
	s_bitcmp1_b32 s0, 2
	s_cbranch_scc1 .Lav0_rc1p_4
	s_bitcmp1_b32 s0, 1
	s_cbranch_scc1 .Lav0_rc1p_2
	s_bitcmp1_b32 s0, 0
	s_cbranch_scc1 .Lav0_rc1p_1
	s_branch .Lav0_issp0

.Lav0_dummyp:
	s_mov_b32 s26, 0
	s_mov_b32 s1, 0
	s_bitcmp1_b32 s0, 2
	s_cbranch_scc1 .Lav0_rc2p_4
	s_bitcmp1_b32 s0, 1
	s_cbranch_scc1 .Lav0_rc2p_2
	s_bitcmp1_b32 s0, 0
	s_cbranch_scc1 .Lav0_rc2p_1
	s_branch .Lav0_sdp0

; #define PB_FENCE asm volatile("" ::: "memory")
; __device__ __forceinline__ void ph_peer_apply(const Params& P, int layer, float* xlat, float* xctx_in, float* xctx_out, int nrows, bool write_next, char* smem, float* xlat_out = nullptr) {
;     ...
;     PB_LOAD(bufA, tv, 0);
;     for (int gq = 0; gq < NG; gq += 2) {
;       PB_LOAD(bufB, tv, gq + 1); PB_FENCE;
;       PB_ACC(bufA, gq);
;       if (gq + 2 < NG) PB_LOAD(bufA, tv, gq + 2);
;       PB_FENCE;
;       PB_ACC(bufB, gq + 1);
;     }
.Lav0_sdl0:
	s_waitcnt vmcnt(21)
	v_lshlrev_b32_e32 v54, 23, v54
	v_cvt_scalef32_pk32_f32_fp6 v[114:145], v[48:53], v54
	s_bitcmp1_b32 s21, 1
	buffer_load_dwordx4 v[48:51], v2, s[16:19], s26 offen
	buffer_load_dwordx2 v[52:53], v2, s[16:19], s26 offen offset:16
	buffer_load_ubyte v54, v3, s[16:19], s26 offen
	s_cbranch_scc1 .Lav0_hi0
	s_bitcmp1_b32 s21, 0
	s_cbranch_scc1 .Lav0_a1_0
	v_pk_fma_f32 v[160:161], v[114:115], s[20:21], v[160:161] op_sel_hi:[1,0,1]
	v_pk_fma_f32 v[162:163], v[116:117], s[20:21], v[162:163] op_sel_hi:[1,0,1]
	v_pk_fma_f32 v[164:165], v[118:119], s[20:21], v[164:165] op_sel_hi:[1,0,1]
	v_pk_fma_f32 v[166:167], v[120:121], s[20:21], v[166:167] op_sel_hi:[1,0,1]
	v_pk_fma_f32 v[168:169], v[122:123], s[20:21], v[168:169] op_sel_hi:[1,0,1]
	v_pk_fma_f32 v[170:171], v[124:125], s[20:21], v[170:171] op_sel_hi:[1,0,1]
	v_pk_fma_f32 v[172:173], v[126:127], s[20:21], v[172:173] op_sel_hi:[1,0,1]
	v_pk_fma_f32 v[174:175], v[128:129], s[20:21], v[174:175] op_sel_hi:[1,0,1]
	v_pk_fma_f32 v[176:177], v[130:131], s[20:21], v[176:177] op_sel_hi:[1,0,1]
	v_pk_fma_f32 v[178:179], v[132:133], s[20:21], v[178:179] op_sel_hi:[1,0,1]
	v_pk_fma_f32 v[180:181], v[134:135], s[20:21], v[180:181] op_sel_hi:[1,0,1]
	v_pk_fma_f32 v[182:183], v[136:137], s[20:21], v[182:183] op_sel_hi:[1,0,1]
	v_pk_fma_f32 v[184:185], v[138:139], s[20:21], v[184:185] op_sel_hi:[1,0,1]
	v_pk_fma_f32 v[186:187], v[140:141], s[20:21], v[186:187] op_sel_hi:[1,0,1]
	v_pk_fma_f32 v[188:189], v[142:143], s[20:21], v[188:189] op_sel_hi:[1,0,1]
	v_pk_fma_f32 v[190:191], v[144:145], s[20:21], v[190:191] op_sel_hi:[1,0,1]
	s_branch .Lav0_ad0
.Lav0_a1_0:
	v_pk_fma_f32 v[4:5], v[114:115], s[20:21], v[4:5] op_sel_hi:[1,0,1]
	v_pk_fma_f32 v[6:7], v[116:117], s[20:21], v[6:7] op_sel_hi:[1,0,1]
	v_pk_fma_f32 v[8:9], v[118:119], s[20:21], v[8:9] op_sel_hi:[1,0,1]
	v_pk_fma_f32 v[10:11], v[120:121], s[20:21], v[10:11] op_sel_hi:[1,0,1]
	v_pk_fma_f32 v[12:13], v[122:123], s[20:21], v[12:13] op_sel_hi:[1,0,1]
	v_pk_fma_f32 v[14:15], v[124:125], s[20:21], v[14:15] op_sel_hi:[1,0,1]
	v_pk_fma_f32 v[16:17], v[126:127], s[20:21], v[16:17] op_sel_hi:[1,0,1]
	v_pk_fma_f32 v[18:19], v[128:129], s[20:21], v[18:19] op_sel_hi:[1,0,1]
	v_pk_fma_f32 v[20:21], v[130:131], s[20:21], v[20:21] op_sel_hi:[1,0,1]
	v_pk_fma_f32 v[22:23], v[132:133], s[20:21], v[22:23] op_sel_hi:[1,0,1]
	v_pk_fma_f32 v[24:25], v[134:135], s[20:21], v[24:25] op_sel_hi:[1,0,1]
	v_pk_fma_f32 v[26:27], v[136:137], s[20:21], v[26:27] op_sel_hi:[1,0,1]
	v_pk_fma_f32 v[28:29], v[138:139], s[20:21], v[28:29] op_sel_hi:[1,0,1]
	v_pk_fma_f32 v[30:31], v[140:141], s[20:21], v[30:31] op_sel_hi:[1,0,1]
	v_pk_fma_f32 v[32:33], v[142:143], s[20:21], v[32:33] op_sel_hi:[1,0,1]
	v_pk_fma_f32 v[34:35], v[144:145], s[20:21], v[34:35] op_sel_hi:[1,0,1]
	s_branch .Lav0_ad0
.Lav0_hi0:
	s_bitcmp1_b32 s21, 0
	s_cbranch_scc1 .Lav0_a3_0
	v_pk_fma_f32 v[192:193], v[114:115], s[20:21], v[192:193] op_sel_hi:[1,0,1]
	v_pk_fma_f32 v[194:195], v[116:117], s[20:21], v[194:195] op_sel_hi:[1,0,1]
	v_pk_fma_f32 v[196:197], v[118:119], s[20:21], v[196:197] op_sel_hi:[1,0,1]
	v_pk_fma_f32 v[198:199], v[120:121], s[20:21], v[198:199] op_sel_hi:[1,0,1]
	v_pk_fma_f32 v[200:201], v[122:123], s[20:21], v[200:201] op_sel_hi:[1,0,1]
	v_pk_fma_f32 v[202:203], v[124:125], s[20:21], v[202:203] op_sel_hi:[1,0,1]
	v_pk_fma_f32 v[204:205], v[126:127], s[20:21], v[204:205] op_sel_hi:[1,0,1]
	v_pk_fma_f32 v[206:207], v[128:129], s[20:21], v[206:207] op_sel_hi:[1,0,1]
	v_pk_fma_f32 v[208:209], v[130:131], s[20:21], v[208:209] op_sel_hi:[1,0,1]
	v_pk_fma_f32 v[210:211], v[132:133], s[20:21], v[210:211] op_sel_hi:[1,0,1]
	v_pk_fma_f32 v[212:213], v[134:135], s[20:21], v[212:213] op_sel_hi:[1,0,1]
	v_pk_fma_f32 v[214:215], v[136:137], s[20:21], v[214:215] op_sel_hi:[1,0,1]
	v_pk_fma_f32 v[216:217], v[138:139], s[20:21], v[216:217] op_sel_hi:[1,0,1]
	v_pk_fma_f32 v[218:219], v[140:141], s[20:21], v[218:219] op_sel_hi:[1,0,1]
	v_pk_fma_f32 v[220:221], v[142:143], s[20:21], v[220:221] op_sel_hi:[1,0,1]
	v_pk_fma_f32 v[222:223], v[144:145], s[20:21], v[222:223] op_sel_hi:[1,0,1]
	s_branch .Lav0_ad0
.Lav0_a3_0:
	v_pk_fma_f32 v[148:149], v[114:115], s[20:21], v[148:149] op_sel_hi:[1,0,1]
	v_pk_fma_f32 v[150:151], v[116:117], s[20:21], v[150:151] op_sel_hi:[1,0,1]
	v_pk_fma_f32 v[152:153], v[118:119], s[20:21], v[152:153] op_sel_hi:[1,0,1]
	v_pk_fma_f32 v[154:155], v[120:121], s[20:21], v[154:155] op_sel_hi:[1,0,1]
	v_pk_fma_f32 v[156:157], v[122:123], s[20:21], v[156:157] op_sel_hi:[1,0,1]
	v_pk_fma_f32 v[158:159], v[124:125], s[20:21], v[158:159] op_sel_hi:[1,0,1]
	v_pk_fma_f32 v[232:233], v[126:127], s[20:21], v[232:233] op_sel_hi:[1,0,1]
	v_pk_fma_f32 v[234:235], v[128:129], s[20:21], v[234:235] op_sel_hi:[1,0,1]
	v_pk_fma_f32 v[236:237], v[130:131], s[20:21], v[236:237] op_sel_hi:[1,0,1]
	v_pk_fma_f32 v[238:239], v[132:133], s[20:21], v[238:239] op_sel_hi:[1,0,1]
	v_pk_fma_f32 v[240:241], v[134:135], s[20:21], v[240:241] op_sel_hi:[1,0,1]
	v_pk_fma_f32 v[242:243], v[136:137], s[20:21], v[242:243] op_sel_hi:[1,0,1]
	v_pk_fma_f32 v[244:245], v[138:139], s[20:21], v[244:245] op_sel_hi:[1,0,1]
	v_pk_fma_f32 v[246:247], v[140:141], s[20:21], v[246:247] op_sel_hi:[1,0,1]
	v_pk_fma_f32 v[248:249], v[142:143], s[20:21], v[248:249] op_sel_hi:[1,0,1]
	v_pk_fma_f32 v[250:251], v[144:145], s[20:21], v[250:251] op_sel_hi:[1,0,1]
.Lav0_ad0:
	s_mov_b32 s20, s1
	s_mov_b32 s21, s59

; #define PB_FENCE asm volatile("" ::: "memory")
; __device__ __forceinline__ void ph_peer_apply(const Params& P, int layer, float* xlat, float* xctx_in, float* xctx_out, int nrows, bool write_next, char* smem, float* xlat_out = nullptr) {
;     ...
;     PB_LOAD(bufA, tv, 0);
;     for (int gq = 0; gq < NG; gq += 2) {
;       PB_LOAD(bufB, tv, gq + 1); PB_FENCE;
;       PB_ACC(bufA, gq);
;       if (gq + 2 < NG) PB_LOAD(bufA, tv, gq + 2);
;       PB_FENCE;
;       PB_ACC(bufB, gq + 1);
;     }
.Lav0_sdl1:
	s_waitcnt vmcnt(21)
	v_lshlrev_b32_e32 v62, 23, v62
	v_cvt_scalef32_pk32_f32_fp6 v[114:145], v[56:61], v62
	s_bitcmp1_b32 s23, 1
	buffer_load_dwordx4 v[56:59], v2, s[16:19], s26 offen
	buffer_load_dwordx2 v[60:61], v2, s[16:19], s26 offen offset:16
	buffer_load_ubyte v62, v3, s[16:19], s26 offen
	s_cbranch_scc1 .Lav0_hi1
	s_bitcmp1_b32 s23, 0
	s_cbranch_scc1 .Lav0_a1_1
	v_pk_fma_f32 v[160:161], v[114:115], s[22:23], v[160:161] op_sel_hi:[1,0,1]
	v_pk_fma_f32 v[162:163], v[116:117], s[22:23], v[162:163] op_sel_hi:[1,0,1]
	v_pk_fma_f32 v[164:165], v[118:119], s[22:23], v[164:165] op_sel_hi:[1,0,1]
	v_pk_fma_f32 v[166:167], v[120:121], s[22:23], v[166:167] op_sel_hi:[1,0,1]
	v_pk_fma_f32 v[168:169], v[122:123], s[22:23], v[168:169] op_sel_hi:[1,0,1]
	v_pk_fma_f32 v[170:171], v[124:125], s[22:23], v[170:171] op_sel_hi:[1,0,1]
	v_pk_fma_f32 v[172:173], v[126:127], s[22:23], v[172:173] op_sel_hi:[1,0,1]
	v_pk_fma_f32 v[174:175], v[128:129], s[22:23], v[174:175] op_sel_hi:[1,0,1]
	v_pk_fma_f32 v[176:177], v[130:131], s[22:23], v[176:177] op_sel_hi:[1,0,1]
	v_pk_fma_f32 v[178:179], v[132:133], s[22:23], v[178:179] op_sel_hi:[1,0,1]
	v_pk_fma_f32 v[180:181], v[134:135], s[22:23], v[180:181] op_sel_hi:[1,0,1]
	v_pk_fma_f32 v[182:183], v[136:137], s[22:23], v[182:183] op_sel_hi:[1,0,1]
	v_pk_fma_f32 v[184:185], v[138:139], s[22:23], v[184:185] op_sel_hi:[1,0,1]
	v_pk_fma_f32 v[186:187], v[140:141], s[22:23], v[186:187] op_sel_hi:[1,0,1]
	v_pk_fma_f32 v[188:189], v[142:143], s[22:23], v[188:189] op_sel_hi:[1,0,1]
	v_pk_fma_f32 v[190:191], v[144:145], s[22:23], v[190:191] op_sel_hi:[1,0,1]
	s_branch .Lav0_ad1
.Lav0_a1_1:
	v_pk_fma_f32 v[4:5], v[114:115], s[22:23], v[4:5] op_sel_hi:[1,0,1]
	v_pk_fma_f32 v[6:7], v[116:117], s[22:23], v[6:7] op_sel_hi:[1,0,1]
	v_pk_fma_f32 v[8:9], v[118:119], s[22:23], v[8:9] op_sel_hi:[1,0,1]
	v_pk_fma_f32 v[10:11], v[120:121], s[22:23], v[10:11] op_sel_hi:[1,0,1]
	v_pk_fma_f32 v[12:13], v[122:123], s[22:23], v[12:13] op_sel_hi:[1,0,1]
	v_pk_fma_f32 v[14:15], v[124:125], s[22:23], v[14:15] op_sel_hi:[1,0,1]
	v_pk_fma_f32 v[16:17], v[126:127], s[22:23], v[16:17] op_sel_hi:[1,0,1]
	v_pk_fma_f32 v[18:19], v[128:129], s[22:23], v[18:19] op_sel_hi:[1,0,1]
	v_pk_fma_f32 v[20:21], v[130:131], s[22:23], v[20:21] op_sel_hi:[1,0,1]
	v_pk_fma_f32 v[22:23], v[132:133], s[22:23], v[22:23] op_sel_hi:[1,0,1]
	v_pk_fma_f32 v[24:25], v[134:135], s[22:23], v[24:25] op_sel_hi:[1,0,1]
	v_pk_fma_f32 v[26:27], v[136:137], s[22:23], v[26:27] op_sel_hi:[1,0,1]
	v_pk_fma_f32 v[28:29], v[138:139], s[22:23], v[28:29] op_sel_hi:[1,0,1]
	v_pk_fma_f32 v[30:31], v[140:141], s[22:23], v[30:31] op_sel_hi:[1,0,1]
	v_pk_fma_f32 v[32:33], v[142:143], s[22:23], v[32:33] op_sel_hi:[1,0,1]
	v_pk_fma_f32 v[34:35], v[144:145], s[22:23], v[34:35] op_sel_hi:[1,0,1]
	s_branch .Lav0_ad1
.Lav0_hi1:
	s_bitcmp1_b32 s23, 0
	s_cbranch_scc1 .Lav0_a3_1
	v_pk_fma_f32 v[192:193], v[114:115], s[22:23], v[192:193] op_sel_hi:[1,0,1]
	v_pk_fma_f32 v[194:195], v[116:117], s[22:23], v[194:195] op_sel_hi:[1,0,1]
	v_pk_fma_f32 v[196:197], v[118:119], s[22:23], v[196:197] op_sel_hi:[1,0,1]
	v_pk_fma_f32 v[198:199], v[120:121], s[22:23], v[198:199] op_sel_hi:[1,0,1]
	v_pk_fma_f32 v[200:201], v[122:123], s[22:23], v[200:201] op_sel_hi:[1,0,1]
	v_pk_fma_f32 v[202:203], v[124:125], s[22:23], v[202:203] op_sel_hi:[1,0,1]
	v_pk_fma_f32 v[204:205], v[126:127], s[22:23], v[204:205] op_sel_hi:[1,0,1]
	v_pk_fma_f32 v[206:207], v[128:129], s[22:23], v[206:207] op_sel_hi:[1,0,1]
	v_pk_fma_f32 v[208:209], v[130:131], s[22:23], v[208:209] op_sel_hi:[1,0,1]
	v_pk_fma_f32 v[210:211], v[132:133], s[22:23], v[210:211] op_sel_hi:[1,0,1]
	v_pk_fma_f32 v[212:213], v[134:135], s[22:23], v[212:213] op_sel_hi:[1,0,1]
	v_pk_fma_f32 v[214:215], v[136:137], s[22:23], v[214:215] op_sel_hi:[1,0,1]
	v_pk_fma_f32 v[216:217], v[138:139], s[22:23], v[216:217] op_sel_hi:[1,0,1]
	v_pk_fma_f32 v[218:219], v[140:141], s[22:23], v[218:219] op_sel_hi:[1,0,1]
	v_pk_fma_f32 v[220:221], v[142:143], s[22:23], v[220:221] op_sel_hi:[1,0,1]
	v_pk_fma_f32 v[222:223], v[144:145], s[22:23], v[222:223] op_sel_hi:[1,0,1]
	s_branch .Lav0_ad1
.Lav0_a3_1:
	v_pk_fma_f32 v[148:149], v[114:115], s[22:23], v[148:149] op_sel_hi:[1,0,1]
	v_pk_fma_f32 v[150:151], v[116:117], s[22:23], v[150:151] op_sel_hi:[1,0,1]
	v_pk_fma_f32 v[152:153], v[118:119], s[22:23], v[152:153] op_sel_hi:[1,0,1]
	v_pk_fma_f32 v[154:155], v[120:121], s[22:23], v[154:155] op_sel_hi:[1,0,1]
	v_pk_fma_f32 v[156:157], v[122:123], s[22:23], v[156:157] op_sel_hi:[1,0,1]
	v_pk_fma_f32 v[158:159], v[124:125], s[22:23], v[158:159] op_sel_hi:[1,0,1]
	v_pk_fma_f32 v[232:233], v[126:127], s[22:23], v[232:233] op_sel_hi:[1,0,1]
	v_pk_fma_f32 v[234:235], v[128:129], s[22:23], v[234:235] op_sel_hi:[1,0,1]
	v_pk_fma_f32 v[236:237], v[130:131], s[22:23], v[236:237] op_sel_hi:[1,0,1]
	v_pk_fma_f32 v[238:239], v[132:133], s[22:23], v[238:239] op_sel_hi:[1,0,1]
	v_pk_fma_f32 v[240:241], v[134:135], s[22:23], v[240:241] op_sel_hi:[1,0,1]
	v_pk_fma_f32 v[242:243], v[136:137], s[22:23], v[242:243] op_sel_hi:[1,0,1]
	v_pk_fma_f32 v[244:245], v[138:139], s[22:23], v[244:245] op_sel_hi:[1,0,1]
	v_pk_fma_f32 v[246:247], v[140:141], s[22:23], v[246:247] op_sel_hi:[1,0,1]
	v_pk_fma_f32 v[248:249], v[142:143], s[22:23], v[248:249] op_sel_hi:[1,0,1]
	v_pk_fma_f32 v[250:251], v[144:145], s[22:23], v[250:251] op_sel_hi:[1,0,1]
.Lav0_ad1:
	s_mov_b32 s22, s1
	s_mov_b32 s23, s59

; #define PB_FENCE asm volatile("" ::: "memory")
; __device__ __forceinline__ void ph_peer_apply(const Params& P, int layer, float* xlat, float* xctx_in, float* xctx_out, int nrows, bool write_next, char* smem, float* xlat_out = nullptr) {
;     ...
;     PB_LOAD(bufA, tv, 0);
;     for (int gq = 0; gq < NG; gq += 2) {
;       PB_LOAD(bufB, tv, gq + 1); PB_FENCE;
;       PB_ACC(bufA, gq);
;       if (gq + 2 < NG) PB_LOAD(bufA, tv, gq + 2);
;       PB_FENCE;
;       PB_ACC(bufB, gq + 1);
;     }
.Lav0_sdl2:
	s_waitcnt vmcnt(21)
	v_lshlrev_b32_e32 v70, 23, v70
	v_cvt_scalef32_pk32_f32_fp6 v[114:145], v[64:69], v70
	s_bitcmp1_b32 s25, 1
	buffer_load_dwordx4 v[64:67], v2, s[16:19], s26 offen
	buffer_load_dwordx2 v[68:69], v2, s[16:19], s26 offen offset:16
	buffer_load_ubyte v70, v3, s[16:19], s26 offen
	s_cbranch_scc1 .Lav0_hi2
	s_bitcmp1_b32 s25, 0
	s_cbranch_scc1 .Lav0_a1_2
	v_pk_fma_f32 v[160:161], v[114:115], s[24:25], v[160:161] op_sel_hi:[1,0,1]
	v_pk_fma_f32 v[162:163], v[116:117], s[24:25], v[162:163] op_sel_hi:[1,0,1]
	v_pk_fma_f32 v[164:165], v[118:119], s[24:25], v[164:165] op_sel_hi:[1,0,1]
	v_pk_fma_f32 v[166:167], v[120:121], s[24:25], v[166:167] op_sel_hi:[1,0,1]
	v_pk_fma_f32 v[168:169], v[122:123], s[24:25], v[168:169] op_sel_hi:[1,0,1]
	v_pk_fma_f32 v[170:171], v[124:125], s[24:25], v[170:171] op_sel_hi:[1,0,1]
	v_pk_fma_f32 v[172:173], v[126:127], s[24:25], v[172:173] op_sel_hi:[1,0,1]
	v_pk_fma_f32 v[174:175], v[128:129], s[24:25], v[174:175] op_sel_hi:[1,0,1]
	v_pk_fma_f32 v[176:177], v[130:131], s[24:25], v[176:177] op_sel_hi:[1,0,1]
	v_pk_fma_f32 v[178:179], v[132:133], s[24:25], v[178:179] op_sel_hi:[1,0,1]
	v_pk_fma_f32 v[180:181], v[134:135], s[24:25], v[180:181] op_sel_hi:[1,0,1]
	v_pk_fma_f32 v[182:183], v[136:137], s[24:25], v[182:183] op_sel_hi:[1,0,1]
	v_pk_fma_f32 v[184:185], v[138:139], s[24:25], v[184:185] op_sel_hi:[1,0,1]
	v_pk_fma_f32 v[186:187], v[140:141], s[24:25], v[186:187] op_sel_hi:[1,0,1]
	v_pk_fma_f32 v[188:189], v[142:143], s[24:25], v[188:189] op_sel_hi:[1,0,1]
	v_pk_fma_f32 v[190:191], v[144:145], s[24:25], v[190:191] op_sel_hi:[1,0,1]
	s_branch .Lav0_ad2
.Lav0_a1_2:
	v_pk_fma_f32 v[4:5], v[114:115], s[24:25], v[4:5] op_sel_hi:[1,0,1]
	v_pk_fma_f32 v[6:7], v[116:117], s[24:25], v[6:7] op_sel_hi:[1,0,1]
	v_pk_fma_f32 v[8:9], v[118:119], s[24:25], v[8:9] op_sel_hi:[1,0,1]
	v_pk_fma_f32 v[10:11], v[120:121], s[24:25], v[10:11] op_sel_hi:[1,0,1]
	v_pk_fma_f32 v[12:13], v[122:123], s[24:25], v[12:13] op_sel_hi:[1,0,1]
	v_pk_fma_f32 v[14:15], v[124:125], s[24:25], v[14:15] op_sel_hi:[1,0,1]
	v_pk_fma_f32 v[16:17], v[126:127], s[24:25], v[16:17] op_sel_hi:[1,0,1]
	v_pk_fma_f32 v[18:19], v[128:129], s[24:25], v[18:19] op_sel_hi:[1,0,1]
	v_pk_fma_f32 v[20:21], v[130:131], s[24:25], v[20:21] op_sel_hi:[1,0,1]
	v_pk_fma_f32 v[22:23], v[132:133], s[24:25], v[22:23] op_sel_hi:[1,0,1]
	v_pk_fma_f32 v[24:25], v[134:135], s[24:25], v[24:25] op_sel_hi:[1,0,1]
	v_pk_fma_f32 v[26:27], v[136:137], s[24:25], v[26:27] op_sel_hi:[1,0,1]
	v_pk_fma_f32 v[28:29], v[138:139], s[24:25], v[28:29] op_sel_hi:[1,0,1]
	v_pk_fma_f32 v[30:31], v[140:141], s[24:25], v[30:31] op_sel_hi:[1,0,1]
	v_pk_fma_f32 v[32:33], v[142:143], s[24:25], v[32:33] op_sel_hi:[1,0,1]
	v_pk_fma_f32 v[34:35], v[144:145], s[24:25], v[34:35] op_sel_hi:[1,0,1]
	s_branch .Lav0_ad2
.Lav0_hi2:
	s_bitcmp1_b32 s25, 0
	s_cbranch_scc1 .Lav0_a3_2
	v_pk_fma_f32 v[192:193], v[114:115], s[24:25], v[192:193] op_sel_hi:[1,0,1]
	v_pk_fma_f32 v[194:195], v[116:117], s[24:25], v[194:195] op_sel_hi:[1,0,1]
	v_pk_fma_f32 v[196:197], v[118:119], s[24:25], v[196:197] op_sel_hi:[1,0,1]
	v_pk_fma_f32 v[198:199], v[120:121], s[24:25], v[198:199] op_sel_hi:[1,0,1]
	v_pk_fma_f32 v[200:201], v[122:123], s[24:25], v[200:201] op_sel_hi:[1,0,1]
	v_pk_fma_f32 v[202:203], v[124:125], s[24:25], v[202:203] op_sel_hi:[1,0,1]
	v_pk_fma_f32 v[204:205], v[126:127], s[24:25], v[204:205] op_sel_hi:[1,0,1]
	v_pk_fma_f32 v[206:207], v[128:129], s[24:25], v[206:207] op_sel_hi:[1,0,1]
	v_pk_fma_f32 v[208:209], v[130:131], s[24:25], v[208:209] op_sel_hi:[1,0,1]
	v_pk_fma_f32 v[210:211], v[132:133], s[24:25], v[210:211] op_sel_hi:[1,0,1]
	v_pk_fma_f32 v[212:213], v[134:135], s[24:25], v[212:213] op_sel_hi:[1,0,1]
	v_pk_fma_f32 v[214:215], v[136:137], s[24:25], v[214:215] op_sel_hi:[1,0,1]
	v_pk_fma_f32 v[216:217], v[138:139], s[24:25], v[216:217] op_sel_hi:[1,0,1]
	v_pk_fma_f32 v[218:219], v[140:141], s[24:25], v[218:219] op_sel_hi:[1,0,1]
	v_pk_fma_f32 v[220:221], v[142:143], s[24:25], v[220:221] op_sel_hi:[1,0,1]
	v_pk_fma_f32 v[222:223], v[144:145], s[24:25], v[222:223] op_sel_hi:[1,0,1]
	s_branch .Lav0_ad2
.Lav0_a3_2:
	v_pk_fma_f32 v[148:149], v[114:115], s[24:25], v[148:149] op_sel_hi:[1,0,1]
	v_pk_fma_f32 v[150:151], v[116:117], s[24:25], v[150:151] op_sel_hi:[1,0,1]
	v_pk_fma_f32 v[152:153], v[118:119], s[24:25], v[152:153] op_sel_hi:[1,0,1]
	v_pk_fma_f32 v[154:155], v[120:121], s[24:25], v[154:155] op_sel_hi:[1,0,1]
	v_pk_fma_f32 v[156:157], v[122:123], s[24:25], v[156:157] op_sel_hi:[1,0,1]
	v_pk_fma_f32 v[158:159], v[124:125], s[24:25], v[158:159] op_sel_hi:[1,0,1]
	v_pk_fma_f32 v[232:233], v[126:127], s[24:25], v[232:233] op_sel_hi:[1,0,1]
	v_pk_fma_f32 v[234:235], v[128:129], s[24:25], v[234:235] op_sel_hi:[1,0,1]
	v_pk_fma_f32 v[236:237], v[130:131], s[24:25], v[236:237] op_sel_hi:[1,0,1]
	v_pk_fma_f32 v[238:239], v[132:133], s[24:25], v[238:239] op_sel_hi:[1,0,1]
	v_pk_fma_f32 v[240:241], v[134:135], s[24:25], v[240:241] op_sel_hi:[1,0,1]
	v_pk_fma_f32 v[242:243], v[136:137], s[24:25], v[242:243] op_sel_hi:[1,0,1]
	v_pk_fma_f32 v[244:245], v[138:139], s[24:25], v[244:245] op_sel_hi:[1,0,1]
	v_pk_fma_f32 v[246:247], v[140:141], s[24:25], v[246:247] op_sel_hi:[1,0,1]
	v_pk_fma_f32 v[248:249], v[142:143], s[24:25], v[248:249] op_sel_hi:[1,0,1]
	v_pk_fma_f32 v[250:251], v[144:145], s[24:25], v[250:251] op_sel_hi:[1,0,1]
.Lav0_ad2:
	s_mov_b32 s24, s1
	s_mov_b32 s25, s59

; #define PB_FENCE asm volatile("" ::: "memory")
; __device__ __forceinline__ void ph_peer_apply(const Params& P, int layer, float* xlat, float* xctx_in, float* xctx_out, int nrows, bool write_next, char* smem, float* xlat_out = nullptr) {
;     ...
;     PB_LOAD(bufA, tv, 0);
;     for (int gq = 0; gq < NG; gq += 2) {
;       PB_LOAD(bufB, tv, gq + 1); PB_FENCE;
;       PB_ACC(bufA, gq);
;       if (gq + 2 < NG) PB_LOAD(bufA, tv, gq + 2);
;       PB_FENCE;
;       PB_ACC(bufB, gq + 1);
;     }
.Lav0_sdl3:
	s_waitcnt vmcnt(21)
	v_lshlrev_b32_e32 v78, 23, v78
	v_cvt_scalef32_pk32_f32_fp6 v[114:145], v[72:77], v78
	s_bitcmp1_b32 s31, 1
	buffer_load_dwordx4 v[72:75], v2, s[16:19], s26 offen
	buffer_load_dwordx2 v[76:77], v2, s[16:19], s26 offen offset:16
	buffer_load_ubyte v78, v3, s[16:19], s26 offen
	s_cbranch_scc1 .Lav0_hi3
	s_bitcmp1_b32 s31, 0
	s_cbranch_scc1 .Lav0_a1_3
	v_pk_fma_f32 v[160:161], v[114:115], s[30:31], v[160:161] op_sel_hi:[1,0,1]
	v_pk_fma_f32 v[162:163], v[116:117], s[30:31], v[162:163] op_sel_hi:[1,0,1]
	v_pk_fma_f32 v[164:165], v[118:119], s[30:31], v[164:165] op_sel_hi:[1,0,1]
	v_pk_fma_f32 v[166:167], v[120:121], s[30:31], v[166:167] op_sel_hi:[1,0,1]
	v_pk_fma_f32 v[168:169], v[122:123], s[30:31], v[168:169] op_sel_hi:[1,0,1]
	v_pk_fma_f32 v[170:171], v[124:125], s[30:31], v[170:171] op_sel_hi:[1,0,1]
	v_pk_fma_f32 v[172:173], v[126:127], s[30:31], v[172:173] op_sel_hi:[1,0,1]
	v_pk_fma_f32 v[174:175], v[128:129], s[30:31], v[174:175] op_sel_hi:[1,0,1]
	v_pk_fma_f32 v[176:177], v[130:131], s[30:31], v[176:177] op_sel_hi:[1,0,1]
	v_pk_fma_f32 v[178:179], v[132:133], s[30:31], v[178:179] op_sel_hi:[1,0,1]
	v_pk_fma_f32 v[180:181], v[134:135], s[30:31], v[180:181] op_sel_hi:[1,0,1]
	v_pk_fma_f32 v[182:183], v[136:137], s[30:31], v[182:183] op_sel_hi:[1,0,1]
	v_pk_fma_f32 v[184:185], v[138:139], s[30:31], v[184:185] op_sel_hi:[1,0,1]
	v_pk_fma_f32 v[186:187], v[140:141], s[30:31], v[186:187] op_sel_hi:[1,0,1]
	v_pk_fma_f32 v[188:189], v[142:143], s[30:31], v[188:189] op_sel_hi:[1,0,1]
	v_pk_fma_f32 v[190:191], v[144:145], s[30:31], v[190:191] op_sel_hi:[1,0,1]
	s_branch .Lav0_ad3
.Lav0_a1_3:
	v_pk_fma_f32 v[4:5], v[114:115], s[30:31], v[4:5] op_sel_hi:[1,0,1]
	v_pk_fma_f32 v[6:7], v[116:117], s[30:31], v[6:7] op_sel_hi:[1,0,1]
	v_pk_fma_f32 v[8:9], v[118:119], s[30:31], v[8:9] op_sel_hi:[1,0,1]
	v_pk_fma_f32 v[10:11], v[120:121], s[30:31], v[10:11] op_sel_hi:[1,0,1]
	v_pk_fma_f32 v[12:13], v[122:123], s[30:31], v[12:13] op_sel_hi:[1,0,1]
	v_pk_fma_f32 v[14:15], v[124:125], s[30:31], v[14:15] op_sel_hi:[1,0,1]
	v_pk_fma_f32 v[16:17], v[126:127], s[30:31], v[16:17] op_sel_hi:[1,0,1]
	v_pk_fma_f32 v[18:19], v[128:129], s[30:31], v[18:19] op_sel_hi:[1,0,1]
	v_pk_fma_f32 v[20:21], v[130:131], s[30:31], v[20:21] op_sel_hi:[1,0,1]
	v_pk_fma_f32 v[22:23], v[132:133], s[30:31], v[22:23] op_sel_hi:[1,0,1]
	v_pk_fma_f32 v[24:25], v[134:135], s[30:31], v[24:25] op_sel_hi:[1,0,1]
	v_pk_fma_f32 v[26:27], v[136:137], s[30:31], v[26:27] op_sel_hi:[1,0,1]
	v_pk_fma_f32 v[28:29], v[138:139], s[30:31], v[28:29] op_sel_hi:[1,0,1]
	v_pk_fma_f32 v[30:31], v[140:141], s[30:31], v[30:31] op_sel_hi:[1,0,1]
	v_pk_fma_f32 v[32:33], v[142:143], s[30:31], v[32:33] op_sel_hi:[1,0,1]
	v_pk_fma_f32 v[34:35], v[144:145], s[30:31], v[34:35] op_sel_hi:[1,0,1]
	s_branch .Lav0_ad3
.Lav0_hi3:
	s_bitcmp1_b32 s31, 0
	s_cbranch_scc1 .Lav0_a3_3
	v_pk_fma_f32 v[192:193], v[114:115], s[30:31], v[192:193] op_sel_hi:[1,0,1]
	v_pk_fma_f32 v[194:195], v[116:117], s[30:31], v[194:195] op_sel_hi:[1,0,1]
	v_pk_fma_f32 v[196:197], v[118:119], s[30:31], v[196:197] op_sel_hi:[1,0,1]
	v_pk_fma_f32 v[198:199], v[120:121], s[30:31], v[198:199] op_sel_hi:[1,0,1]
	v_pk_fma_f32 v[200:201], v[122:123], s[30:31], v[200:201] op_sel_hi:[1,0,1]
	v_pk_fma_f32 v[202:203], v[124:125], s[30:31], v[202:203] op_sel_hi:[1,0,1]
	v_pk_fma_f32 v[204:205], v[126:127], s[30:31], v[204:205] op_sel_hi:[1,0,1]
	v_pk_fma_f32 v[206:207], v[128:129], s[30:31], v[206:207] op_sel_hi:[1,0,1]
	v_pk_fma_f32 v[208:209], v[130:131], s[30:31], v[208:209] op_sel_hi:[1,0,1]
	v_pk_fma_f32 v[210:211], v[132:133], s[30:31], v[210:211] op_sel_hi:[1,0,1]
	v_pk_fma_f32 v[212:213], v[134:135], s[30:31], v[212:213] op_sel_hi:[1,0,1]
	v_pk_fma_f32 v[214:215], v[136:137], s[30:31], v[214:215] op_sel_hi:[1,0,1]
	v_pk_fma_f32 v[216:217], v[138:139], s[30:31], v[216:217] op_sel_hi:[1,0,1]
	v_pk_fma_f32 v[218:219], v[140:141], s[30:31], v[218:219] op_sel_hi:[1,0,1]
	v_pk_fma_f32 v[220:221], v[142:143], s[30:31], v[220:221] op_sel_hi:[1,0,1]
	v_pk_fma_f32 v[222:223], v[144:145], s[30:31], v[222:223] op_sel_hi:[1,0,1]
	s_branch .Lav0_ad3
.Lav0_a3_3:
	v_pk_fma_f32 v[148:149], v[114:115], s[30:31], v[148:149] op_sel_hi:[1,0,1]
	v_pk_fma_f32 v[150:151], v[116:117], s[30:31], v[150:151] op_sel_hi:[1,0,1]
	v_pk_fma_f32 v[152:153], v[118:119], s[30:31], v[152:153] op_sel_hi:[1,0,1]
	v_pk_fma_f32 v[154:155], v[120:121], s[30:31], v[154:155] op_sel_hi:[1,0,1]
	v_pk_fma_f32 v[156:157], v[122:123], s[30:31], v[156:157] op_sel_hi:[1,0,1]
	v_pk_fma_f32 v[158:159], v[124:125], s[30:31], v[158:159] op_sel_hi:[1,0,1]
	v_pk_fma_f32 v[232:233], v[126:127], s[30:31], v[232:233] op_sel_hi:[1,0,1]
	v_pk_fma_f32 v[234:235], v[128:129], s[30:31], v[234:235] op_sel_hi:[1,0,1]
	v_pk_fma_f32 v[236:237], v[130:131], s[30:31], v[236:237] op_sel_hi:[1,0,1]
	v_pk_fma_f32 v[238:239], v[132:133], s[30:31], v[238:239] op_sel_hi:[1,0,1]
	v_pk_fma_f32 v[240:241], v[134:135], s[30:31], v[240:241] op_sel_hi:[1,0,1]
	v_pk_fma_f32 v[242:243], v[136:137], s[30:31], v[242:243] op_sel_hi:[1,0,1]
	v_pk_fma_f32 v[244:245], v[138:139], s[30:31], v[244:245] op_sel_hi:[1,0,1]
	v_pk_fma_f32 v[246:247], v[140:141], s[30:31], v[246:247] op_sel_hi:[1,0,1]
	v_pk_fma_f32 v[248:249], v[142:143], s[30:31], v[248:249] op_sel_hi:[1,0,1]
	v_pk_fma_f32 v[250:251], v[144:145], s[30:31], v[250:251] op_sel_hi:[1,0,1]
.Lav0_ad3:
	s_mov_b32 s30, s1
	s_mov_b32 s31, s59

; #define PB_FENCE asm volatile("" ::: "memory")
; __device__ __forceinline__ void ph_peer_apply(const Params& P, int layer, float* xlat, float* xctx_in, float* xctx_out, int nrows, bool write_next, char* smem, float* xlat_out = nullptr) {
;     ...
;     PB_LOAD(bufA, tv, 0);
;     for (int gq = 0; gq < NG; gq += 2) {
;       PB_LOAD(bufB, tv, gq + 1); PB_FENCE;
;       PB_ACC(bufA, gq);
;       if (gq + 2 < NG) PB_LOAD(bufA, tv, gq + 2);
;       PB_FENCE;
;       PB_ACC(bufB, gq + 1);
;     }
.Lav0_sdl4:
	s_waitcnt vmcnt(21)
	v_lshlrev_b32_e32 v86, 23, v86
	v_cvt_scalef32_pk32_f32_fp6 v[114:145], v[80:85], v86
	s_bitcmp1_b32 s37, 1
	buffer_load_dwordx4 v[80:83], v2, s[16:19], s26 offen
	buffer_load_dwordx2 v[84:85], v2, s[16:19], s26 offen offset:16
	buffer_load_ubyte v86, v3, s[16:19], s26 offen
	s_cbranch_scc1 .Lav0_hi4
	s_bitcmp1_b32 s37, 0
	s_cbranch_scc1 .Lav0_a1_4
	v_pk_fma_f32 v[160:161], v[114:115], s[36:37], v[160:161] op_sel_hi:[1,0,1]
	v_pk_fma_f32 v[162:163], v[116:117], s[36:37], v[162:163] op_sel_hi:[1,0,1]
	v_pk_fma_f32 v[164:165], v[118:119], s[36:37], v[164:165] op_sel_hi:[1,0,1]
	v_pk_fma_f32 v[166:167], v[120:121], s[36:37], v[166:167] op_sel_hi:[1,0,1]
	v_pk_fma_f32 v[168:169], v[122:123], s[36:37], v[168:169] op_sel_hi:[1,0,1]
	v_pk_fma_f32 v[170:171], v[124:125], s[36:37], v[170:171] op_sel_hi:[1,0,1]
	v_pk_fma_f32 v[172:173], v[126:127], s[36:37], v[172:173] op_sel_hi:[1,0,1]
	v_pk_fma_f32 v[174:175], v[128:129], s[36:37], v[174:175] op_sel_hi:[1,0,1]
	v_pk_fma_f32 v[176:177], v[130:131], s[36:37], v[176:177] op_sel_hi:[1,0,1]
	v_pk_fma_f32 v[178:179], v[132:133], s[36:37], v[178:179] op_sel_hi:[1,0,1]
	v_pk_fma_f32 v[180:181], v[134:135], s[36:37], v[180:181] op_sel_hi:[1,0,1]
	v_pk_fma_f32 v[182:183], v[136:137], s[36:37], v[182:183] op_sel_hi:[1,0,1]
	v_pk_fma_f32 v[184:185], v[138:139], s[36:37], v[184:185] op_sel_hi:[1,0,1]
	v_pk_fma_f32 v[186:187], v[140:141], s[36:37], v[186:187] op_sel_hi:[1,0,1]
	v_pk_fma_f32 v[188:189], v[142:143], s[36:37], v[188:189] op_sel_hi:[1,0,1]
	v_pk_fma_f32 v[190:191], v[144:145], s[36:37], v[190:191] op_sel_hi:[1,0,1]
	s_branch .Lav0_ad4
.Lav0_a1_4:
	v_pk_fma_f32 v[4:5], v[114:115], s[36:37], v[4:5] op_sel_hi:[1,0,1]
	v_pk_fma_f32 v[6:7], v[116:117], s[36:37], v[6:7] op_sel_hi:[1,0,1]
	v_pk_fma_f32 v[8:9], v[118:119], s[36:37], v[8:9] op_sel_hi:[1,0,1]
	v_pk_fma_f32 v[10:11], v[120:121], s[36:37], v[10:11] op_sel_hi:[1,0,1]
	v_pk_fma_f32 v[12:13], v[122:123], s[36:37], v[12:13] op_sel_hi:[1,0,1]
	v_pk_fma_f32 v[14:15], v[124:125], s[36:37], v[14:15] op_sel_hi:[1,0,1]
	v_pk_fma_f32 v[16:17], v[126:127], s[36:37], v[16:17] op_sel_hi:[1,0,1]
	v_pk_fma_f32 v[18:19], v[128:129], s[36:37], v[18:19] op_sel_hi:[1,0,1]
	v_pk_fma_f32 v[20:21], v[130:131], s[36:37], v[20:21] op_sel_hi:[1,0,1]
	v_pk_fma_f32 v[22:23], v[132:133], s[36:37], v[22:23] op_sel_hi:[1,0,1]
	v_pk_fma_f32 v[24:25], v[134:135], s[36:37], v[24:25] op_sel_hi:[1,0,1]
	v_pk_fma_f32 v[26:27], v[136:137], s[36:37], v[26:27] op_sel_hi:[1,0,1]
	v_pk_fma_f32 v[28:29], v[138:139], s[36:37], v[28:29] op_sel_hi:[1,0,1]
	v_pk_fma_f32 v[30:31], v[140:141], s[36:37], v[30:31] op_sel_hi:[1,0,1]
	v_pk_fma_f32 v[32:33], v[142:143], s[36:37], v[32:33] op_sel_hi:[1,0,1]
	v_pk_fma_f32 v[34:35], v[144:145], s[36:37], v[34:35] op_sel_hi:[1,0,1]
	s_branch .Lav0_ad4
.Lav0_hi4:
	s_bitcmp1_b32 s37, 0
	s_cbranch_scc1 .Lav0_a3_4
	v_pk_fma_f32 v[192:193], v[114:115], s[36:37], v[192:193] op_sel_hi:[1,0,1]
	v_pk_fma_f32 v[194:195], v[116:117], s[36:37], v[194:195] op_sel_hi:[1,0,1]
	v_pk_fma_f32 v[196:197], v[118:119], s[36:37], v[196:197] op_sel_hi:[1,0,1]
	v_pk_fma_f32 v[198:199], v[120:121], s[36:37], v[198:199] op_sel_hi:[1,0,1]
	v_pk_fma_f32 v[200:201], v[122:123], s[36:37], v[200:201] op_sel_hi:[1,0,1]
	v_pk_fma_f32 v[202:203], v[124:125], s[36:37], v[202:203] op_sel_hi:[1,0,1]
	v_pk_fma_f32 v[204:205], v[126:127], s[36:37], v[204:205] op_sel_hi:[1,0,1]
	v_pk_fma_f32 v[206:207], v[128:129], s[36:37], v[206:207] op_sel_hi:[1,0,1]
	v_pk_fma_f32 v[208:209], v[130:131], s[36:37], v[208:209] op_sel_hi:[1,0,1]
	v_pk_fma_f32 v[210:211], v[132:133], s[36:37], v[210:211] op_sel_hi:[1,0,1]
	v_pk_fma_f32 v[212:213], v[134:135], s[36:37], v[212:213] op_sel_hi:[1,0,1]
	v_pk_fma_f32 v[214:215], v[136:137], s[36:37], v[214:215] op_sel_hi:[1,0,1]
	v_pk_fma_f32 v[216:217], v[138:139], s[36:37], v[216:217] op_sel_hi:[1,0,1]
	v_pk_fma_f32 v[218:219], v[140:141], s[36:37], v[218:219] op_sel_hi:[1,0,1]
	v_pk_fma_f32 v[220:221], v[142:143], s[36:37], v[220:221] op_sel_hi:[1,0,1]
	v_pk_fma_f32 v[222:223], v[144:145], s[36:37], v[222:223] op_sel_hi:[1,0,1]
	s_branch .Lav0_ad4
.Lav0_a3_4:
	v_pk_fma_f32 v[148:149], v[114:115], s[36:37], v[148:149] op_sel_hi:[1,0,1]
	v_pk_fma_f32 v[150:151], v[116:117], s[36:37], v[150:151] op_sel_hi:[1,0,1]
	v_pk_fma_f32 v[152:153], v[118:119], s[36:37], v[152:153] op_sel_hi:[1,0,1]
	v_pk_fma_f32 v[154:155], v[120:121], s[36:37], v[154:155] op_sel_hi:[1,0,1]
	v_pk_fma_f32 v[156:157], v[122:123], s[36:37], v[156:157] op_sel_hi:[1,0,1]
	v_pk_fma_f32 v[158:159], v[124:125], s[36:37], v[158:159] op_sel_hi:[1,0,1]
	v_pk_fma_f32 v[232:233], v[126:127], s[36:37], v[232:233] op_sel_hi:[1,0,1]
	v_pk_fma_f32 v[234:235], v[128:129], s[36:37], v[234:235] op_sel_hi:[1,0,1]
	v_pk_fma_f32 v[236:237], v[130:131], s[36:37], v[236:237] op_sel_hi:[1,0,1]
	v_pk_fma_f32 v[238:239], v[132:133], s[36:37], v[238:239] op_sel_hi:[1,0,1]
	v_pk_fma_f32 v[240:241], v[134:135], s[36:37], v[240:241] op_sel_hi:[1,0,1]
	v_pk_fma_f32 v[242:243], v[136:137], s[36:37], v[242:243] op_sel_hi:[1,0,1]
	v_pk_fma_f32 v[244:245], v[138:139], s[36:37], v[244:245] op_sel_hi:[1,0,1]
	v_pk_fma_f32 v[246:247], v[140:141], s[36:37], v[246:247] op_sel_hi:[1,0,1]
	v_pk_fma_f32 v[248:249], v[142:143], s[36:37], v[248:249] op_sel_hi:[1,0,1]
	v_pk_fma_f32 v[250:251], v[144:145], s[36:37], v[250:251] op_sel_hi:[1,0,1]
.Lav0_ad4:
	s_mov_b32 s36, s1
	s_mov_b32 s37, s59

; #define PB_FENCE asm volatile("" ::: "memory")
; __device__ __forceinline__ void ph_peer_apply(const Params& P, int layer, float* xlat, float* xctx_in, float* xctx_out, int nrows, bool write_next, char* smem, float* xlat_out = nullptr) {
;     ...
;     PB_LOAD(bufA, tv, 0);
;     for (int gq = 0; gq < NG; gq += 2) {
;       PB_LOAD(bufB, tv, gq + 1); PB_FENCE;
;       PB_ACC(bufA, gq);
;       if (gq + 2 < NG) PB_LOAD(bufA, tv, gq + 2);
;       PB_FENCE;
;       PB_ACC(bufB, gq + 1);
;     }
.Lav0_sdl5:
	s_waitcnt vmcnt(21)
	v_lshlrev_b32_e32 v94, 23, v94
	v_cvt_scalef32_pk32_f32_fp6 v[114:145], v[88:93], v94
	s_bitcmp1_b32 s39, 1
	buffer_load_dwordx4 v[88:91], v2, s[16:19], s26 offen
	buffer_load_dwordx2 v[92:93], v2, s[16:19], s26 offen offset:16
	buffer_load_ubyte v94, v3, s[16:19], s26 offen
	s_cbranch_scc1 .Lav0_hi5
	s_bitcmp1_b32 s39, 0
	s_cbranch_scc1 .Lav0_a1_5
	v_pk_fma_f32 v[160:161], v[114:115], s[38:39], v[160:161] op_sel_hi:[1,0,1]
	v_pk_fma_f32 v[162:163], v[116:117], s[38:39], v[162:163] op_sel_hi:[1,0,1]
	v_pk_fma_f32 v[164:165], v[118:119], s[38:39], v[164:165] op_sel_hi:[1,0,1]
	v_pk_fma_f32 v[166:167], v[120:121], s[38:39], v[166:167] op_sel_hi:[1,0,1]
	v_pk_fma_f32 v[168:169], v[122:123], s[38:39], v[168:169] op_sel_hi:[1,0,1]
	v_pk_fma_f32 v[170:171], v[124:125], s[38:39], v[170:171] op_sel_hi:[1,0,1]
	v_pk_fma_f32 v[172:173], v[126:127], s[38:39], v[172:173] op_sel_hi:[1,0,1]
	v_pk_fma_f32 v[174:175], v[128:129], s[38:39], v[174:175] op_sel_hi:[1,0,1]
	v_pk_fma_f32 v[176:177], v[130:131], s[38:39], v[176:177] op_sel_hi:[1,0,1]
	v_pk_fma_f32 v[178:179], v[132:133], s[38:39], v[178:179] op_sel_hi:[1,0,1]
	v_pk_fma_f32 v[180:181], v[134:135], s[38:39], v[180:181] op_sel_hi:[1,0,1]
	v_pk_fma_f32 v[182:183], v[136:137], s[38:39], v[182:183] op_sel_hi:[1,0,1]
	v_pk_fma_f32 v[184:185], v[138:139], s[38:39], v[184:185] op_sel_hi:[1,0,1]
	v_pk_fma_f32 v[186:187], v[140:141], s[38:39], v[186:187] op_sel_hi:[1,0,1]
	v_pk_fma_f32 v[188:189], v[142:143], s[38:39], v[188:189] op_sel_hi:[1,0,1]
	v_pk_fma_f32 v[190:191], v[144:145], s[38:39], v[190:191] op_sel_hi:[1,0,1]
	s_branch .Lav0_ad5
.Lav0_a1_5:
	v_pk_fma_f32 v[4:5], v[114:115], s[38:39], v[4:5] op_sel_hi:[1,0,1]
	v_pk_fma_f32 v[6:7], v[116:117], s[38:39], v[6:7] op_sel_hi:[1,0,1]
	v_pk_fma_f32 v[8:9], v[118:119], s[38:39], v[8:9] op_sel_hi:[1,0,1]
	v_pk_fma_f32 v[10:11], v[120:121], s[38:39], v[10:11] op_sel_hi:[1,0,1]
	v_pk_fma_f32 v[12:13], v[122:123], s[38:39], v[12:13] op_sel_hi:[1,0,1]
	v_pk_fma_f32 v[14:15], v[124:125], s[38:39], v[14:15] op_sel_hi:[1,0,1]
	v_pk_fma_f32 v[16:17], v[126:127], s[38:39], v[16:17] op_sel_hi:[1,0,1]
	v_pk_fma_f32 v[18:19], v[128:129], s[38:39], v[18:19] op_sel_hi:[1,0,1]
	v_pk_fma_f32 v[20:21], v[130:131], s[38:39], v[20:21] op_sel_hi:[1,0,1]
	v_pk_fma_f32 v[22:23], v[132:133], s[38:39], v[22:23] op_sel_hi:[1,0,1]
	v_pk_fma_f32 v[24:25], v[134:135], s[38:39], v[24:25] op_sel_hi:[1,0,1]
	v_pk_fma_f32 v[26:27], v[136:137], s[38:39], v[26:27] op_sel_hi:[1,0,1]
	v_pk_fma_f32 v[28:29], v[138:139], s[38:39], v[28:29] op_sel_hi:[1,0,1]
	v_pk_fma_f32 v[30:31], v[140:141], s[38:39], v[30:31] op_sel_hi:[1,0,1]
	v_pk_fma_f32 v[32:33], v[142:143], s[38:39], v[32:33] op_sel_hi:[1,0,1]
	v_pk_fma_f32 v[34:35], v[144:145], s[38:39], v[34:35] op_sel_hi:[1,0,1]
	s_branch .Lav0_ad5
.Lav0_hi5:
	s_bitcmp1_b32 s39, 0
	s_cbranch_scc1 .Lav0_a3_5
	v_pk_fma_f32 v[192:193], v[114:115], s[38:39], v[192:193] op_sel_hi:[1,0,1]
	v_pk_fma_f32 v[194:195], v[116:117], s[38:39], v[194:195] op_sel_hi:[1,0,1]
	v_pk_fma_f32 v[196:197], v[118:119], s[38:39], v[196:197] op_sel_hi:[1,0,1]
	v_pk_fma_f32 v[198:199], v[120:121], s[38:39], v[198:199] op_sel_hi:[1,0,1]
	v_pk_fma_f32 v[200:201], v[122:123], s[38:39], v[200:201] op_sel_hi:[1,0,1]
	v_pk_fma_f32 v[202:203], v[124:125], s[38:39], v[202:203] op_sel_hi:[1,0,1]
	v_pk_fma_f32 v[204:205], v[126:127], s[38:39], v[204:205] op_sel_hi:[1,0,1]
	v_pk_fma_f32 v[206:207], v[128:129], s[38:39], v[206:207] op_sel_hi:[1,0,1]
	v_pk_fma_f32 v[208:209], v[130:131], s[38:39], v[208:209] op_sel_hi:[1,0,1]
	v_pk_fma_f32 v[210:211], v[132:133], s[38:39], v[210:211] op_sel_hi:[1,0,1]
	v_pk_fma_f32 v[212:213], v[134:135], s[38:39], v[212:213] op_sel_hi:[1,0,1]
	v_pk_fma_f32 v[214:215], v[136:137], s[38:39], v[214:215] op_sel_hi:[1,0,1]
	v_pk_fma_f32 v[216:217], v[138:139], s[38:39], v[216:217] op_sel_hi:[1,0,1]
	v_pk_fma_f32 v[218:219], v[140:141], s[38:39], v[218:219] op_sel_hi:[1,0,1]
	v_pk_fma_f32 v[220:221], v[142:143], s[38:39], v[220:221] op_sel_hi:[1,0,1]
	v_pk_fma_f32 v[222:223], v[144:145], s[38:39], v[222:223] op_sel_hi:[1,0,1]
	s_branch .Lav0_ad5
.Lav0_a3_5:
	v_pk_fma_f32 v[148:149], v[114:115], s[38:39], v[148:149] op_sel_hi:[1,0,1]
	v_pk_fma_f32 v[150:151], v[116:117], s[38:39], v[150:151] op_sel_hi:[1,0,1]
	v_pk_fma_f32 v[152:153], v[118:119], s[38:39], v[152:153] op_sel_hi:[1,0,1]
	v_pk_fma_f32 v[154:155], v[120:121], s[38:39], v[154:155] op_sel_hi:[1,0,1]
	v_pk_fma_f32 v[156:157], v[122:123], s[38:39], v[156:157] op_sel_hi:[1,0,1]
	v_pk_fma_f32 v[158:159], v[124:125], s[38:39], v[158:159] op_sel_hi:[1,0,1]
	v_pk_fma_f32 v[232:233], v[126:127], s[38:39], v[232:233] op_sel_hi:[1,0,1]
	v_pk_fma_f32 v[234:235], v[128:129], s[38:39], v[234:235] op_sel_hi:[1,0,1]
	v_pk_fma_f32 v[236:237], v[130:131], s[38:39], v[236:237] op_sel_hi:[1,0,1]
	v_pk_fma_f32 v[238:239], v[132:133], s[38:39], v[238:239] op_sel_hi:[1,0,1]
	v_pk_fma_f32 v[240:241], v[134:135], s[38:39], v[240:241] op_sel_hi:[1,0,1]
	v_pk_fma_f32 v[242:243], v[136:137], s[38:39], v[242:243] op_sel_hi:[1,0,1]
	v_pk_fma_f32 v[244:245], v[138:139], s[38:39], v[244:245] op_sel_hi:[1,0,1]
	v_pk_fma_f32 v[246:247], v[140:141], s[38:39], v[246:247] op_sel_hi:[1,0,1]
	v_pk_fma_f32 v[248:249], v[142:143], s[38:39], v[248:249] op_sel_hi:[1,0,1]
	v_pk_fma_f32 v[250:251], v[144:145], s[38:39], v[250:251] op_sel_hi:[1,0,1]
.Lav0_ad5:
	s_mov_b32 s38, s1
	s_mov_b32 s39, s59

; #define PB_FENCE asm volatile("" ::: "memory")
; __device__ __forceinline__ void ph_peer_apply(const Params& P, int layer, float* xlat, float* xctx_in, float* xctx_out, int nrows, bool write_next, char* smem, float* xlat_out = nullptr) {
;     ...
;     PB_LOAD(bufA, tv, 0);
;     for (int gq = 0; gq < NG; gq += 2) {
;       PB_LOAD(bufB, tv, gq + 1); PB_FENCE;
;       PB_ACC(bufA, gq);
;       if (gq + 2 < NG) PB_LOAD(bufA, tv, gq + 2);
;       PB_FENCE;
;       PB_ACC(bufB, gq + 1);
;     }
.Lav0_sdl6:
	s_waitcnt vmcnt(21)
	v_lshlrev_b32_e32 v102, 23, v102
	v_cvt_scalef32_pk32_f32_fp6 v[114:145], v[96:101], v102
	s_bitcmp1_b32 s41, 1
	buffer_load_dwordx4 v[96:99], v2, s[16:19], s26 offen
	buffer_load_dwordx2 v[100:101], v2, s[16:19], s26 offen offset:16
	buffer_load_ubyte v102, v3, s[16:19], s26 offen
	s_cbranch_scc1 .Lav0_hi6
	s_bitcmp1_b32 s41, 0
	s_cbranch_scc1 .Lav0_a1_6
	v_pk_fma_f32 v[160:161], v[114:115], s[40:41], v[160:161] op_sel_hi:[1,0,1]
	v_pk_fma_f32 v[162:163], v[116:117], s[40:41], v[162:163] op_sel_hi:[1,0,1]
	v_pk_fma_f32 v[164:165], v[118:119], s[40:41], v[164:165] op_sel_hi:[1,0,1]
	v_pk_fma_f32 v[166:167], v[120:121], s[40:41], v[166:167] op_sel_hi:[1,0,1]
	v_pk_fma_f32 v[168:169], v[122:123], s[40:41], v[168:169] op_sel_hi:[1,0,1]
	v_pk_fma_f32 v[170:171], v[124:125], s[40:41], v[170:171] op_sel_hi:[1,0,1]
	v_pk_fma_f32 v[172:173], v[126:127], s[40:41], v[172:173] op_sel_hi:[1,0,1]
	v_pk_fma_f32 v[174:175], v[128:129], s[40:41], v[174:175] op_sel_hi:[1,0,1]
	v_pk_fma_f32 v[176:177], v[130:131], s[40:41], v[176:177] op_sel_hi:[1,0,1]
	v_pk_fma_f32 v[178:179], v[132:133], s[40:41], v[178:179] op_sel_hi:[1,0,1]
	v_pk_fma_f32 v[180:181], v[134:135], s[40:41], v[180:181] op_sel_hi:[1,0,1]
	v_pk_fma_f32 v[182:183], v[136:137], s[40:41], v[182:183] op_sel_hi:[1,0,1]
	v_pk_fma_f32 v[184:185], v[138:139], s[40:41], v[184:185] op_sel_hi:[1,0,1]
	v_pk_fma_f32 v[186:187], v[140:141], s[40:41], v[186:187] op_sel_hi:[1,0,1]
	v_pk_fma_f32 v[188:189], v[142:143], s[40:41], v[188:189] op_sel_hi:[1,0,1]
	v_pk_fma_f32 v[190:191], v[144:145], s[40:41], v[190:191] op_sel_hi:[1,0,1]
	s_branch .Lav0_ad6
.Lav0_a1_6:
	v_pk_fma_f32 v[4:5], v[114:115], s[40:41], v[4:5] op_sel_hi:[1,0,1]
	v_pk_fma_f32 v[6:7], v[116:117], s[40:41], v[6:7] op_sel_hi:[1,0,1]
	v_pk_fma_f32 v[8:9], v[118:119], s[40:41], v[8:9] op_sel_hi:[1,0,1]
	v_pk_fma_f32 v[10:11], v[120:121], s[40:41], v[10:11] op_sel_hi:[1,0,1]
	v_pk_fma_f32 v[12:13], v[122:123], s[40:41], v[12:13] op_sel_hi:[1,0,1]
	v_pk_fma_f32 v[14:15], v[124:125], s[40:41], v[14:15] op_sel_hi:[1,0,1]
	v_pk_fma_f32 v[16:17], v[126:127], s[40:41], v[16:17] op_sel_hi:[1,0,1]
	v_pk_fma_f32 v[18:19], v[128:129], s[40:41], v[18:19] op_sel_hi:[1,0,1]
	v_pk_fma_f32 v[20:21], v[130:131], s[40:41], v[20:21] op_sel_hi:[1,0,1]
	v_pk_fma_f32 v[22:23], v[132:133], s[40:41], v[22:23] op_sel_hi:[1,0,1]
	v_pk_fma_f32 v[24:25], v[134:135], s[40:41], v[24:25] op_sel_hi:[1,0,1]
	v_pk_fma_f32 v[26:27], v[136:137], s[40:41], v[26:27] op_sel_hi:[1,0,1]
	v_pk_fma_f32 v[28:29], v[138:139], s[40:41], v[28:29] op_sel_hi:[1,0,1]
	v_pk_fma_f32 v[30:31], v[140:141], s[40:41], v[30:31] op_sel_hi:[1,0,1]
	v_pk_fma_f32 v[32:33], v[142:143], s[40:41], v[32:33] op_sel_hi:[1,0,1]
	v_pk_fma_f32 v[34:35], v[144:145], s[40:41], v[34:35] op_sel_hi:[1,0,1]
	s_branch .Lav0_ad6
.Lav0_hi6:
	s_bitcmp1_b32 s41, 0
	s_cbranch_scc1 .Lav0_a3_6
	v_pk_fma_f32 v[192:193], v[114:115], s[40:41], v[192:193] op_sel_hi:[1,0,1]
	v_pk_fma_f32 v[194:195], v[116:117], s[40:41], v[194:195] op_sel_hi:[1,0,1]
	v_pk_fma_f32 v[196:197], v[118:119], s[40:41], v[196:197] op_sel_hi:[1,0,1]
	v_pk_fma_f32 v[198:199], v[120:121], s[40:41], v[198:199] op_sel_hi:[1,0,1]
	v_pk_fma_f32 v[200:201], v[122:123], s[40:41], v[200:201] op_sel_hi:[1,0,1]
	v_pk_fma_f32 v[202:203], v[124:125], s[40:41], v[202:203] op_sel_hi:[1,0,1]
	v_pk_fma_f32 v[204:205], v[126:127], s[40:41], v[204:205] op_sel_hi:[1,0,1]
	v_pk_fma_f32 v[206:207], v[128:129], s[40:41], v[206:207] op_sel_hi:[1,0,1]
	v_pk_fma_f32 v[208:209], v[130:131], s[40:41], v[208:209] op_sel_hi:[1,0,1]
	v_pk_fma_f32 v[210:211], v[132:133], s[40:41], v[210:211] op_sel_hi:[1,0,1]
	v_pk_fma_f32 v[212:213], v[134:135], s[40:41], v[212:213] op_sel_hi:[1,0,1]
	v_pk_fma_f32 v[214:215], v[136:137], s[40:41], v[214:215] op_sel_hi:[1,0,1]
	v_pk_fma_f32 v[216:217], v[138:139], s[40:41], v[216:217] op_sel_hi:[1,0,1]
	v_pk_fma_f32 v[218:219], v[140:141], s[40:41], v[218:219] op_sel_hi:[1,0,1]
	v_pk_fma_f32 v[220:221], v[142:143], s[40:41], v[220:221] op_sel_hi:[1,0,1]
	v_pk_fma_f32 v[222:223], v[144:145], s[40:41], v[222:223] op_sel_hi:[1,0,1]
	s_branch .Lav0_ad6
.Lav0_a3_6:
	v_pk_fma_f32 v[148:149], v[114:115], s[40:41], v[148:149] op_sel_hi:[1,0,1]
	v_pk_fma_f32 v[150:151], v[116:117], s[40:41], v[150:151] op_sel_hi:[1,0,1]
	v_pk_fma_f32 v[152:153], v[118:119], s[40:41], v[152:153] op_sel_hi:[1,0,1]
	v_pk_fma_f32 v[154:155], v[120:121], s[40:41], v[154:155] op_sel_hi:[1,0,1]
	v_pk_fma_f32 v[156:157], v[122:123], s[40:41], v[156:157] op_sel_hi:[1,0,1]
	v_pk_fma_f32 v[158:159], v[124:125], s[40:41], v[158:159] op_sel_hi:[1,0,1]
	v_pk_fma_f32 v[232:233], v[126:127], s[40:41], v[232:233] op_sel_hi:[1,0,1]
	v_pk_fma_f32 v[234:235], v[128:129], s[40:41], v[234:235] op_sel_hi:[1,0,1]
	v_pk_fma_f32 v[236:237], v[130:131], s[40:41], v[236:237] op_sel_hi:[1,0,1]
	v_pk_fma_f32 v[238:239], v[132:133], s[40:41], v[238:239] op_sel_hi:[1,0,1]
	v_pk_fma_f32 v[240:241], v[134:135], s[40:41], v[240:241] op_sel_hi:[1,0,1]
	v_pk_fma_f32 v[242:243], v[136:137], s[40:41], v[242:243] op_sel_hi:[1,0,1]
	v_pk_fma_f32 v[244:245], v[138:139], s[40:41], v[244:245] op_sel_hi:[1,0,1]
	v_pk_fma_f32 v[246:247], v[140:141], s[40:41], v[246:247] op_sel_hi:[1,0,1]
	v_pk_fma_f32 v[248:249], v[142:143], s[40:41], v[248:249] op_sel_hi:[1,0,1]
	v_pk_fma_f32 v[250:251], v[144:145], s[40:41], v[250:251] op_sel_hi:[1,0,1]
.Lav0_ad6:
	s_mov_b32 s40, s1
	s_mov_b32 s41, s59

; #define PB_FENCE asm volatile("" ::: "memory")
; __device__ __forceinline__ void ph_peer_apply(const Params& P, int layer, float* xlat, float* xctx_in, float* xctx_out, int nrows, bool write_next, char* smem, float* xlat_out = nullptr) {
;     ...
;     PB_LOAD(bufA, tv, 0);
;     for (int gq = 0; gq < NG; gq += 2) {
;       PB_LOAD(bufB, tv, gq + 1); PB_FENCE;
;       PB_ACC(bufA, gq);
;       if (gq + 2 < NG) PB_LOAD(bufA, tv, gq + 2);
;       PB_FENCE;
;       PB_ACC(bufB, gq + 1);
;     }
.Lav0_sdl7:
	s_waitcnt vmcnt(21)
	v_lshlrev_b32_e32 v110, 23, v110
	v_cvt_scalef32_pk32_f32_fp6 v[114:145], v[104:109], v110
	s_bitcmp1_b32 s43, 1
	buffer_load_dwordx4 v[104:107], v2, s[16:19], s26 offen
	buffer_load_dwordx2 v[108:109], v2, s[16:19], s26 offen offset:16
	buffer_load_ubyte v110, v3, s[16:19], s26 offen
	s_cbranch_scc1 .Lav0_hi7
	s_bitcmp1_b32 s43, 0
	s_cbranch_scc1 .Lav0_a1_7
	v_pk_fma_f32 v[160:161], v[114:115], s[42:43], v[160:161] op_sel_hi:[1,0,1]
	v_pk_fma_f32 v[162:163], v[116:117], s[42:43], v[162:163] op_sel_hi:[1,0,1]
	v_pk_fma_f32 v[164:165], v[118:119], s[42:43], v[164:165] op_sel_hi:[1,0,1]
	v_pk_fma_f32 v[166:167], v[120:121], s[42:43], v[166:167] op_sel_hi:[1,0,1]
	v_pk_fma_f32 v[168:169], v[122:123], s[42:43], v[168:169] op_sel_hi:[1,0,1]
	v_pk_fma_f32 v[170:171], v[124:125], s[42:43], v[170:171] op_sel_hi:[1,0,1]
	v_pk_fma_f32 v[172:173], v[126:127], s[42:43], v[172:173] op_sel_hi:[1,0,1]
	v_pk_fma_f32 v[174:175], v[128:129], s[42:43], v[174:175] op_sel_hi:[1,0,1]
	v_pk_fma_f32 v[176:177], v[130:131], s[42:43], v[176:177] op_sel_hi:[1,0,1]
	v_pk_fma_f32 v[178:179], v[132:133], s[42:43], v[178:179] op_sel_hi:[1,0,1]
	v_pk_fma_f32 v[180:181], v[134:135], s[42:43], v[180:181] op_sel_hi:[1,0,1]
	v_pk_fma_f32 v[182:183], v[136:137], s[42:43], v[182:183] op_sel_hi:[1,0,1]
	v_pk_fma_f32 v[184:185], v[138:139], s[42:43], v[184:185] op_sel_hi:[1,0,1]
	v_pk_fma_f32 v[186:187], v[140:141], s[42:43], v[186:187] op_sel_hi:[1,0,1]
	v_pk_fma_f32 v[188:189], v[142:143], s[42:43], v[188:189] op_sel_hi:[1,0,1]
	v_pk_fma_f32 v[190:191], v[144:145], s[42:43], v[190:191] op_sel_hi:[1,0,1]
	s_branch .Lav0_ad7
.Lav0_a1_7:
	v_pk_fma_f32 v[4:5], v[114:115], s[42:43], v[4:5] op_sel_hi:[1,0,1]
	v_pk_fma_f32 v[6:7], v[116:117], s[42:43], v[6:7] op_sel_hi:[1,0,1]
	v_pk_fma_f32 v[8:9], v[118:119], s[42:43], v[8:9] op_sel_hi:[1,0,1]
	v_pk_fma_f32 v[10:11], v[120:121], s[42:43], v[10:11] op_sel_hi:[1,0,1]
	v_pk_fma_f32 v[12:13], v[122:123], s[42:43], v[12:13] op_sel_hi:[1,0,1]
	v_pk_fma_f32 v[14:15], v[124:125], s[42:43], v[14:15] op_sel_hi:[1,0,1]
	v_pk_fma_f32 v[16:17], v[126:127], s[42:43], v[16:17] op_sel_hi:[1,0,1]
	v_pk_fma_f32 v[18:19], v[128:129], s[42:43], v[18:19] op_sel_hi:[1,0,1]
	v_pk_fma_f32 v[20:21], v[130:131], s[42:43], v[20:21] op_sel_hi:[1,0,1]
	v_pk_fma_f32 v[22:23], v[132:133], s[42:43], v[22:23] op_sel_hi:[1,0,1]
	v_pk_fma_f32 v[24:25], v[134:135], s[42:43], v[24:25] op_sel_hi:[1,0,1]
	v_pk_fma_f32 v[26:27], v[136:137], s[42:43], v[26:27] op_sel_hi:[1,0,1]
	v_pk_fma_f32 v[28:29], v[138:139], s[42:43], v[28:29] op_sel_hi:[1,0,1]
	v_pk_fma_f32 v[30:31], v[140:141], s[42:43], v[30:31] op_sel_hi:[1,0,1]
	v_pk_fma_f32 v[32:33], v[142:143], s[42:43], v[32:33] op_sel_hi:[1,0,1]
	v_pk_fma_f32 v[34:35], v[144:145], s[42:43], v[34:35] op_sel_hi:[1,0,1]
	s_branch .Lav0_ad7
.Lav0_hi7:
	s_bitcmp1_b32 s43, 0
	s_cbranch_scc1 .Lav0_a3_7
	v_pk_fma_f32 v[192:193], v[114:115], s[42:43], v[192:193] op_sel_hi:[1,0,1]
	v_pk_fma_f32 v[194:195], v[116:117], s[42:43], v[194:195] op_sel_hi:[1,0,1]
	v_pk_fma_f32 v[196:197], v[118:119], s[42:43], v[196:197] op_sel_hi:[1,0,1]
	v_pk_fma_f32 v[198:199], v[120:121], s[42:43], v[198:199] op_sel_hi:[1,0,1]
	v_pk_fma_f32 v[200:201], v[122:123], s[42:43], v[200:201] op_sel_hi:[1,0,1]
	v_pk_fma_f32 v[202:203], v[124:125], s[42:43], v[202:203] op_sel_hi:[1,0,1]
	v_pk_fma_f32 v[204:205], v[126:127], s[42:43], v[204:205] op_sel_hi:[1,0,1]
	v_pk_fma_f32 v[206:207], v[128:129], s[42:43], v[206:207] op_sel_hi:[1,0,1]
	v_pk_fma_f32 v[208:209], v[130:131], s[42:43], v[208:209] op_sel_hi:[1,0,1]
	v_pk_fma_f32 v[210:211], v[132:133], s[42:43], v[210:211] op_sel_hi:[1,0,1]
	v_pk_fma_f32 v[212:213], v[134:135], s[42:43], v[212:213] op_sel_hi:[1,0,1]
	v_pk_fma_f32 v[214:215], v[136:137], s[42:43], v[214:215] op_sel_hi:[1,0,1]
	v_pk_fma_f32 v[216:217], v[138:139], s[42:43], v[216:217] op_sel_hi:[1,0,1]
	v_pk_fma_f32 v[218:219], v[140:141], s[42:43], v[218:219] op_sel_hi:[1,0,1]
	v_pk_fma_f32 v[220:221], v[142:143], s[42:43], v[220:221] op_sel_hi:[1,0,1]
	v_pk_fma_f32 v[222:223], v[144:145], s[42:43], v[222:223] op_sel_hi:[1,0,1]
	s_branch .Lav0_ad7
.Lav0_a3_7:
	v_pk_fma_f32 v[148:149], v[114:115], s[42:43], v[148:149] op_sel_hi:[1,0,1]
	v_pk_fma_f32 v[150:151], v[116:117], s[42:43], v[150:151] op_sel_hi:[1,0,1]
	v_pk_fma_f32 v[152:153], v[118:119], s[42:43], v[152:153] op_sel_hi:[1,0,1]
	v_pk_fma_f32 v[154:155], v[120:121], s[42:43], v[154:155] op_sel_hi:[1,0,1]
	v_pk_fma_f32 v[156:157], v[122:123], s[42:43], v[156:157] op_sel_hi:[1,0,1]
	v_pk_fma_f32 v[158:159], v[124:125], s[42:43], v[158:159] op_sel_hi:[1,0,1]
	v_pk_fma_f32 v[232:233], v[126:127], s[42:43], v[232:233] op_sel_hi:[1,0,1]
	v_pk_fma_f32 v[234:235], v[128:129], s[42:43], v[234:235] op_sel_hi:[1,0,1]
	v_pk_fma_f32 v[236:237], v[130:131], s[42:43], v[236:237] op_sel_hi:[1,0,1]
	v_pk_fma_f32 v[238:239], v[132:133], s[42:43], v[238:239] op_sel_hi:[1,0,1]
	v_pk_fma_f32 v[240:241], v[134:135], s[42:43], v[240:241] op_sel_hi:[1,0,1]
	v_pk_fma_f32 v[242:243], v[136:137], s[42:43], v[242:243] op_sel_hi:[1,0,1]
	v_pk_fma_f32 v[244:245], v[138:139], s[42:43], v[244:245] op_sel_hi:[1,0,1]
	v_pk_fma_f32 v[246:247], v[140:141], s[42:43], v[246:247] op_sel_hi:[1,0,1]
	v_pk_fma_f32 v[248:249], v[142:143], s[42:43], v[248:249] op_sel_hi:[1,0,1]
	v_pk_fma_f32 v[250:251], v[144:145], s[42:43], v[250:251] op_sel_hi:[1,0,1]
.Lav0_ad7:
	s_mov_b32 s42, s1
	s_mov_b32 s43, s59
	s_cmp_lg_u32 s48, 0
	s_cbranch_scc0 .Lav0_pass
	s_add_u32 s49, s49, 1
	s_cmp_lt_u32 s49, 2
	s_cbranch_scc1 .Lav0_pass
	s_branch .Lav0_gend

; #define PB_FENCE asm volatile("" ::: "memory")
; __device__ __forceinline__ void ph_peer_apply(const Params& P, int layer, float* xlat, float* xctx_in, float* xctx_out, int nrows, bool write_next, char* smem, float* xlat_out = nullptr) {
;     ...
;     for (int gq = 0; gq < NG; gq += 2) {
;       PB_LOAD(bufB, tv, gq + 1); PB_FENCE;
;       PB_ACC(bufA, gq);
;       if (gq + 2 < NG) PB_LOAD(bufA, tv, gq + 2);
;       PB_FENCE;
;       PB_ACC(bufB, gq + 1);
;     }
;     ...
;     const float* xs1 = (row < NL ? xlat + (size_t)row * D : xctx_in + (size_t)(row - NL) * D) + lb * 32;
;     float* xo = (row < NL ? (xlat_out ? xlat_out : xlat) + (size_t)row * D : xctx_out + (size_t)(row - NL) * D) + lb * 32;
;     const float* gt = mod_ptr(P, layer, row, 5) + lb * 32;
.Lav0_gend:
	s_waitcnt vmcnt(0)
	v_mov_b32_e32 v48, v192
	v_mov_b32_e32 v49, v193
	v_mov_b32_e32 v50, v194
	v_mov_b32_e32 v51, v195
	v_mov_b32_e32 v52, v196
	v_mov_b32_e32 v53, v197
	v_mov_b32_e32 v54, v198
	v_mov_b32_e32 v55, v199
	v_mov_b32_e32 v56, v200
	v_mov_b32_e32 v57, v201
	v_mov_b32_e32 v58, v202
	v_mov_b32_e32 v59, v203
	v_mov_b32_e32 v60, v204
	v_mov_b32_e32 v61, v205
	v_mov_b32_e32 v62, v206
	v_mov_b32_e32 v63, v207
	v_mov_b32_e32 v64, v208
	v_mov_b32_e32 v65, v209
	v_mov_b32_e32 v66, v210
	v_mov_b32_e32 v67, v211
	v_mov_b32_e32 v68, v212
	v_mov_b32_e32 v69, v213
	v_mov_b32_e32 v70, v214
	v_mov_b32_e32 v71, v215
	v_mov_b32_e32 v72, v216
	v_mov_b32_e32 v73, v217
	v_mov_b32_e32 v74, v218
	v_mov_b32_e32 v75, v219
	v_mov_b32_e32 v76, v220
	v_mov_b32_e32 v77, v221
	v_mov_b32_e32 v78, v222
	v_mov_b32_e32 v79, v223
	s_mov_b32 s63, 0
.Lav0_lnl:
	s_add_u32 s1, s51, s63
	s_mul_i32 s1, s1, s44
	s_add_u32 s45, s1, s13
	s_cmp_eq_u32 s63, 1
	s_cbranch_scc1 .Lav0_cp1
	s_cmp_eq_u32 s63, 2
	s_cbranch_scc1 .Lav0_cp2
	s_cmp_eq_u32 s63, 3
	s_cbranch_scc1 .Lav0_cp3
	s_branch .Lav0_cpd
.Lav0_cp1:
	v_mov_b32_e32 v160, v4
	v_mov_b32_e32 v161, v5
	v_mov_b32_e32 v162, v6
	v_mov_b32_e32 v163, v7
	v_mov_b32_e32 v164, v8
	v_mov_b32_e32 v165, v9
	v_mov_b32_e32 v166, v10
	v_mov_b32_e32 v167, v11
	v_mov_b32_e32 v168, v12
	v_mov_b32_e32 v169, v13
	v_mov_b32_e32 v170, v14
	v_mov_b32_e32 v171, v15
	v_mov_b32_e32 v172, v16
	v_mov_b32_e32 v173, v17
	v_mov_b32_e32 v174, v18
	v_mov_b32_e32 v175, v19
	v_mov_b32_e32 v176, v20
	v_mov_b32_e32 v177, v21
	v_mov_b32_e32 v178, v22
	v_mov_b32_e32 v179, v23
	v_mov_b32_e32 v180, v24
	v_mov_b32_e32 v181, v25
	v_mov_b32_e32 v182, v26
	v_mov_b32_e32 v183, v27
	v_mov_b32_e32 v184, v28
	v_mov_b32_e32 v185, v29
	v_mov_b32_e32 v186, v30
	v_mov_b32_e32 v187, v31
	v_mov_b32_e32 v188, v32
	v_mov_b32_e32 v189, v33
	v_mov_b32_e32 v190, v34
	v_mov_b32_e32 v191, v35
	s_branch .Lav0_cpd
.Lav0_cp2:
	v_mov_b32_e32 v160, v48
	v_mov_b32_e32 v161, v49
	v_mov_b32_e32 v162, v50
	v_mov_b32_e32 v163, v51
	v_mov_b32_e32 v164, v52
	v_mov_b32_e32 v165, v53
	v_mov_b32_e32 v166, v54
	v_mov_b32_e32 v167, v55
	v_mov_b32_e32 v168, v56
	v_mov_b32_e32 v169, v57
	v_mov_b32_e32 v170, v58
	v_mov_b32_e32 v171, v59
	v_mov_b32_e32 v172, v60
	v_mov_b32_e32 v173, v61
	v_mov_b32_e32 v174, v62
	v_mov_b32_e32 v175, v63
	v_mov_b32_e32 v176, v64
	v_mov_b32_e32 v177, v65
	v_mov_b32_e32 v178, v66
	v_mov_b32_e32 v179, v67
	v_mov_b32_e32 v180, v68
	v_mov_b32_e32 v181, v69
	v_mov_b32_e32 v182, v70
	v_mov_b32_e32 v183, v71
	v_mov_b32_e32 v184, v72
	v_mov_b32_e32 v185, v73
	v_mov_b32_e32 v186, v74
	v_mov_b32_e32 v187, v75
	v_mov_b32_e32 v188, v76
	v_mov_b32_e32 v189, v77
	v_mov_b32_e32 v190, v78
	v_mov_b32_e32 v191, v79
	s_branch .Lav0_cpd
.Lav0_cp3:
	v_mov_b32_e32 v160, v148
	v_mov_b32_e32 v161, v149
	v_mov_b32_e32 v162, v150
	v_mov_b32_e32 v163, v151
	v_mov_b32_e32 v164, v152
	v_mov_b32_e32 v165, v153
	v_mov_b32_e32 v166, v154
	v_mov_b32_e32 v167, v155
	v_mov_b32_e32 v168, v156
	v_mov_b32_e32 v169, v157
	v_mov_b32_e32 v170, v158
	v_mov_b32_e32 v171, v159
	v_mov_b32_e32 v172, v232
	v_mov_b32_e32 v173, v233
	v_mov_b32_e32 v174, v234
	v_mov_b32_e32 v175, v235
	v_mov_b32_e32 v176, v236
	v_mov_b32_e32 v177, v237
	v_mov_b32_e32 v178, v238
	v_mov_b32_e32 v179, v239
	v_mov_b32_e32 v180, v240
	v_mov_b32_e32 v181, v241
	v_mov_b32_e32 v182, v242
	v_mov_b32_e32 v183, v243
	v_mov_b32_e32 v184, v244
	v_mov_b32_e32 v185, v245
	v_mov_b32_e32 v186, v246
	v_mov_b32_e32 v187, v247
	v_mov_b32_e32 v188, v248
	v_mov_b32_e32 v189, v249
	v_mov_b32_e32 v190, v250
	v_mov_b32_e32 v191, v251
; __device__ __forceinline__ void ph_peer_apply(const Params& P, int layer, float* xlat, float* xctx_in, float* xctx_out, int nrows, bool write_next, char* smem, float* xlat_out = nullptr) {
;     ...
;     const float* xs1 = (row < NL ? xlat + (size_t)row * D : xctx_in + (size_t)(row - NL) * D) + lb * 32;
;     float* xo = (row < NL ? (xlat_out ? xlat_out : xlat) + (size_t)row * D : xctx_out + (size_t)(row - NL) * D) + lb * 32;
;     const float* gt = mod_ptr(P, layer, row, 5) + lb * 32;
;     float s = 0.f;
; #pragma unroll
;     for (int j4 = 0; j4 < 8; ++j4) {
;       float4 xa; const float4 ga = *(const float4*)(gt + j4 * 4);
;       if (row < NL) { const h16x4 xh_ = *(const h16x4*)((const h16*)(xlat + (size_t)row * D) + lb * 32 + j4 * 4); xa = make_float4((float)xh_[0], (float)xh_[1], (float)xh_[2], (float)xh_[3]); }
;       else xa = *(const float4*)(xs1 + j4 * 4);
;       o[j4 * 4 + 0] = ALPHA * xa.x + ga.x * o[j4 * 4 + 0]; o[j4 * 4 + 1] = ALPHA * xa.y + ga.y * o[j4 * 4 + 1];
;       o[j4 * 4 + 2] = ALPHA * xa.z + ga.z * o[j4 * 4 + 2]; o[j4 * 4 + 3] = ALPHA * xa.w + ga.w * o[j4 * 4 + 3];
;       s += (o[j4 * 4 + 0] + o[j4 * 4 + 1]) + (o[j4 * 4 + 2] + o[j4 * 4 + 3]);
;     }
.Lav0_cpd:
	s_cmp_ge_u32 s45, 0x8000
	s_cselect_b32 s48, 1, 0
	s_lshr_b32 s49, s45, 14
	s_cmp_lg_u32 s48, 0
	s_cselect_b32 s49, 2, s49
	s_sub_u32 s50, s45, 0x8000
	s_lshl_b32 s15, s45, 13
	s_lshr_b32 s31, s45, 19
	s_add_u32 s40, s6, s15
	s_addc_u32 s41, s7, s31
	s_add_u32 s15, s49, 0
	s_mul_i32 s15, s15, 6
	s_add_u32 s15, s15, 5
	s_lshl_b32 s15, s15, 13
	s_add_u32 s42, s4, 0x4000
	s_addc_u32 s43, s5, 0
	s_add_u32 s42, s42, s15
	s_addc_u32 s43, s43, 0
	global_load_dwordx4 v[112:115], v225, s[42:43]
	global_load_dwordx4 v[116:119], v225, s[42:43] offset:16
	global_load_dwordx4 v[120:123], v225, s[42:43] offset:32
	global_load_dwordx4 v[124:127], v225, s[42:43] offset:48
	global_load_dwordx4 v[128:131], v225, s[42:43] offset:64
	global_load_dwordx4 v[132:135], v225, s[42:43] offset:80
	global_load_dwordx4 v[136:139], v225, s[42:43] offset:96
	global_load_dwordx4 v[140:143], v225, s[42:43] offset:112
	s_mov_b32 s15, 0x3fb504f3
	s_cmp_lg_u32 s48, 0
	s_cbranch_scc1 .Lap0_res_ctx
	global_load_dwordx4 v[192:195], v224, s[40:41]
	global_load_dwordx4 v[196:199], v224, s[40:41] offset:16
	global_load_dwordx4 v[200:203], v224, s[40:41] offset:32
	global_load_dwordx4 v[204:207], v224, s[40:41] offset:48
	s_waitcnt vmcnt(0)
	v_mul_f32_e32 v160, v112, v160
	v_mul_f32_e32 v161, v113, v161
	v_mul_f32_e32 v162, v114, v162
	v_mul_f32_e32 v163, v115, v163
	v_mul_f32_e32 v164, v116, v164
	v_mul_f32_e32 v165, v117, v165
	v_mul_f32_e32 v166, v118, v166
	v_mul_f32_e32 v167, v119, v167
	v_mul_f32_e32 v168, v120, v168
	v_mul_f32_e32 v169, v121, v169
	v_mul_f32_e32 v170, v122, v170
	v_mul_f32_e32 v171, v123, v171
	v_mul_f32_e32 v172, v124, v172
	v_mul_f32_e32 v173, v125, v173
	v_mul_f32_e32 v174, v126, v174
	v_mul_f32_e32 v175, v127, v175
	v_mul_f32_e32 v176, v128, v176
	v_mul_f32_e32 v177, v129, v177
	v_mul_f32_e32 v178, v130, v178
	v_mul_f32_e32 v179, v131, v179
	v_mul_f32_e32 v180, v132, v180
	v_mul_f32_e32 v181, v133, v181
	v_mul_f32_e32 v182, v134, v182
	v_mul_f32_e32 v183, v135, v183
	v_mul_f32_e32 v184, v136, v184
	v_mul_f32_e32 v185, v137, v185
	v_mul_f32_e32 v186, v138, v186
	v_mul_f32_e32 v187, v139, v187
	v_mul_f32_e32 v188, v140, v188
	v_mul_f32_e32 v189, v141, v189
	v_mul_f32_e32 v190, v142, v190
	v_mul_f32_e32 v191, v143, v191
	v_fma_mix_f32 v160, s15, v192, v160 op_sel_hi:[0,1,0]
	v_fma_mix_f32 v161, s15, v192, v161 op_sel:[0,1,0] op_sel_hi:[0,1,0]
	v_fma_mix_f32 v162, s15, v193, v162 op_sel_hi:[0,1,0]
	v_fma_mix_f32 v163, s15, v193, v163 op_sel:[0,1,0] op_sel_hi:[0,1,0]
	v_fma_mix_f32 v164, s15, v194, v164 op_sel_hi:[0,1,0]
	v_fma_mix_f32 v165, s15, v194, v165 op_sel:[0,1,0] op_sel_hi:[0,1,0]
	v_fma_mix_f32 v166, s15, v195, v166 op_sel_hi:[0,1,0]
	v_fma_mix_f32 v167, s15, v195, v167 op_sel:[0,1,0] op_sel_hi:[0,1,0]
	v_fma_mix_f32 v168, s15, v196, v168 op_sel_hi:[0,1,0]
	v_fma_mix_f32 v169, s15, v196, v169 op_sel:[0,1,0] op_sel_hi:[0,1,0]
	v_fma_mix_f32 v170, s15, v197, v170 op_sel_hi:[0,1,0]
	v_fma_mix_f32 v171, s15, v197, v171 op_sel:[0,1,0] op_sel_hi:[0,1,0]
	v_fma_mix_f32 v172, s15, v198, v172 op_sel_hi:[0,1,0]
	v_fma_mix_f32 v173, s15, v198, v173 op_sel:[0,1,0] op_sel_hi:[0,1,0]
	v_fma_mix_f32 v174, s15, v199, v174 op_sel_hi:[0,1,0]
	v_fma_mix_f32 v175, s15, v199, v175 op_sel:[0,1,0] op_sel_hi:[0,1,0]
	v_fma_mix_f32 v176, s15, v200, v176 op_sel_hi:[0,1,0]
	v_fma_mix_f32 v177, s15, v200, v177 op_sel:[0,1,0] op_sel_hi:[0,1,0]
	v_fma_mix_f32 v178, s15, v201, v178 op_sel_hi:[0,1,0]
	v_fma_mix_f32 v179, s15, v201, v179 op_sel:[0,1,0] op_sel_hi:[0,1,0]
	v_fma_mix_f32 v180, s15, v202, v180 op_sel_hi:[0,1,0]
	v_fma_mix_f32 v181, s15, v202, v181 op_sel:[0,1,0] op_sel_hi:[0,1,0]
	v_fma_mix_f32 v182, s15, v203, v182 op_sel_hi:[0,1,0]
	v_fma_mix_f32 v183, s15, v203, v183 op_sel:[0,1,0] op_sel_hi:[0,1,0]
	v_fma_mix_f32 v184, s15, v204, v184 op_sel_hi:[0,1,0]
	v_fma_mix_f32 v185, s15, v204, v185 op_sel:[0,1,0] op_sel_hi:[0,1,0]
	v_fma_mix_f32 v186, s15, v205, v186 op_sel_hi:[0,1,0]
	v_fma_mix_f32 v187, s15, v205, v187 op_sel:[0,1,0] op_sel_hi:[0,1,0]
	v_fma_mix_f32 v188, s15, v206, v188 op_sel_hi:[0,1,0]
	v_fma_mix_f32 v189, s15, v206, v189 op_sel:[0,1,0] op_sel_hi:[0,1,0]
	v_fma_mix_f32 v190, s15, v207, v190 op_sel_hi:[0,1,0]
	v_fma_mix_f32 v191, s15, v207, v191 op_sel:[0,1,0] op_sel_hi:[0,1,0]
	s_branch .Lap0_res_done

; __device__ __forceinline__ void ph_peer_apply(const Params& P, int layer, float* xlat, float* xctx_in, float* xctx_out, int nrows, bool write_next, char* smem, float* xlat_out = nullptr) {
;     ...
;     const float* sh1n = mod_ptr(P, 1, row, 0) + lb * 32;
;     const float* sc1n = mod_ptr(P, 1, row, 1) + lb * 32;
;     if (lact) {
; #pragma unroll
;       for (int j4 = 0; j4 < 8; ++j4) {
;         const float4 gv = *(const float4*)(gp + j4 * 4), bv = *(const float4*)(bp + j4 * 4);
;         float4 ov;
;         ov.x = (o[j4 * 4 + 0] - mu) * rstd * gv.x + bv.x; ov.y = (o[j4 * 4 + 1] - mu) * rstd * gv.y + bv.y;
;         ov.z = (o[j4 * 4 + 2] - mu) * rstd * gv.z + bv.z; ov.w = (o[j4 * 4 + 3] - mu) * rstd * gv.w + bv.w;
;         if (row < NL && write_next) { h16x4 oh_; oh_[0] = (h16)ov.x; oh_[1] = (h16)ov.y; oh_[2] = (h16)ov.z; oh_[3] = (h16)ov.w; *(h16x4*)((h16*)((xlat_out ? xlat_out : xlat) + (size_t)row * D) + lb * 32 + j4 * 4) = oh_; }
;         else *(float4*)(xo + j4 * 4) = ov;
;         if (write_next) {
;           const float4 sv = *(const float4*)(sc1n + j4 * 4), hv = *(const float4*)(sh1n + j4 * 4);
;           h16x4 nx;
;           nx[0] = (h16)(ov.x * (1.f + sv.x) + hv.x); nx[1] = (h16)(ov.y * (1.f + sv.y) + hv.y);
;           nx[2] = (h16)(ov.z * (1.f + sv.z) + hv.z); nx[3] = (h16)(ov.w * (1.f + sv.w) + hv.w);
;           *(h16x4*)(xq + (size_t)row * D + lb * 32 + j4 * 4) = nx;
;         }
.Lap0_out_done:
	s_add_u32 s15, s49, 3
	s_mul_i32 s15, s15, 6
	s_lshl_b32 s15, s15, 13
	s_add_u32 s42, s4, 0x4000
	s_addc_u32 s43, s5, 0
	s_add_u32 s42, s42, s15
	s_addc_u32 s43, s43, 0
	s_add_u32 s26, s42, 0x2000
	s_addc_u32 s27, s43, 0
	global_load_dwordx4 v[112:115], v225, s[26:27]
	global_load_dwordx4 v[116:119], v225, s[26:27] offset:16
	global_load_dwordx4 v[120:123], v225, s[26:27] offset:32
	global_load_dwordx4 v[124:127], v225, s[26:27] offset:48
	global_load_dwordx4 v[128:131], v225, s[26:27] offset:64
	global_load_dwordx4 v[132:135], v225, s[26:27] offset:80
	global_load_dwordx4 v[136:139], v225, s[26:27] offset:96
	global_load_dwordx4 v[140:143], v225, s[26:27] offset:112
	global_load_dwordx4 v[192:195], v225, s[42:43]
	global_load_dwordx4 v[196:199], v225, s[42:43] offset:16
	global_load_dwordx4 v[200:203], v225, s[42:43] offset:32
	global_load_dwordx4 v[204:207], v225, s[42:43] offset:48
	global_load_dwordx4 v[208:211], v225, s[42:43] offset:64
	global_load_dwordx4 v[212:215], v225, s[42:43] offset:80
	global_load_dwordx4 v[216:219], v225, s[42:43] offset:96
	global_load_dwordx4 v[220:223], v225, s[42:43] offset:112
	s_lshl_b32 s15, s45, 12
	s_lshr_b32 s31, s45, 20
	s_add_u32 s20, s4, 0xbe4c000
	s_addc_u32 s21, s5, 0
	s_add_u32 s20, s20, s15
	s_addc_u32 s21, s21, s31
	s_waitcnt vmcnt(0)
	v_fma_f32 v160, v160, v112, v160
	v_fma_f32 v161, v161, v113, v161
	v_fma_f32 v162, v162, v114, v162
	v_fma_f32 v163, v163, v115, v163
	v_fma_f32 v164, v164, v116, v164
	v_fma_f32 v165, v165, v117, v165
	v_fma_f32 v166, v166, v118, v166
	v_fma_f32 v167, v167, v119, v167
	v_fma_f32 v168, v168, v120, v168
	v_fma_f32 v169, v169, v121, v169
	v_fma_f32 v170, v170, v122, v170
	v_fma_f32 v171, v171, v123, v171
	v_fma_f32 v172, v172, v124, v172
	v_fma_f32 v173, v173, v125, v173
	v_fma_f32 v174, v174, v126, v174
	v_fma_f32 v175, v175, v127, v175
	v_fma_f32 v176, v176, v128, v176
	v_fma_f32 v177, v177, v129, v177
	v_fma_f32 v178, v178, v130, v178
	v_fma_f32 v179, v179, v131, v179
	v_fma_f32 v180, v180, v132, v180
	v_fma_f32 v181, v181, v133, v181
	v_fma_f32 v182, v182, v134, v182
	v_fma_f32 v183, v183, v135, v183
	v_fma_f32 v184, v184, v136, v184
	v_fma_f32 v185, v185, v137, v185
	v_fma_f32 v186, v186, v138, v186
	v_fma_f32 v187, v187, v139, v187
	v_fma_f32 v188, v188, v140, v188
	v_fma_f32 v189, v189, v141, v189
	v_fma_f32 v190, v190, v142, v190
	v_fma_f32 v191, v191, v143, v191
	v_add_f32_e32 v160, v160, v192
	v_add_f32_e32 v161, v161, v193
	v_add_f32_e32 v162, v162, v194
	v_add_f32_e32 v163, v163, v195
	v_add_f32_e32 v164, v164, v196
	v_add_f32_e32 v165, v165, v197
	v_add_f32_e32 v166, v166, v198
	v_add_f32_e32 v167, v167, v199
	v_add_f32_e32 v168, v168, v200
	v_add_f32_e32 v169, v169, v201
	v_add_f32_e32 v170, v170, v202
	v_add_f32_e32 v171, v171, v203
	v_add_f32_e32 v172, v172, v204
	v_add_f32_e32 v173, v173, v205
	v_add_f32_e32 v174, v174, v206
	v_add_f32_e32 v175, v175, v207
	v_add_f32_e32 v176, v176, v208
	v_add_f32_e32 v177, v177, v209
	v_add_f32_e32 v178, v178, v210
	v_add_f32_e32 v179, v179, v211
	v_add_f32_e32 v180, v180, v212
	v_add_f32_e32 v181, v181, v213
	v_add_f32_e32 v182, v182, v214
	v_add_f32_e32 v183, v183, v215
	v_add_f32_e32 v184, v184, v216
	v_add_f32_e32 v185, v185, v217
	v_add_f32_e32 v186, v186, v218
	v_add_f32_e32 v187, v187, v219
	v_add_f32_e32 v188, v188, v220
	v_add_f32_e32 v189, v189, v221
	v_add_f32_e32 v190, v190, v222
	v_add_f32_e32 v191, v191, v223
	v_cvt_pk_f16_f32 v192, v160, v161
	v_cvt_pk_f16_f32 v193, v162, v163
	v_cvt_pk_f16_f32 v194, v164, v165
	v_cvt_pk_f16_f32 v195, v166, v167
	v_cvt_pk_f16_f32 v196, v168, v169
	v_cvt_pk_f16_f32 v197, v170, v171
	v_cvt_pk_f16_f32 v198, v172, v173
	v_cvt_pk_f16_f32 v199, v174, v175
	v_cvt_pk_f16_f32 v200, v176, v177
	v_cvt_pk_f16_f32 v201, v178, v179
	v_cvt_pk_f16_f32 v202, v180, v181
	v_cvt_pk_f16_f32 v203, v182, v183
	v_cvt_pk_f16_f32 v204, v184, v185
	v_cvt_pk_f16_f32 v205, v186, v187
	v_cvt_pk_f16_f32 v206, v188, v189
	v_cvt_pk_f16_f32 v207, v190, v191
	global_store_dwordx4 v224, v[192:195], s[20:21]
	global_store_dwordx4 v224, v[196:199], s[20:21] offset:16
	global_store_dwordx4 v224, v[200:203], s[20:21] offset:32
	global_store_dwordx4 v224, v[204:207], s[20:21] offset:48
	s_add_u32 s63, s63, 1
	s_cmp_lt_u32 s63, s57
	s_cbranch_scc1 .Lav0_lnl
	s_add_u32 s51, s51, 4
	s_cmp_lt_u32 s51, s62
	s_cbranch_scc1 .Lav0_group

; #define TIDX tid_fn()
; __device__ __forceinline__ void ph_peer_apply(const Params& P, int layer, float* xlat, float* xctx_in, float* xctx_out, int nrows, bool write_next, char* smem, float* xlat_out = nullptr) {
;     ...
;   const int tid = TIDX, wave = tid >> 6, lane = tid & 63;
;   const bool lact = lane < P6_NB;
;   const int lb = lact ? lane : 0;
;   for (int row = blockIdx.x * (NTHR / 64) + wave; row < nrows; row += gridDim.x * (NTHR / 64)) {
;     float xv[32];
; #pragma unroll
;     for (int j8 = 0; j8 < 4; ++j8) {
;       const h16x8 t = *(const h16x8*)(xq + (size_t)row * D + lb * 32 + j8 * 8);
; #pragma unroll
;       for (int j = 0; j < 8; ++j) xv[j8 * 8 + j] = lact ? (float)t[j] : 0.f;
;     }
;     const int id0 = seli[(size_t)row * NSEL + lane], id1 = seli[(size_t)row * NSEL + 64 + lane];
;     const float g0 = selg[(size_t)row * NSEL + lane], g1 = selg[(size_t)row * NSEL + 64 + lane];
.LBB0_3667:
	s_or_b64 exec, exec, s[2:3]
	s_waitcnt lgkmcnt(0)
	s_barrier
	s_load_dwordx4 s[4:7], s[96:97], 0x170
	s_load_dwordx4 s[8:11], s[96:97], 0x30
	v_readfirstlane_b32 s12, v0
	s_lshr_b32 s12, s12, 6
	v_and_b32_e32 v1, 63, v0
	v_mul_u32_u24_e32 v2, 24, v1
	v_add_u32_e32 v3, 0x600, v1
	v_lshlrev_b32_e32 v224, 6, v1
	v_lshlrev_b32_e32 v225, 7, v1
	v_lshlrev_b32_e32 v226, 2, v1
	v_lshrrev_b32_e32 v192, 2, v1
	v_and_b32_e32 v193, 1, v1
	v_lshl_add_u32 v192, v192, 1, v193
	v_lshlrev_b32_e32 v227, 2, v192
	s_mul_i32 s15, s12, 0x2800
	v_add_u32_e32 v228, s15, v226
	v_add_u32_e32 v227, s15, v227
	s_mov_b32 s46, 0x3333
	s_mov_b32 s47, 0
	s_mov_b32 s34, 0x22222222
	s_mov_b32 s35, 0x22222222
	s_waitcnt lgkmcnt(0)
	s_mov_b64 s[40:41], s[4:5]
	s_mov_b64 s[4:5], s[6:7]
	s_mov_b64 s[6:7], s[40:41]
	s_add_u32 s16, s4, 0x3c7c000
	s_addc_u32 s17, s5, 0
	s_add_u32 s18, s4, 0x7c7c000
	s_addc_u32 s19, s5, 0
	s_add_u32 s13, s60, s12
	s_lshl_b32 s44, s84, 3
	s_add_u32 s16, s4, 0x3c7c000
	s_addc_u32 s17, s5, 0
	s_and_b32 s17, s17, 0xffff
	s_mov_b32 s18, 0x1900000
	s_mov_b32 s19, 0x20000
	s_mov_b32 s50, 0
	s_mov_b32 s1, s13
.Lau1_ntl:
	s_add_u32 s50, s50, 1
	s_add_u32 s1, s1, s44
	s_cmp_lt_u32 s1, 0x8000
	s_cbranch_scc1 .Lau1_ntl
	s_mov_b32 s58, 0
	s_mov_b32 s59, 0
	s_mov_b32 s62, 0
	s_mov_b32 s48, 0
	s_mov_b32 s49, 0
	s_mov_b32 s45, s13
	s_lshl_b32 s15, s45, 12
	s_lshr_b32 s31, s45, 20
	s_add_u32 s20, s4, 0xbe4c000
	s_addc_u32 s21, s5, 0
	s_add_u32 s20, s20, s15
	s_addc_u32 s21, s21, s31
	s_lshl_b32 s15, s45, 9
	s_add_u32 s22, s4, 0x1404c000
	s_addc_u32 s23, s5, 0
	s_add_u32 s22, s22, s15
	s_addc_u32 s23, s23, 0
	global_load_dwordx4 v[230:233], v224, s[20:21]
	global_load_dwordx4 v[234:237], v224, s[20:21] offset:16
	global_load_dwordx4 v[238:241], v224, s[20:21] offset:32
	global_load_dwordx4 v[242:245], v224, s[20:21] offset:48
	global_load_dword v36, v226, s[22:23]
	global_load_dword v37, v226, s[22:23] offset:256
	s_waitcnt vmcnt(0)
	v_cvt_f32_f16_e32 v4, v230
	v_cvt_f32_f16_sdwa v5, v230 dst_sel:DWORD dst_unused:UNUSED_PAD src0_sel:WORD_1
	v_cvt_f32_f16_e32 v6, v231
	v_cvt_f32_f16_sdwa v7, v231 dst_sel:DWORD dst_unused:UNUSED_PAD src0_sel:WORD_1
	v_cvt_f32_f16_e32 v8, v232
	v_cvt_f32_f16_sdwa v9, v232 dst_sel:DWORD dst_unused:UNUSED_PAD src0_sel:WORD_1
	v_cvt_f32_f16_e32 v10, v233
	v_cvt_f32_f16_sdwa v11, v233 dst_sel:DWORD dst_unused:UNUSED_PAD src0_sel:WORD_1
	v_cvt_f32_f16_e32 v12, v234
	v_cvt_f32_f16_sdwa v13, v234 dst_sel:DWORD dst_unused:UNUSED_PAD src0_sel:WORD_1
	v_cvt_f32_f16_e32 v14, v235
	v_cvt_f32_f16_sdwa v15, v235 dst_sel:DWORD dst_unused:UNUSED_PAD src0_sel:WORD_1
	v_cvt_f32_f16_e32 v16, v236
	v_cvt_f32_f16_sdwa v17, v236 dst_sel:DWORD dst_unused:UNUSED_PAD src0_sel:WORD_1
	v_cvt_f32_f16_e32 v18, v237
	v_cvt_f32_f16_sdwa v19, v237 dst_sel:DWORD dst_unused:UNUSED_PAD src0_sel:WORD_1
	v_cvt_f32_f16_e32 v20, v238
	v_cvt_f32_f16_sdwa v21, v238 dst_sel:DWORD dst_unused:UNUSED_PAD src0_sel:WORD_1
	v_cvt_f32_f16_e32 v22, v239
	v_cvt_f32_f16_sdwa v23, v239 dst_sel:DWORD dst_unused:UNUSED_PAD src0_sel:WORD_1
	v_cvt_f32_f16_e32 v24, v240
	v_cvt_f32_f16_sdwa v25, v240 dst_sel:DWORD dst_unused:UNUSED_PAD src0_sel:WORD_1
	v_cvt_f32_f16_e32 v26, v241
	v_cvt_f32_f16_sdwa v27, v241 dst_sel:DWORD dst_unused:UNUSED_PAD src0_sel:WORD_1
	v_cvt_f32_f16_e32 v28, v242
	v_cvt_f32_f16_sdwa v29, v242 dst_sel:DWORD dst_unused:UNUSED_PAD src0_sel:WORD_1
	v_cvt_f32_f16_e32 v30, v243
	v_cvt_f32_f16_sdwa v31, v243 dst_sel:DWORD dst_unused:UNUSED_PAD src0_sel:WORD_1
	v_cvt_f32_f16_e32 v32, v244
	v_cvt_f32_f16_sdwa v33, v244 dst_sel:DWORD dst_unused:UNUSED_PAD src0_sel:WORD_1
	v_cvt_f32_f16_e32 v34, v245
	v_cvt_f32_f16_sdwa v35, v245 dst_sel:DWORD dst_unused:UNUSED_PAD src0_sel:WORD_1
	v_lshrrev_b32_e32 v249, 11, v36
	v_lshrrev_b32_e32 v250, 11, v37
	v_cmp_eq_u32_e64 s[52:53], s58, v249
	v_cmp_eq_u32_e64 s[54:55], s58, v250
	v_mul_u32_u24_e32 v44, 0x640, v36
	s_mov_b32 s61, 0
	s_lshl_b32 s63, s59, 9
	s_mul_i32 s1, s12, 0x2800
	s_add_u32 s63, s63, s1
	v_add_u32_e32 v46, s63, v226
	s_bcnt1_i32_b64 s1, s[52:53]
	s_bcnt1_i32_b64 s15, s[54:55]
	s_add_u32 s1, s1, s15
	s_sub_u32 s57, 8, s1
	s_cselect_b32 s57, 0, s57
	s_add_u32 s1, s59, 1
	s_cmp_lt_u32 s1, s50
	s_cbranch_scc1 .Lau1_pfki
	s_mov_b32 s1, 0
	s_cmp_lt_u32 s58, 7
	s_cbranch_scc0 .Lau1_pfdi

; __device__ __forceinline__ float geluf_(float x) { return 0.5f * x * (1.0f + tanhf(0.7978845608028654f * (x + 0.044715f * x * x * x))); }
; #define PB_FENCE asm volatile("" ::: "memory")
; __device__ __forceinline__ void ph_peer_apply(const Params& P, int layer, float* xlat, float* xctx_in, float* xctx_out, int nrows, bool write_next, char* smem, float* xlat_out = nullptr) {
;     ...
;     PB_LOAD(bufA, tu, 0);
;     for (int gq = 0; gq < NG; gq += 2) {
;       PB_LOAD(bufB, tu, gq + 1); PB_FENCE;
;       PB_DOT(bufA, gq);
;       if (gq + 2 < NG) PB_LOAD(bufA, tu, gq + 2);
;       PB_FENCE;
;       PB_DOT(bufB, gq + 1);
;     }
;     a0 = geluf_(a0) * g0; a1 = geluf_(a1) * g1;
.Lau1_rc2l_7:
	s_branch .Lau1_sdl7
.Lau1_s1end:
	s_waitcnt vmcnt(0) lgkmcnt(0)
	s_mov_b32 s14, 0
	s_mov_b32 s45, s13

; #define TIDX tid_fn()
; __device__ __forceinline__ void ph_peer_apply(const Params& P, int layer, float* xlat, float* xctx_in, float* xctx_out, int nrows, bool write_next, char* smem, float* xlat_out = nullptr) {
;     ...
;   const int tid = TIDX, wave = tid >> 6, lane = tid & 63;
;   const bool lact = lane < P6_NB;
;   const int lb = lact ? lane : 0;
;   for (int row = blockIdx.x * (NTHR / 64) + wave; row < nrows; row += gridDim.x * (NTHR / 64)) {
.Lav1_ntl:
	s_add_u32 s62, s62, 1
	s_add_u32 s1, s1, s44
	s_cmp_lt_u32 s1, 0x8000
	s_cbranch_scc1 .Lav1_ntl
	s_mov_b32 s51, 0

; __device__ __forceinline__ float wave_sum(float v) { v = row_sum16(v); v += __shfl_xor(v, 16); v += __shfl_xor(v, 32); return v; }
; __device__ __forceinline__ void ph_peer_apply(const Params& P, int layer, float* xlat, float* xctx_in, float* xctx_out, int nrows, bool write_next, char* smem, float* xlat_out = nullptr) {
;     ...
;     const float* xs1 = (row < NL ? xlat + (size_t)row * D : xctx_in + (size_t)(row - NL) * D) + lb * 32;
;     float* xo = (row < NL ? (xlat_out ? xlat_out : xlat) + (size_t)row * D : xctx_out + (size_t)(row - NL) * D) + lb * 32;
;     const float* gt = mod_ptr(P, layer, row, 5) + lb * 32;
;     float s = 0.f;
; #pragma unroll
;     for (int j4 = 0; j4 < 8; ++j4) {
;       float4 xa; const float4 ga = *(const float4*)(gt + j4 * 4);
;       if (row < NL) { const h16x4 xh_ = *(const h16x4*)((const h16*)(xlat + (size_t)row * D) + lb * 32 + j4 * 4); xa = make_float4((float)xh_[0], (float)xh_[1], (float)xh_[2], (float)xh_[3]); }
;       else xa = *(const float4*)(xs1 + j4 * 4);
;       o[j4 * 4 + 0] = ALPHA * xa.x + ga.x * o[j4 * 4 + 0]; o[j4 * 4 + 1] = ALPHA * xa.y + ga.y * o[j4 * 4 + 1];
;       o[j4 * 4 + 2] = ALPHA * xa.z + ga.z * o[j4 * 4 + 2]; o[j4 * 4 + 3] = ALPHA * xa.w + ga.w * o[j4 * 4 + 3];
;       s += (o[j4 * 4 + 0] + o[j4 * 4 + 1]) + (o[j4 * 4 + 2] + o[j4 * 4 + 3]);
;     }
;     s = wave_sum(lact ? s : 0.f);
.Lav1_cpd:
	s_cmp_ge_u32 s45, 0x8000
	s_cselect_b32 s48, 1, 0
	s_lshr_b32 s49, s45, 14
	s_cmp_lg_u32 s48, 0
	s_cselect_b32 s49, 2, s49
	s_sub_u32 s50, s45, 0x8000
	s_lshl_b32 s15, s45, 13
	s_lshr_b32 s31, s45, 19
	s_add_u32 s40, s6, s15
	s_addc_u32 s41, s7, s31
	s_add_u32 s15, s49, 3
	s_mul_i32 s15, s15, 6
	s_add_u32 s15, s15, 5
	s_lshl_b32 s15, s15, 13
	s_add_u32 s42, s4, 0x4000
	s_addc_u32 s43, s5, 0
	s_add_u32 s42, s42, s15
	s_addc_u32 s43, s43, 0
	global_load_dwordx4 v[112:115], v225, s[42:43]
	global_load_dwordx4 v[116:119], v225, s[42:43] offset:16
	global_load_dwordx4 v[120:123], v225, s[42:43] offset:32
	global_load_dwordx4 v[124:127], v225, s[42:43] offset:48
	global_load_dwordx4 v[128:131], v225, s[42:43] offset:64
	global_load_dwordx4 v[132:135], v225, s[42:43] offset:80
	global_load_dwordx4 v[136:139], v225, s[42:43] offset:96
	global_load_dwordx4 v[140:143], v225, s[42:43] offset:112
	s_mov_b32 s15, 0x3fb504f3
	global_load_dwordx4 v[192:195], v224, s[40:41]
	global_load_dwordx4 v[196:199], v224, s[40:41] offset:16
	global_load_dwordx4 v[200:203], v224, s[40:41] offset:32
	global_load_dwordx4 v[204:207], v224, s[40:41] offset:48
	s_waitcnt vmcnt(0)
	v_mul_f32_e32 v160, v112, v160
	v_mul_f32_e32 v161, v113, v161
	v_mul_f32_e32 v162, v114, v162
	v_mul_f32_e32 v163, v115, v163
	v_mul_f32_e32 v164, v116, v164
	v_mul_f32_e32 v165, v117, v165
	v_mul_f32_e32 v166, v118, v166
	v_mul_f32_e32 v167, v119, v167
	v_mul_f32_e32 v168, v120, v168
	v_mul_f32_e32 v169, v121, v169
	v_mul_f32_e32 v170, v122, v170
	v_mul_f32_e32 v171, v123, v171
	v_mul_f32_e32 v172, v124, v172
	v_mul_f32_e32 v173, v125, v173
	v_mul_f32_e32 v174, v126, v174
	v_mul_f32_e32 v175, v127, v175
	v_mul_f32_e32 v176, v128, v176
	v_mul_f32_e32 v177, v129, v177
	v_mul_f32_e32 v178, v130, v178
	v_mul_f32_e32 v179, v131, v179
	v_mul_f32_e32 v180, v132, v180
	v_mul_f32_e32 v181, v133, v181
	v_mul_f32_e32 v182, v134, v182
	v_mul_f32_e32 v183, v135, v183
	v_mul_f32_e32 v184, v136, v184
	v_mul_f32_e32 v185, v137, v185
	v_mul_f32_e32 v186, v138, v186
	v_mul_f32_e32 v187, v139, v187
	v_mul_f32_e32 v188, v140, v188
	v_mul_f32_e32 v189, v141, v189
	v_mul_f32_e32 v190, v142, v190
	v_mul_f32_e32 v191, v143, v191
	v_fma_mix_f32 v160, s15, v192, v160 op_sel_hi:[0,1,0]
	v_fma_mix_f32 v161, s15, v192, v161 op_sel:[0,1,0] op_sel_hi:[0,1,0]
	v_fma_mix_f32 v162, s15, v193, v162 op_sel_hi:[0,1,0]
	v_fma_mix_f32 v163, s15, v193, v163 op_sel:[0,1,0] op_sel_hi:[0,1,0]
	v_fma_mix_f32 v164, s15, v194, v164 op_sel_hi:[0,1,0]
	v_fma_mix_f32 v165, s15, v194, v165 op_sel:[0,1,0] op_sel_hi:[0,1,0]
	v_fma_mix_f32 v166, s15, v195, v166 op_sel_hi:[0,1,0]
	v_fma_mix_f32 v167, s15, v195, v167 op_sel:[0,1,0] op_sel_hi:[0,1,0]
	v_fma_mix_f32 v168, s15, v196, v168 op_sel_hi:[0,1,0]
	v_fma_mix_f32 v169, s15, v196, v169 op_sel:[0,1,0] op_sel_hi:[0,1,0]
	v_fma_mix_f32 v170, s15, v197, v170 op_sel_hi:[0,1,0]
	v_fma_mix_f32 v171, s15, v197, v171 op_sel:[0,1,0] op_sel_hi:[0,1,0]
	v_fma_mix_f32 v172, s15, v198, v172 op_sel_hi:[0,1,0]
	v_fma_mix_f32 v173, s15, v198, v173 op_sel:[0,1,0] op_sel_hi:[0,1,0]
	v_fma_mix_f32 v174, s15, v199, v174 op_sel_hi:[0,1,0]
	v_fma_mix_f32 v175, s15, v199, v175 op_sel:[0,1,0] op_sel_hi:[0,1,0]
	v_fma_mix_f32 v176, s15, v200, v176 op_sel_hi:[0,1,0]
	v_fma_mix_f32 v177, s15, v200, v177 op_sel:[0,1,0] op_sel_hi:[0,1,0]
	v_fma_mix_f32 v178, s15, v201, v178 op_sel_hi:[0,1,0]
	v_fma_mix_f32 v179, s15, v201, v179 op_sel:[0,1,0] op_sel_hi:[0,1,0]
	v_fma_mix_f32 v180, s15, v202, v180 op_sel_hi:[0,1,0]
	v_fma_mix_f32 v181, s15, v202, v181 op_sel:[0,1,0] op_sel_hi:[0,1,0]
	v_fma_mix_f32 v182, s15, v203, v182 op_sel_hi:[0,1,0]
	v_fma_mix_f32 v183, s15, v203, v183 op_sel:[0,1,0] op_sel_hi:[0,1,0]
	v_fma_mix_f32 v184, s15, v204, v184 op_sel_hi:[0,1,0]
	v_fma_mix_f32 v185, s15, v204, v185 op_sel:[0,1,0] op_sel_hi:[0,1,0]
	v_fma_mix_f32 v186, s15, v205, v186 op_sel_hi:[0,1,0]
	v_fma_mix_f32 v187, s15, v205, v187 op_sel:[0,1,0] op_sel_hi:[0,1,0]
	v_fma_mix_f32 v188, s15, v206, v188 op_sel_hi:[0,1,0]
	v_fma_mix_f32 v189, s15, v206, v189 op_sel:[0,1,0] op_sel_hi:[0,1,0]
	v_fma_mix_f32 v190, s15, v207, v190 op_sel_hi:[0,1,0]
	v_fma_mix_f32 v191, s15, v207, v191 op_sel:[0,1,0] op_sel_hi:[0,1,0]
	v_add_f32_e32 v208, v160, v161
	v_add_f32_e32 v208, v208, v162
	v_add_f32_e32 v208, v208, v163
	v_add_f32_e32 v208, v208, v164
	v_add_f32_e32 v208, v208, v165
	v_add_f32_e32 v208, v208, v166
	v_add_f32_e32 v208, v208, v167
	v_add_f32_e32 v208, v208, v168
	v_add_f32_e32 v208, v208, v169
	v_add_f32_e32 v208, v208, v170
	v_add_f32_e32 v208, v208, v171
	v_add_f32_e32 v208, v208, v172
	v_add_f32_e32 v208, v208, v173
	v_add_f32_e32 v208, v208, v174
	v_add_f32_e32 v208, v208, v175
	v_add_f32_e32 v208, v208, v176
	v_add_f32_e32 v208, v208, v177
	v_add_f32_e32 v208, v208, v178
	v_add_f32_e32 v208, v208, v179
	v_add_f32_e32 v208, v208, v180
	v_add_f32_e32 v208, v208, v181
	v_add_f32_e32 v208, v208, v182
	v_add_f32_e32 v208, v208, v183
	v_add_f32_e32 v208, v208, v184
	v_add_f32_e32 v208, v208, v185
	v_add_f32_e32 v208, v208, v186
	v_add_f32_e32 v208, v208, v187
	v_add_f32_e32 v208, v208, v188
	v_add_f32_e32 v208, v208, v189
	v_add_f32_e32 v208, v208, v190
	v_add_f32_e32 v208, v208, v191
	s_nop 1
	v_add_f32_dpp v208, v208, v208 quad_perm:[1,0,3,2] row_mask:0xf bank_mask:0xf bound_ctrl:1
	s_nop 1
	v_add_f32_dpp v208, v208, v208 quad_perm:[2,3,0,1] row_mask:0xf bank_mask:0xf bound_ctrl:1
	s_nop 1
	v_add_f32_dpp v208, v208, v208 row_ror:4 row_mask:0xf bank_mask:0xf bound_ctrl:1
	s_nop 1
	v_add_f32_dpp v208, v208, v208 row_ror:8 row_mask:0xf bank_mask:0xf bound_ctrl:1
	v_mov_b32_e32 v193, v208
	s_nop 1
	v_permlane32_swap_b32_e32 v193, v208
; __device__ __forceinline__ float wave_sum(float v) { v = row_sum16(v); v += __shfl_xor(v, 16); v += __shfl_xor(v, 32); return v; }
; __device__ __forceinline__ void ph_peer_apply(const Params& P, int layer, float* xlat, float* xctx_in, float* xctx_out, int nrows, bool write_next, char* smem, float* xlat_out = nullptr) {
;     ...
;     s = wave_sum(lact ? s : 0.f);
;     const float mu = s / (float)D;
;     float s2 = 0.f;
; #pragma unroll
;     for (int j = 0; j < 32; ++j) { const float dd = o[j] - mu; s2 += dd * dd; }
;     s2 = wave_sum(lact ? s2 : 0.f);
;     const float rstd = rsqrtf(s2 / (float)D + LN_EPS);
;     const float* gp = g + lb * 32; const float* bp = bb + lb * 32;
;     const float* sh1n = mod_ptr(P, 1, row, 0) + lb * 32;
	v_add_f32_e32 v208, v208, v193
	v_mov_b32_e32 v193, v208
	s_nop 1
	v_permlane16_swap_b32_e32 v193, v208
	v_add_f32_e32 v208, v208, v193
	v_mul_f32_e32 v210, 0x3a000000, v208
	v_sub_f32_e32 v160, v160, v210
	v_sub_f32_e32 v161, v161, v210
	v_sub_f32_e32 v162, v162, v210
	v_sub_f32_e32 v163, v163, v210
	v_sub_f32_e32 v164, v164, v210
	v_sub_f32_e32 v165, v165, v210
	v_sub_f32_e32 v166, v166, v210
	v_sub_f32_e32 v167, v167, v210
	v_sub_f32_e32 v168, v168, v210
	v_sub_f32_e32 v169, v169, v210
	v_sub_f32_e32 v170, v170, v210
	v_sub_f32_e32 v171, v171, v210
	v_sub_f32_e32 v172, v172, v210
	v_sub_f32_e32 v173, v173, v210
	v_sub_f32_e32 v174, v174, v210
	v_sub_f32_e32 v175, v175, v210
	v_sub_f32_e32 v176, v176, v210
	v_sub_f32_e32 v177, v177, v210
	v_sub_f32_e32 v178, v178, v210
	v_sub_f32_e32 v179, v179, v210
	v_sub_f32_e32 v180, v180, v210
	v_sub_f32_e32 v181, v181, v210
	v_sub_f32_e32 v182, v182, v210
	v_sub_f32_e32 v183, v183, v210
	v_sub_f32_e32 v184, v184, v210
	v_sub_f32_e32 v185, v185, v210
	v_sub_f32_e32 v186, v186, v210
	v_sub_f32_e32 v187, v187, v210
	v_sub_f32_e32 v188, v188, v210
	v_sub_f32_e32 v189, v189, v210
	v_sub_f32_e32 v190, v190, v210
	v_sub_f32_e32 v191, v191, v210
	v_mul_f32_e32 v209, v160, v160
	v_fmac_f32_e32 v209, v161, v161
	v_fmac_f32_e32 v209, v162, v162
	v_fmac_f32_e32 v209, v163, v163
	v_fmac_f32_e32 v209, v164, v164
	v_fmac_f32_e32 v209, v165, v165
	v_fmac_f32_e32 v209, v166, v166
	v_fmac_f32_e32 v209, v167, v167
	v_fmac_f32_e32 v209, v168, v168
	v_fmac_f32_e32 v209, v169, v169
	v_fmac_f32_e32 v209, v170, v170
	v_fmac_f32_e32 v209, v171, v171
	v_fmac_f32_e32 v209, v172, v172
	v_fmac_f32_e32 v209, v173, v173
	v_fmac_f32_e32 v209, v174, v174
	v_fmac_f32_e32 v209, v175, v175
	v_fmac_f32_e32 v209, v176, v176
	v_fmac_f32_e32 v209, v177, v177
	v_fmac_f32_e32 v209, v178, v178
	v_fmac_f32_e32 v209, v179, v179
	v_fmac_f32_e32 v209, v180, v180
	v_fmac_f32_e32 v209, v181, v181
	v_fmac_f32_e32 v209, v182, v182
	v_fmac_f32_e32 v209, v183, v183
	v_fmac_f32_e32 v209, v184, v184
	v_fmac_f32_e32 v209, v185, v185
	v_fmac_f32_e32 v209, v186, v186
	v_fmac_f32_e32 v209, v187, v187
	v_fmac_f32_e32 v209, v188, v188
	v_fmac_f32_e32 v209, v189, v189
	v_fmac_f32_e32 v209, v190, v190
	v_fmac_f32_e32 v209, v191, v191
	s_nop 1
	v_add_f32_dpp v209, v209, v209 quad_perm:[1,0,3,2] row_mask:0xf bank_mask:0xf bound_ctrl:1
	s_nop 1
	v_add_f32_dpp v209, v209, v209 quad_perm:[2,3,0,1] row_mask:0xf bank_mask:0xf bound_ctrl:1
	s_nop 1
	v_add_f32_dpp v209, v209, v209 row_ror:4 row_mask:0xf bank_mask:0xf bound_ctrl:1
	s_nop 1
	v_add_f32_dpp v209, v209, v209 row_ror:8 row_mask:0xf bank_mask:0xf bound_ctrl:1
	v_mov_b32_e32 v193, v209
	s_nop 1
	v_permlane32_swap_b32_e32 v193, v209
	v_add_f32_e32 v209, v209, v193
	v_mov_b32_e32 v193, v209
	s_nop 1
	v_permlane16_swap_b32_e32 v193, v209
	v_add_f32_e32 v209, v209, v193
	v_mov_b32_e32 v211, 0x3727c5ac
	v_fmac_f32_e32 v211, 0x3a000000, v209
	v_rsq_f32_e32 v211, v211
	s_add_u32 s26, s8, 0x6000
	s_addc_u32 s27, s9, 0
	global_load_dwordx4 v[112:115], v225, s[26:27]
	global_load_dwordx4 v[116:119], v225, s[26:27] offset:16
	global_load_dwordx4 v[120:123], v225, s[26:27] offset:32
	global_load_dwordx4 v[124:127], v225, s[26:27] offset:48
	global_load_dwordx4 v[128:131], v225, s[26:27] offset:64
	global_load_dwordx4 v[132:135], v225, s[26:27] offset:80
	global_load_dwordx4 v[136:139], v225, s[26:27] offset:96
	global_load_dwordx4 v[140:143], v225, s[26:27] offset:112
	s_add_u32 s26, s10, 0x6000
	s_addc_u32 s27, s11, 0
	global_load_dwordx4 v[192:195], v225, s[26:27]
	global_load_dwordx4 v[196:199], v225, s[26:27] offset:16
	global_load_dwordx4 v[200:203], v225, s[26:27] offset:32
	global_load_dwordx4 v[204:207], v225, s[26:27] offset:48
	s_waitcnt vmcnt(4)
; __device__ __forceinline__ void ph_peer_apply(const Params& P, int layer, float* xlat, float* xctx_in, float* xctx_out, int nrows, bool write_next, char* smem, float* xlat_out = nullptr) {
;     ...
;     if (lact) {
; #pragma unroll
;       for (int j4 = 0; j4 < 8; ++j4) {
;         const float4 gv = *(const float4*)(gp + j4 * 4), bv = *(const float4*)(bp + j4 * 4);
;         float4 ov;
;         ov.x = (o[j4 * 4 + 0] - mu) * rstd * gv.x + bv.x; ov.y = (o[j4 * 4 + 1] - mu) * rstd * gv.y + bv.y;
;         ov.z = (o[j4 * 4 + 2] - mu) * rstd * gv.z + bv.z; ov.w = (o[j4 * 4 + 3] - mu) * rstd * gv.w + bv.w;
;         if (row < NL && write_next) { h16x4 oh_; oh_[0] = (h16)ov.x; oh_[1] = (h16)ov.y; oh_[2] = (h16)ov.z; oh_[3] = (h16)ov.w; *(h16x4*)((h16*)((xlat_out ? xlat_out : xlat) + (size_t)row * D) + lb * 32 + j4 * 4) = oh_; }
;         else *(float4*)(xo + j4 * 4) = ov;
	v_mul_f32_e32 v160, v160, v211
	v_mul_f32_e32 v161, v161, v211
	v_mul_f32_e32 v162, v162, v211
	v_mul_f32_e32 v163, v163, v211
	v_mul_f32_e32 v164, v164, v211
	v_mul_f32_e32 v165, v165, v211
	v_mul_f32_e32 v166, v166, v211
	v_mul_f32_e32 v167, v167, v211
	v_mul_f32_e32 v168, v168, v211
	v_mul_f32_e32 v169, v169, v211
	v_mul_f32_e32 v170, v170, v211
	v_mul_f32_e32 v171, v171, v211
	v_mul_f32_e32 v172, v172, v211
	v_mul_f32_e32 v173, v173, v211
	v_mul_f32_e32 v174, v174, v211
	v_mul_f32_e32 v175, v175, v211
	v_mul_f32_e32 v176, v176, v211
	v_mul_f32_e32 v177, v177, v211
	v_mul_f32_e32 v178, v178, v211
	v_mul_f32_e32 v179, v179, v211
	v_mul_f32_e32 v180, v180, v211
	v_mul_f32_e32 v181, v181, v211
	v_mul_f32_e32 v182, v182, v211
	v_mul_f32_e32 v183, v183, v211
	v_mul_f32_e32 v184, v184, v211
	v_mul_f32_e32 v185, v185, v211
	v_mul_f32_e32 v186, v186, v211
	v_mul_f32_e32 v187, v187, v211
	v_mul_f32_e32 v188, v188, v211
	v_mul_f32_e32 v189, v189, v211
	v_mul_f32_e32 v190, v190, v211
	v_mul_f32_e32 v191, v191, v211
	v_mul_f32_e32 v160, v160, v112
	v_mul_f32_e32 v161, v161, v113
	v_mul_f32_e32 v162, v162, v114
	v_mul_f32_e32 v163, v163, v115
	v_mul_f32_e32 v164, v164, v116
	v_mul_f32_e32 v165, v165, v117
	v_mul_f32_e32 v166, v166, v118
	v_mul_f32_e32 v167, v167, v119
	v_mul_f32_e32 v168, v168, v120
	v_mul_f32_e32 v169, v169, v121
	v_mul_f32_e32 v170, v170, v122
	v_mul_f32_e32 v171, v171, v123
	v_mul_f32_e32 v172, v172, v124
	v_mul_f32_e32 v173, v173, v125
	v_mul_f32_e32 v174, v174, v126
	v_mul_f32_e32 v175, v175, v127
	v_mul_f32_e32 v176, v176, v128
	v_mul_f32_e32 v177, v177, v129
	v_mul_f32_e32 v178, v178, v130
	v_mul_f32_e32 v179, v179, v131
	v_mul_f32_e32 v180, v180, v132
	v_mul_f32_e32 v181, v181, v133
	v_mul_f32_e32 v182, v182, v134
	v_mul_f32_e32 v183, v183, v135
	v_mul_f32_e32 v184, v184, v136
	v_mul_f32_e32 v185, v185, v137
	v_mul_f32_e32 v186, v186, v138
	v_mul_f32_e32 v187, v187, v139
	v_mul_f32_e32 v188, v188, v140
	v_mul_f32_e32 v189, v189, v141
	v_mul_f32_e32 v190, v190, v142
	v_mul_f32_e32 v191, v191, v143
	s_waitcnt vmcnt(0)
	v_add_f32_e32 v160, v160, v192
	v_add_f32_e32 v161, v161, v193
	v_add_f32_e32 v162, v162, v194
	v_add_f32_e32 v163, v163, v195
	v_add_f32_e32 v164, v164, v196
	v_add_f32_e32 v165, v165, v197
	v_add_f32_e32 v166, v166, v198
	v_add_f32_e32 v167, v167, v199
	v_add_f32_e32 v168, v168, v200
	v_add_f32_e32 v169, v169, v201
	v_add_f32_e32 v170, v170, v202
	v_add_f32_e32 v171, v171, v203
	v_add_f32_e32 v172, v172, v204
	v_add_f32_e32 v173, v173, v205
	v_add_f32_e32 v174, v174, v206
	v_add_f32_e32 v175, v175, v207
	global_load_dwordx4 v[192:195], v225, s[26:27] offset:64
	global_load_dwordx4 v[196:199], v225, s[26:27] offset:80
	global_load_dwordx4 v[200:203], v225, s[26:27] offset:96
	global_load_dwordx4 v[204:207], v225, s[26:27] offset:112
	s_waitcnt vmcnt(0)
	v_add_f32_e32 v176, v176, v192
	v_add_f32_e32 v177, v177, v193
	v_add_f32_e32 v178, v178, v194
	v_add_f32_e32 v179, v179, v195
	v_add_f32_e32 v180, v180, v196
	v_add_f32_e32 v181, v181, v197
	v_add_f32_e32 v182, v182, v198
	v_add_f32_e32 v183, v183, v199
	v_add_f32_e32 v184, v184, v200
	v_add_f32_e32 v185, v185, v201
	v_add_f32_e32 v186, v186, v202
	v_add_f32_e32 v187, v187, v203
	v_add_f32_e32 v188, v188, v204
	v_add_f32_e32 v189, v189, v205
	v_add_f32_e32 v190, v190, v206
	v_add_f32_e32 v191, v191, v207
	global_store_dwordx4 v225, v[160:163], s[40:41]
	global_store_dwordx4 v225, v[164:167], s[40:41] offset:16
	global_store_dwordx4 v225, v[168:171], s[40:41] offset:32
	global_store_dwordx4 v225, v[172:175], s[40:41] offset:48
	global_store_dwordx4 v225, v[176:179], s[40:41] offset:64
	global_store_dwordx4 v225, v[180:183], s[40:41] offset:80
	global_store_dwordx4 v225, v[184:187], s[40:41] offset:96
	global_store_dwordx4 v225, v[188:191], s[40:41] offset:112
	s_add_u32 s63, s63, 1
	s_cmp_lt_u32 s63, s57
	s_cbranch_scc1 .Lav1_lnl
	s_add_u32 s51, s51, 4
	s_cmp_lt_u32 s51, s62
	s_cbranch_scc1 .Lav1_group
